# GEMM load slots: s_setprio 1 issued before the two closing waits, so no instruction sits between the last wait and the barrier (36 sites)
# speedup vs baseline: 1.0029x; 1.0029x over previous
; #define PG8_STAGE(bufoff, gbase, voff) do { _Pragma("unroll") for (int _i = 0; _i < 2; ++_i) \
;         __builtin_amdgcn_global_load_lds((const unsigned*)((const char*)(gbase) + (voff)[_i]), (PG8_LAS unsigned*)(lds + (bufoff) + ldsw + _i * 8192), 16, 0, 0); } while (0)
; #define PG8_LDA(dst, b, h) do { _Pragma("unroll") for (int m = 0; m < 4; ++m) _Pragma("unroll") for (int k = 0; k < 2; ++k) dst[m][k] = *(const PG8_LAS bf16x8*)(lds + PG8_SA(b, h) + aoff + m * 2048 + k * 1024); } while (0)
; #define PG8_LDB(dst, b, h) do { _Pragma("unroll") for (int n = 0; n < 2; ++n) _Pragma("unroll") for (int k = 0; k < 2; ++k) dst[n][k] = *(const PG8_LAS bf16x8*)(lds + PG8_SB(b, h) + boff + n * 2048 + k * 1024); } while (0)
; #define PG8_WAIT_V(n) asm volatile("s_waitcnt vmcnt(" #n ")" ::: "memory")
; #define PG8_WAIT_L(n) asm volatile("s_waitcnt lgkmcnt(" #n ")" ::: "memory")
; #define PG8_BAR __builtin_amdgcn_s_barrier()
; #define PG8_SCHED __builtin_amdgcn_sched_barrier(0)
; template <class Epi, class Sched, bool ALIGN_EPI = false, bool SP2 = false, bool F8 = false>
; __device__ __forceinline__ void gemm_phase(PG8_LAS unsigned char* lds, const Gemm g, const Sched& S, const Epi& E) {
;     ...
;             PG8_LDB(B0, 0, 0); PG8_LDB(B1, 0, 1); PG8_SCHED; PG8_LDA(At, 0, 0); PG8_STAGE(PG8_SA(1, 1), a1 + hA, voffA);
;             PG8_WAIT_V(8); PG8_WAIT_L(0); PG8_BAR; PG8_MMA(0, 0, At, B0); PG8_MMA(0, 1, At, B1); PG8_BAR; PG8_SCHED;
;             PG8_LDA(At, 0, 1); PG8_STAGE(PG8_SB(0, 0), b2, voffB); PG8_STAGE(PG8_SB(0, 1), b2 + hB, voffB); PG8_STAGE(PG8_SA(0, 0), a2, voffA);
;             PG8_WAIT_V(8); PG8_WAIT_L(0); PG8_BAR; PG8_MMA(1, 0, At, B0); PG8_MMA(1, 1, At, B1); PG8_BAR; PG8_SCHED;
.LBB0_128:
	ds_read_b128 v[152:155], v149
	ds_read_b128 v[156:159], v149 offset:1024
	ds_read_b128 v[160:163], v149 offset:2048
	ds_read_b128 v[164:167], v149 offset:3072
	ds_read_b128 v[168:171], v150
	ds_read_b128 v[172:175], v150 offset:1024
	ds_read_b128 v[176:179], v150 offset:2048
	ds_read_b128 v[180:183], v150 offset:3072
	s_add_u32 s40, s38, 0xfff00080
	s_addc_u32 s41, s39, -1
	s_cmp_eq_u32 s66, 60
	s_cselect_b32 s43, s31, s41
	s_cselect_b32 s42, s62, s40
	s_cselect_b32 s41, s29, s65
	s_cselect_b32 s40, s63, s64
	v_lshl_add_u64 v[216:217], s[38:39], 0, v[140:141]
	s_add_i32 m0, s27, 0xc000
	ds_read_b128 v[184:187], v151
	ds_read_b128 v[188:191], v151 offset:1024
	ds_read_b128 v[192:195], v151 offset:2048
	ds_read_b128 v[196:199], v151 offset:3072
	ds_read_b128 v[200:203], v151 offset:4096
	ds_read_b128 v[204:207], v151 offset:5120
	ds_read_b128 v[208:211], v151 offset:6144
	ds_read_b128 v[212:215], v151 offset:7168
	global_load_lds_dwordx4 v[216:217], off
	v_lshl_add_u64 v[216:217], s[38:39], 0, v[138:139]
	s_add_i32 m0, s27, 0xe000
	s_nop 0
	global_load_lds_dwordx4 v[216:217], off
	s_setprio 1
	s_waitcnt vmcnt(8)
	s_waitcnt lgkmcnt(0)
	s_barrier
	v_mfma_f32_16x16x32_bf16 v[126:129], v[152:155], v[184:187], v[126:129]
	v_mfma_f32_16x16x32_bf16 v[122:125], v[160:163], v[184:187], v[122:125]
	v_mfma_f32_16x16x32_bf16 v[118:121], v[152:155], v[192:195], v[118:121]
	v_mfma_f32_16x16x32_bf16 v[114:117], v[160:163], v[192:195], v[114:117]
	v_mfma_f32_16x16x32_bf16 v[102:105], v[152:155], v[200:203], v[102:105]
	v_mfma_f32_16x16x32_bf16 v[98:101], v[160:163], v[200:203], v[98:101]
	v_mfma_f32_16x16x32_bf16 v[86:89], v[152:155], v[208:211], v[86:89]
	v_mfma_f32_16x16x32_bf16 v[82:85], v[160:163], v[208:211], v[82:85]
	v_mfma_f32_16x16x32_bf16 v[126:129], v[156:159], v[188:191], v[126:129]
	v_mfma_f32_16x16x32_bf16 v[122:125], v[164:167], v[188:191], v[122:125]
	v_mfma_f32_16x16x32_bf16 v[118:121], v[156:159], v[196:199], v[118:121]
	v_mfma_f32_16x16x32_bf16 v[114:117], v[164:167], v[196:199], v[114:117]
	v_mfma_f32_16x16x32_bf16 v[102:105], v[156:159], v[204:207], v[102:105]
	v_mfma_f32_16x16x32_bf16 v[98:101], v[164:167], v[204:207], v[98:101]
	v_mfma_f32_16x16x32_bf16 v[86:89], v[156:159], v[212:215], v[86:89]
	v_mfma_f32_16x16x32_bf16 v[82:85], v[164:167], v[212:215], v[82:85]
	v_mfma_f32_16x16x32_bf16 v[110:113], v[168:171], v[184:187], v[110:113]
	v_mfma_f32_16x16x32_bf16 v[106:109], v[176:179], v[184:187], v[106:109]
	v_mfma_f32_16x16x32_bf16 v[94:97], v[168:171], v[192:195], v[94:97]
	v_mfma_f32_16x16x32_bf16 v[90:93], v[176:179], v[192:195], v[90:93]
	v_mfma_f32_16x16x32_bf16 v[78:81], v[168:171], v[200:203], v[78:81]
	v_mfma_f32_16x16x32_bf16 v[74:77], v[176:179], v[200:203], v[74:77]
	v_mfma_f32_16x16x32_bf16 v[70:73], v[168:171], v[208:211], v[70:73]
	v_mfma_f32_16x16x32_bf16 v[66:69], v[176:179], v[208:211], v[66:69]
	v_mfma_f32_16x16x32_bf16 v[110:113], v[172:175], v[188:191], v[110:113]
	v_mfma_f32_16x16x32_bf16 v[106:109], v[180:183], v[188:191], v[106:109]
	v_mfma_f32_16x16x32_bf16 v[94:97], v[172:175], v[196:199], v[94:97]
	v_mfma_f32_16x16x32_bf16 v[90:93], v[180:183], v[196:199], v[90:93]
	v_mfma_f32_16x16x32_bf16 v[78:81], v[172:175], v[204:207], v[78:81]
	v_mfma_f32_16x16x32_bf16 v[74:77], v[180:183], v[204:207], v[74:77]
	v_mfma_f32_16x16x32_bf16 v[70:73], v[172:175], v[212:215], v[70:73]
	v_mfma_f32_16x16x32_bf16 v[66:69], v[180:183], v[212:215], v[66:69]
	s_barrier
	s_setprio 0
	s_add_i32 s67, s55, s45
	v_lshl_add_u64 v[216:217], s[40:41], 0, v[134:135]
	s_mov_b32 m0, s67
	ds_read_b128 v[184:187], v151 offset:16384
	ds_read_b128 v[188:191], v151 offset:17408
	ds_read_b128 v[192:195], v151 offset:18432
	ds_read_b128 v[196:199], v151 offset:19456
	ds_read_b128 v[200:203], v151 offset:20480
	ds_read_b128 v[204:207], v151 offset:21504
	ds_read_b128 v[208:211], v151 offset:22528
	ds_read_b128 v[212:215], v151 offset:23552
	global_load_lds_dwordx4 v[216:217], off
	s_add_i32 m0, s67, 0x2000
	s_add_u32 s70, s40, 0x100000
	v_lshl_add_u64 v[218:219], s[40:41], 0, v[130:131]
	s_addc_u32 s71, s41, 0
	s_add_i32 s67, s56, s45
	global_load_lds_dwordx4 v[218:219], off
	v_lshl_add_u64 v[220:221], s[70:71], 0, v[134:135]
	s_mov_b32 m0, s67
	v_lshl_add_u64 v[222:223], s[42:43], 0, v[132:133]
	global_load_lds_dwordx4 v[220:221], off
	v_lshl_add_u64 v[220:221], s[70:71], 0, v[130:131]
	s_add_i32 m0, s67, 0x2000
	s_nop 0
	global_load_lds_dwordx4 v[220:221], off
	v_lshl_add_u64 v[220:221], s[42:43], 0, v[136:137]
	s_mov_b32 m0, s27
	s_nop 0
	global_load_lds_dwordx4 v[220:221], off
	s_mov_b32 m0, s48
	s_nop 0
	global_load_lds_dwordx4 v[222:223], off
	s_setprio 1
	s_waitcnt vmcnt(8)
	s_waitcnt lgkmcnt(0)
	s_barrier
; #define PG8_STAGE(bufoff, gbase, voff) do { _Pragma("unroll") for (int _i = 0; _i < 2; ++_i) \
;         __builtin_amdgcn_global_load_lds((const unsigned*)((const char*)(gbase) + (voff)[_i]), (PG8_LAS unsigned*)(lds + (bufoff) + ldsw + _i * 8192), 16, 0, 0); } while (0)
; #define PG8_LDA(dst, b, h) do { _Pragma("unroll") for (int m = 0; m < 4; ++m) _Pragma("unroll") for (int k = 0; k < 2; ++k) dst[m][k] = *(const PG8_LAS bf16x8*)(lds + PG8_SA(b, h) + aoff + m * 2048 + k * 1024); } while (0)
; #define PG8_LDB(dst, b, h) do { _Pragma("unroll") for (int n = 0; n < 2; ++n) _Pragma("unroll") for (int k = 0; k < 2; ++k) dst[n][k] = *(const PG8_LAS bf16x8*)(lds + PG8_SB(b, h) + boff + n * 2048 + k * 1024); } while (0)
; #define PG8_WAIT_V(n) asm volatile("s_waitcnt vmcnt(" #n ")" ::: "memory")
; #define PG8_WAIT_L(n) asm volatile("s_waitcnt lgkmcnt(" #n ")" ::: "memory")
; #define PG8_BAR __builtin_amdgcn_s_barrier()
; #define PG8_SCHED __builtin_amdgcn_sched_barrier(0)
; template <class Epi, class Sched, bool ALIGN_EPI = false, bool SP2 = false, bool F8 = false>
; __device__ __forceinline__ void gemm_phase(PG8_LAS unsigned char* lds, const Gemm g, const Sched& S, const Epi& E) {
;     ...
;             PG8_WAIT_V(8); PG8_WAIT_L(0); PG8_BAR; PG8_MMA(1, 0, At, B0); PG8_MMA(1, 1, At, B1); PG8_BAR; PG8_SCHED;
;             PG8_LDB(B0, 1, 0); PG8_LDB(B1, 1, 1); PG8_SCHED; PG8_LDA(At, 1, 0); PG8_STAGE(PG8_SA(0, 1), a2 + hA, voffA);
;             PG8_WAIT_V(8); PG8_WAIT_L(0); PG8_BAR; PG8_MMA(0, 0, At, B0); PG8_MMA(0, 1, At, B1); PG8_BAR; PG8_SCHED;
	v_mfma_f32_16x16x32_bf16 v[62:65], v[152:155], v[184:187], v[62:65]
	v_mfma_f32_16x16x32_bf16 v[58:61], v[160:163], v[184:187], v[58:61]
	v_mfma_f32_16x16x32_bf16 v[54:57], v[152:155], v[192:195], v[54:57]
	v_mfma_f32_16x16x32_bf16 v[50:53], v[160:163], v[192:195], v[50:53]
	v_mfma_f32_16x16x32_bf16 v[38:41], v[152:155], v[200:203], v[38:41]
	v_mfma_f32_16x16x32_bf16 v[34:37], v[160:163], v[200:203], v[34:37]
	v_mfma_f32_16x16x32_bf16 v[22:25], v[152:155], v[208:211], v[22:25]
	v_mfma_f32_16x16x32_bf16 v[18:21], v[160:163], v[208:211], v[18:21]
	v_mfma_f32_16x16x32_bf16 v[62:65], v[156:159], v[188:191], v[62:65]
	v_mfma_f32_16x16x32_bf16 v[58:61], v[164:167], v[188:191], v[58:61]
	v_mfma_f32_16x16x32_bf16 v[54:57], v[156:159], v[196:199], v[54:57]
	v_mfma_f32_16x16x32_bf16 v[50:53], v[164:167], v[196:199], v[50:53]
	v_mfma_f32_16x16x32_bf16 v[38:41], v[156:159], v[204:207], v[38:41]
	v_mfma_f32_16x16x32_bf16 v[34:37], v[164:167], v[204:207], v[34:37]
	v_mfma_f32_16x16x32_bf16 v[22:25], v[156:159], v[212:215], v[22:25]
	v_mfma_f32_16x16x32_bf16 v[18:21], v[164:167], v[212:215], v[18:21]
	v_mfma_f32_16x16x32_bf16 v[46:49], v[168:171], v[184:187], v[46:49]
	v_mfma_f32_16x16x32_bf16 v[42:45], v[176:179], v[184:187], v[42:45]
	v_mfma_f32_16x16x32_bf16 v[30:33], v[168:171], v[192:195], v[30:33]
	v_mfma_f32_16x16x32_bf16 v[26:29], v[176:179], v[192:195], v[26:29]
	v_mfma_f32_16x16x32_bf16 v[14:17], v[168:171], v[200:203], v[14:17]
	v_mfma_f32_16x16x32_bf16 v[10:13], v[176:179], v[200:203], v[10:13]
	v_mfma_f32_16x16x32_bf16 v[6:9], v[168:171], v[208:211], v[6:9]
	v_mfma_f32_16x16x32_bf16 v[2:5], v[176:179], v[208:211], v[2:5]
	v_mfma_f32_16x16x32_bf16 v[46:49], v[172:175], v[188:191], v[46:49]
	v_mfma_f32_16x16x32_bf16 v[42:45], v[180:183], v[188:191], v[42:45]
	v_mfma_f32_16x16x32_bf16 v[30:33], v[172:175], v[196:199], v[30:33]
	v_mfma_f32_16x16x32_bf16 v[26:29], v[180:183], v[196:199], v[26:29]
	v_mfma_f32_16x16x32_bf16 v[14:17], v[172:175], v[204:207], v[14:17]
	v_mfma_f32_16x16x32_bf16 v[10:13], v[180:183], v[204:207], v[10:13]
	v_mfma_f32_16x16x32_bf16 v[6:9], v[172:175], v[212:215], v[6:9]
	v_mfma_f32_16x16x32_bf16 v[2:5], v[180:183], v[212:215], v[2:5]
	s_barrier
	s_setprio 0
	s_add_i32 s67, 0, 0x18000
	s_add_i32 s69, 0, 0x1c000
	v_add_u32_e32 v164, s67, v147
	v_add_u32_e32 v180, s69, v147
	ds_read_b128 v[152:155], v164
	ds_read_b128 v[156:159], v164 offset:1024
	ds_read_b128 v[160:163], v164 offset:2048
	ds_read_b128 v[164:167], v164 offset:3072
	ds_read_b128 v[168:171], v180
	ds_read_b128 v[172:175], v180 offset:1024
	ds_read_b128 v[176:179], v180 offset:2048
	ds_read_b128 v[180:183], v180 offset:3072
	s_add_u32 s42, s42, 0x100000
	s_addc_u32 s43, s43, 0
	s_mov_b32 m0, s49
	v_lshl_add_u64 v[224:225], s[42:43], 0, v[136:137]
	ds_read_b128 v[184:187], v151 offset:32768
	ds_read_b128 v[188:191], v151 offset:33792
	ds_read_b128 v[192:195], v151 offset:34816
	ds_read_b128 v[196:199], v151 offset:35840
	ds_read_b128 v[200:203], v151 offset:36864
	ds_read_b128 v[204:207], v151 offset:37888
	ds_read_b128 v[208:211], v151 offset:38912
	ds_read_b128 v[212:215], v151 offset:39936
	global_load_lds_dwordx4 v[224:225], off
	v_lshl_add_u64 v[224:225], s[42:43], 0, v[132:133]
	s_mov_b32 m0, s50
	s_nop 0
	global_load_lds_dwordx4 v[224:225], off
	s_setprio 1
	s_waitcnt vmcnt(8)
	s_waitcnt lgkmcnt(0)
	s_barrier
	v_mfma_f32_16x16x32_bf16 v[126:129], v[152:155], v[184:187], v[126:129]
	v_mfma_f32_16x16x32_bf16 v[122:125], v[160:163], v[184:187], v[122:125]
	v_mfma_f32_16x16x32_bf16 v[118:121], v[152:155], v[192:195], v[118:121]
	v_mfma_f32_16x16x32_bf16 v[114:117], v[160:163], v[192:195], v[114:117]
	v_mfma_f32_16x16x32_bf16 v[102:105], v[152:155], v[200:203], v[102:105]
	v_mfma_f32_16x16x32_bf16 v[98:101], v[160:163], v[200:203], v[98:101]
	v_mfma_f32_16x16x32_bf16 v[86:89], v[152:155], v[208:211], v[86:89]
	v_mfma_f32_16x16x32_bf16 v[82:85], v[160:163], v[208:211], v[82:85]
	v_mfma_f32_16x16x32_bf16 v[126:129], v[156:159], v[188:191], v[126:129]
	v_mfma_f32_16x16x32_bf16 v[122:125], v[164:167], v[188:191], v[122:125]
	v_mfma_f32_16x16x32_bf16 v[118:121], v[156:159], v[196:199], v[118:121]
	v_mfma_f32_16x16x32_bf16 v[114:117], v[164:167], v[196:199], v[114:117]
	v_mfma_f32_16x16x32_bf16 v[102:105], v[156:159], v[204:207], v[102:105]
	v_mfma_f32_16x16x32_bf16 v[98:101], v[164:167], v[204:207], v[98:101]
	v_mfma_f32_16x16x32_bf16 v[86:89], v[156:159], v[212:215], v[86:89]
	v_mfma_f32_16x16x32_bf16 v[82:85], v[164:167], v[212:215], v[82:85]
	v_mfma_f32_16x16x32_bf16 v[110:113], v[168:171], v[184:187], v[110:113]
	v_mfma_f32_16x16x32_bf16 v[106:109], v[176:179], v[184:187], v[106:109]
	v_mfma_f32_16x16x32_bf16 v[94:97], v[168:171], v[192:195], v[94:97]
	v_mfma_f32_16x16x32_bf16 v[90:93], v[176:179], v[192:195], v[90:93]
	v_mfma_f32_16x16x32_bf16 v[78:81], v[168:171], v[200:203], v[78:81]
	v_mfma_f32_16x16x32_bf16 v[74:77], v[176:179], v[200:203], v[74:77]
	v_mfma_f32_16x16x32_bf16 v[70:73], v[168:171], v[208:211], v[70:73]
	v_mfma_f32_16x16x32_bf16 v[66:69], v[176:179], v[208:211], v[66:69]
	v_mfma_f32_16x16x32_bf16 v[110:113], v[172:175], v[188:191], v[110:113]
	v_mfma_f32_16x16x32_bf16 v[106:109], v[180:183], v[188:191], v[106:109]
	v_mfma_f32_16x16x32_bf16 v[94:97], v[172:175], v[196:199], v[94:97]
	v_mfma_f32_16x16x32_bf16 v[90:93], v[180:183], v[196:199], v[90:93]
	v_mfma_f32_16x16x32_bf16 v[78:81], v[172:175], v[204:207], v[78:81]
	v_mfma_f32_16x16x32_bf16 v[74:77], v[180:183], v[204:207], v[74:77]
	v_mfma_f32_16x16x32_bf16 v[70:73], v[172:175], v[212:215], v[70:73]
	v_mfma_f32_16x16x32_bf16 v[66:69], v[180:183], v[212:215], v[66:69]
	s_barrier
; #define PG8_STAGE(bufoff, gbase, voff) do { _Pragma("unroll") for (int _i = 0; _i < 2; ++_i) \
;         __builtin_amdgcn_global_load_lds((const unsigned*)((const char*)(gbase) + (voff)[_i]), (PG8_LAS unsigned*)(lds + (bufoff) + ldsw + _i * 8192), 16, 0, 0); } while (0)
; #define PG8_LDA(dst, b, h) do { _Pragma("unroll") for (int m = 0; m < 4; ++m) _Pragma("unroll") for (int k = 0; k < 2; ++k) dst[m][k] = *(const PG8_LAS bf16x8*)(lds + PG8_SA(b, h) + aoff + m * 2048 + k * 1024); } while (0)
; #define PG8_WAIT_V(n) asm volatile("s_waitcnt vmcnt(" #n ")" ::: "memory")
; #define PG8_WAIT_L(n) asm volatile("s_waitcnt lgkmcnt(" #n ")" ::: "memory")
; #define PG8_BAR __builtin_amdgcn_s_barrier()
; #define PG8_SCHED __builtin_amdgcn_sched_barrier(0)
; template <class Epi, class Sched, bool ALIGN_EPI = false, bool SP2 = false, bool F8 = false>
; __device__ __forceinline__ void gemm_phase(PG8_LAS unsigned char* lds, const Gemm g, const Sched& S, const Epi& E) {
;     ...
;             PG8_LDA(At, 1, 1); PG8_STAGE(PG8_SB(1, 0), b3, voffB); PG8_STAGE(PG8_SB(1, 1), b3 + hB, voffB); PG8_STAGE(PG8_SA(1, 0), a3, voffA);
;             PG8_WAIT_V(8); PG8_WAIT_L(0); PG8_BAR; PG8_MMA(1, 0, At, B0); PG8_MMA(1, 1, At, B1); PG8_BAR; PG8_SCHED;
;     ...
;         if constexpr (ALIGN_EPI) { if (wr == 0) PG8_BAR; }
	s_setprio 0
	s_add_i32 s42, s67, s45
	v_lshl_add_u64 v[216:217], v[216:217], 0, s[12:13]
	s_mov_b32 m0, s42
	ds_read_b128 v[184:187], v151 offset:49152
	ds_read_b128 v[188:191], v151 offset:50176
	ds_read_b128 v[192:195], v151 offset:51200
	ds_read_b128 v[196:199], v151 offset:52224
	ds_read_b128 v[200:203], v151 offset:53248
	ds_read_b128 v[204:207], v151 offset:54272
	ds_read_b128 v[208:211], v151 offset:55296
	ds_read_b128 v[212:215], v151 offset:56320
	global_load_lds_dwordx4 v[216:217], off
	s_add_i32 m0, s42, 0x2000
	s_add_u32 s40, s40, 0x100080
	v_lshl_add_u64 v[216:217], v[218:219], 0, s[12:13]
	s_addc_u32 s41, s41, 0
	s_add_i32 s42, s69, s45
	global_load_lds_dwordx4 v[216:217], off
	v_lshl_add_u64 v[216:217], s[40:41], 0, v[134:135]
	s_mov_b32 m0, s42
	s_nop 0
	global_load_lds_dwordx4 v[216:217], off
	v_lshl_add_u64 v[216:217], s[40:41], 0, v[130:131]
	s_add_i32 m0, s42, 0x2000
	s_nop 0
	global_load_lds_dwordx4 v[216:217], off
	v_lshl_add_u64 v[216:217], v[220:221], 0, s[12:13]
	s_mov_b32 m0, s52
	s_nop 0
	global_load_lds_dwordx4 v[216:217], off
	v_lshl_add_u64 v[216:217], v[222:223], 0, s[12:13]
	s_mov_b32 m0, s53
	s_nop 0
	global_load_lds_dwordx4 v[216:217], off
	s_setprio 1
	s_waitcnt vmcnt(8)
	s_waitcnt lgkmcnt(0)
	s_barrier
	v_mfma_f32_16x16x32_bf16 v[62:65], v[152:155], v[184:187], v[62:65]
	v_mfma_f32_16x16x32_bf16 v[58:61], v[160:163], v[184:187], v[58:61]
	v_mfma_f32_16x16x32_bf16 v[54:57], v[152:155], v[192:195], v[54:57]
	v_mfma_f32_16x16x32_bf16 v[50:53], v[160:163], v[192:195], v[50:53]
	v_mfma_f32_16x16x32_bf16 v[38:41], v[152:155], v[200:203], v[38:41]
	v_mfma_f32_16x16x32_bf16 v[34:37], v[160:163], v[200:203], v[34:37]
	v_mfma_f32_16x16x32_bf16 v[22:25], v[152:155], v[208:211], v[22:25]
	v_mfma_f32_16x16x32_bf16 v[18:21], v[160:163], v[208:211], v[18:21]
	v_mfma_f32_16x16x32_bf16 v[62:65], v[156:159], v[188:191], v[62:65]
	v_mfma_f32_16x16x32_bf16 v[58:61], v[164:167], v[188:191], v[58:61]
	v_mfma_f32_16x16x32_bf16 v[54:57], v[156:159], v[196:199], v[54:57]
	v_mfma_f32_16x16x32_bf16 v[50:53], v[164:167], v[196:199], v[50:53]
	v_mfma_f32_16x16x32_bf16 v[38:41], v[156:159], v[204:207], v[38:41]
	v_mfma_f32_16x16x32_bf16 v[34:37], v[164:167], v[204:207], v[34:37]
	v_mfma_f32_16x16x32_bf16 v[22:25], v[156:159], v[212:215], v[22:25]
	v_mfma_f32_16x16x32_bf16 v[18:21], v[164:167], v[212:215], v[18:21]
	v_mfma_f32_16x16x32_bf16 v[46:49], v[168:171], v[184:187], v[46:49]
	v_mfma_f32_16x16x32_bf16 v[42:45], v[176:179], v[184:187], v[42:45]
	v_mfma_f32_16x16x32_bf16 v[30:33], v[168:171], v[192:195], v[30:33]
	v_mfma_f32_16x16x32_bf16 v[26:29], v[176:179], v[192:195], v[26:29]
	v_mfma_f32_16x16x32_bf16 v[14:17], v[168:171], v[200:203], v[14:17]
	v_mfma_f32_16x16x32_bf16 v[10:13], v[176:179], v[200:203], v[10:13]
	v_mfma_f32_16x16x32_bf16 v[6:9], v[168:171], v[208:211], v[6:9]
	v_mfma_f32_16x16x32_bf16 v[2:5], v[176:179], v[208:211], v[2:5]
	v_mfma_f32_16x16x32_bf16 v[46:49], v[172:175], v[188:191], v[46:49]
	v_mfma_f32_16x16x32_bf16 v[42:45], v[180:183], v[188:191], v[42:45]
	v_mfma_f32_16x16x32_bf16 v[30:33], v[172:175], v[196:199], v[30:33]
	v_mfma_f32_16x16x32_bf16 v[26:29], v[180:183], v[196:199], v[26:29]
	v_mfma_f32_16x16x32_bf16 v[14:17], v[172:175], v[204:207], v[14:17]
	v_mfma_f32_16x16x32_bf16 v[10:13], v[180:183], v[204:207], v[10:13]
	v_mfma_f32_16x16x32_bf16 v[6:9], v[172:175], v[212:215], v[6:9]
	v_mfma_f32_16x16x32_bf16 v[2:5], v[180:183], v[212:215], v[2:5]
	s_barrier
	s_setprio 0
	s_add_i32 s66, s66, 2
	s_add_u32 s64, s64, 0x100
	s_addc_u32 s65, s65, 0
	s_add_u32 s38, s38, 0x100
	s_addc_u32 s39, s39, 0
	s_cmp_gt_u32 s66, 61
	s_cbranch_scc0 .LBB0_128
	s_and_b64 vcc, exec, s[14:15]
	s_cbranch_vccz .LBB0_131
	s_barrier

; #define PG8_STAGE(bufoff, gbase, voff) do { _Pragma("unroll") for (int _i = 0; _i < 2; ++_i) \
;         __builtin_amdgcn_global_load_lds((const unsigned*)((const char*)(gbase) + (voff)[_i]), (PG8_LAS unsigned*)(lds + (bufoff) + ldsw + _i * 8192), 16, 0, 0); } while (0)
; #define PG8_LDA(dst, b, h) do { _Pragma("unroll") for (int m = 0; m < 4; ++m) _Pragma("unroll") for (int k = 0; k < 2; ++k) dst[m][k] = *(const PG8_LAS bf16x8*)(lds + PG8_SA(b, h) + aoff + m * 2048 + k * 1024); } while (0)
; #define PG8_LDB(dst, b, h) do { _Pragma("unroll") for (int n = 0; n < 2; ++n) _Pragma("unroll") for (int k = 0; k < 2; ++k) dst[n][k] = *(const PG8_LAS bf16x8*)(lds + PG8_SB(b, h) + boff + n * 2048 + k * 1024); } while (0)
; #define PG8_WAIT_V(n) asm volatile("s_waitcnt vmcnt(" #n ")" ::: "memory")
; #define PG8_WAIT_L(n) asm volatile("s_waitcnt lgkmcnt(" #n ")" ::: "memory")
; #define PG8_BAR __builtin_amdgcn_s_barrier()
; #define PG8_SCHED __builtin_amdgcn_sched_barrier(0)
; template <class Epi, class Sched, bool ALIGN_EPI = false, bool SP2 = false, bool F8 = false>
; __device__ __forceinline__ void gemm_phase(PG8_LAS unsigned char* lds, const Gemm g, const Sched& S, const Epi& E) {
;     ...
;             PG8_LDB(B0, 0, 0); PG8_LDB(B1, 0, 1); PG8_SCHED; PG8_LDA(At, 0, 0); PG8_STAGE(PG8_SA(1, 1), a1 + hA, voffA);
;             PG8_WAIT_V(8); PG8_WAIT_L(0); PG8_BAR; PG8_MMA(0, 0, At, B0); PG8_MMA(0, 1, At, B1); PG8_BAR; PG8_SCHED;
;             PG8_LDA(At, 0, 1); PG8_STAGE(PG8_SB(0, 0), b2, voffB); PG8_STAGE(PG8_SB(0, 1), b2 + hB, voffB); PG8_STAGE(PG8_SA(0, 0), a2, voffA);
;             PG8_WAIT_V(8); PG8_WAIT_L(0); PG8_BAR; PG8_MMA(1, 0, At, B0); PG8_MMA(1, 1, At, B1); PG8_BAR; PG8_SCHED;
.LBB0_146:
	ds_read_b128 v[26:29], v190
	ds_read_b128 v[30:33], v190 offset:1024
	ds_read_b128 v[18:21], v190 offset:2048
	ds_read_b128 v[22:25], v190 offset:3072
	ds_read_b128 v[10:13], v191
	ds_read_b128 v[14:17], v191 offset:1024
	ds_read_b128 v[2:5], v191 offset:2048
	ds_read_b128 v[6:9], v191 offset:3072
	s_add_u32 s40, s6, 0xfff80080
	s_addc_u32 s41, s7, -1
	s_cmp_eq_u32 s60, 28
	s_cselect_b32 s43, s29, s41
	s_cselect_b32 s42, s37, s40
	s_cselect_b32 s41, s27, s59
	s_cselect_b32 s40, s44, s45
	v_lshl_add_u64 v[218:219], s[6:7], 0, v[172:173]
	s_add_i32 m0, s39, 0xc000
	ds_read_b128 v[178:181], v192
	ds_read_b128 v[182:185], v192 offset:1024
	ds_read_b128 v[194:197], v192 offset:2048
	ds_read_b128 v[198:201], v192 offset:3072
	ds_read_b128 v[202:205], v192 offset:4096
	ds_read_b128 v[206:209], v192 offset:5120
	ds_read_b128 v[210:213], v192 offset:6144
	ds_read_b128 v[214:217], v192 offset:7168
	global_load_lds_dwordx4 v[218:219], off
	v_lshl_add_u64 v[218:219], s[6:7], 0, v[170:171]
	s_add_i32 m0, s39, 0xe000
	s_nop 0
	global_load_lds_dwordx4 v[218:219], off
	s_setprio 1
	s_waitcnt vmcnt(8)
	s_waitcnt lgkmcnt(0)
	s_barrier
	v_mfma_scale_f32_16x16x128_f8f6f4 v[158:161], v[26:33], v[178:185], v[158:161], v186, v186 op_sel_hi:[0,0,0]
	v_mfma_scale_f32_16x16x128_f8f6f4 v[154:157], v[18:25], v[178:185], v[154:157], v186, v186 op_sel_hi:[0,0,0]
	v_mfma_scale_f32_16x16x128_f8f6f4 v[142:145], v[26:33], v[194:201], v[142:145], v186, v186 op_sel_hi:[0,0,0]
	v_mfma_scale_f32_16x16x128_f8f6f4 v[138:141], v[18:25], v[194:201], v[138:141], v186, v186 op_sel_hi:[0,0,0]
	v_mfma_scale_f32_16x16x128_f8f6f4 v[126:129], v[26:33], v[202:209], v[126:129], v186, v186 op_sel_hi:[0,0,0]
	v_mfma_scale_f32_16x16x128_f8f6f4 v[122:125], v[18:25], v[202:209], v[122:125], v186, v186 op_sel_hi:[0,0,0]
	v_mfma_scale_f32_16x16x128_f8f6f4 v[110:113], v[26:33], v[210:217], v[110:113], v186, v186 op_sel_hi:[0,0,0]
	v_mfma_scale_f32_16x16x128_f8f6f4 v[106:109], v[18:25], v[210:217], v[106:109], v186, v186 op_sel_hi:[0,0,0]
	v_mfma_scale_f32_16x16x128_f8f6f4 v[150:153], v[10:17], v[178:185], v[150:153], v186, v186 op_sel_hi:[0,0,0]
	v_mfma_scale_f32_16x16x128_f8f6f4 v[146:149], v[2:9], v[178:185], v[146:149], v186, v186 op_sel_hi:[0,0,0]
	v_mfma_scale_f32_16x16x128_f8f6f4 v[134:137], v[10:17], v[194:201], v[134:137], v186, v186 op_sel_hi:[0,0,0]
	v_mfma_scale_f32_16x16x128_f8f6f4 v[130:133], v[2:9], v[194:201], v[130:133], v186, v186 op_sel_hi:[0,0,0]
	v_mfma_scale_f32_16x16x128_f8f6f4 v[118:121], v[10:17], v[202:209], v[118:121], v186, v186 op_sel_hi:[0,0,0]
	v_mfma_scale_f32_16x16x128_f8f6f4 v[114:117], v[2:9], v[202:209], v[114:117], v186, v186 op_sel_hi:[0,0,0]
	v_mfma_scale_f32_16x16x128_f8f6f4 v[102:105], v[10:17], v[210:217], v[102:105], v186, v186 op_sel_hi:[0,0,0]
	v_mfma_scale_f32_16x16x128_f8f6f4 v[98:101], v[2:9], v[210:217], v[98:101], v186, v186 op_sel_hi:[0,0,0]
	s_barrier
	s_setprio 0
	s_add_i32 s61, s57, s47
	v_lshl_add_u64 v[178:179], s[40:41], 0, v[164:165]
	s_mov_b32 m0, s61
	ds_read_b128 v[194:197], v192 offset:16384
	ds_read_b128 v[198:201], v192 offset:17408
	ds_read_b128 v[202:205], v192 offset:18432
	ds_read_b128 v[206:209], v192 offset:19456
	ds_read_b128 v[210:213], v192 offset:20480
	ds_read_b128 v[214:217], v192 offset:21504
	ds_read_b128 v[218:221], v192 offset:22528
	ds_read_b128 v[222:225], v192 offset:23552
	global_load_lds_dwordx4 v[178:179], off
	s_add_i32 m0, s61, 0x2000
	s_add_u32 s62, s40, 0x80000
	v_lshl_add_u64 v[180:181], s[40:41], 0, v[168:169]
	s_addc_u32 s63, s41, 0
	s_add_i32 s61, s58, s47
	global_load_lds_dwordx4 v[180:181], off
	v_lshl_add_u64 v[182:183], s[62:63], 0, v[164:165]
	s_mov_b32 m0, s61
	v_lshl_add_u64 v[184:185], s[42:43], 0, v[166:167]
	global_load_lds_dwordx4 v[182:183], off
	v_lshl_add_u64 v[182:183], s[62:63], 0, v[168:169]
	s_add_i32 m0, s61, 0x2000
	s_nop 0
	global_load_lds_dwordx4 v[182:183], off
	v_lshl_add_u64 v[182:183], s[42:43], 0, v[162:163]
	s_mov_b32 m0, s39
	s_nop 0
	global_load_lds_dwordx4 v[182:183], off
	s_mov_b32 m0, s48
	s_nop 0
	global_load_lds_dwordx4 v[184:185], off
	s_setprio 1
	s_waitcnt vmcnt(8)
	s_waitcnt lgkmcnt(0)
	s_barrier
	v_mfma_scale_f32_16x16x128_f8f6f4 v[94:97], v[26:33], v[194:201], v[94:97], v186, v186 op_sel_hi:[0,0,0]
	v_mfma_scale_f32_16x16x128_f8f6f4 v[90:93], v[18:25], v[194:201], v[90:93], v186, v186 op_sel_hi:[0,0,0]
	v_mfma_scale_f32_16x16x128_f8f6f4 v[78:81], v[26:33], v[202:209], v[78:81], v186, v186 op_sel_hi:[0,0,0]
	v_mfma_scale_f32_16x16x128_f8f6f4 v[74:77], v[18:25], v[202:209], v[74:77], v186, v186 op_sel_hi:[0,0,0]
	v_mfma_scale_f32_16x16x128_f8f6f4 v[62:65], v[26:33], v[210:217], v[62:65], v186, v186 op_sel_hi:[0,0,0]
	v_mfma_scale_f32_16x16x128_f8f6f4 v[58:61], v[18:25], v[210:217], v[58:61], v186, v186 op_sel_hi:[0,0,0]
	v_mfma_scale_f32_16x16x128_f8f6f4 v[46:49], v[26:33], v[218:225], v[46:49], v186, v186 op_sel_hi:[0,0,0]
	v_mfma_scale_f32_16x16x128_f8f6f4 v[42:45], v[18:25], v[218:225], v[42:45], v186, v186 op_sel_hi:[0,0,0]
	v_mfma_scale_f32_16x16x128_f8f6f4 v[86:89], v[10:17], v[194:201], v[86:89], v186, v186 op_sel_hi:[0,0,0]
	v_mfma_scale_f32_16x16x128_f8f6f4 v[82:85], v[2:9], v[194:201], v[82:85], v186, v186 op_sel_hi:[0,0,0]
	v_mfma_scale_f32_16x16x128_f8f6f4 v[70:73], v[10:17], v[202:209], v[70:73], v186, v186 op_sel_hi:[0,0,0]
	v_mfma_scale_f32_16x16x128_f8f6f4 v[66:69], v[2:9], v[202:209], v[66:69], v186, v186 op_sel_hi:[0,0,0]
	v_mfma_scale_f32_16x16x128_f8f6f4 v[54:57], v[10:17], v[210:217], v[54:57], v186, v186 op_sel_hi:[0,0,0]
	v_mfma_scale_f32_16x16x128_f8f6f4 v[50:53], v[2:9], v[210:217], v[50:53], v186, v186 op_sel_hi:[0,0,0]
	v_mfma_scale_f32_16x16x128_f8f6f4 v[38:41], v[10:17], v[218:225], v[38:41], v186, v186 op_sel_hi:[0,0,0]
	v_mfma_scale_f32_16x16x128_f8f6f4 v[34:37], v[2:9], v[218:225], v[34:37], v186, v186 op_sel_hi:[0,0,0]
	s_barrier
; #define PG8_STAGE(bufoff, gbase, voff) do { _Pragma("unroll") for (int _i = 0; _i < 2; ++_i) \
;         __builtin_amdgcn_global_load_lds((const unsigned*)((const char*)(gbase) + (voff)[_i]), (PG8_LAS unsigned*)(lds + (bufoff) + ldsw + _i * 8192), 16, 0, 0); } while (0)
; #define PG8_LDA(dst, b, h) do { _Pragma("unroll") for (int m = 0; m < 4; ++m) _Pragma("unroll") for (int k = 0; k < 2; ++k) dst[m][k] = *(const PG8_LAS bf16x8*)(lds + PG8_SA(b, h) + aoff + m * 2048 + k * 1024); } while (0)
; #define PG8_LDB(dst, b, h) do { _Pragma("unroll") for (int n = 0; n < 2; ++n) _Pragma("unroll") for (int k = 0; k < 2; ++k) dst[n][k] = *(const PG8_LAS bf16x8*)(lds + PG8_SB(b, h) + boff + n * 2048 + k * 1024); } while (0)
; #define PG8_WAIT_V(n) asm volatile("s_waitcnt vmcnt(" #n ")" ::: "memory")
; #define PG8_WAIT_L(n) asm volatile("s_waitcnt lgkmcnt(" #n ")" ::: "memory")
; #define PG8_BAR __builtin_amdgcn_s_barrier()
; #define PG8_SCHED __builtin_amdgcn_sched_barrier(0)
; template <class Epi, class Sched, bool ALIGN_EPI = false, bool SP2 = false, bool F8 = false>
; __device__ __forceinline__ void gemm_phase(PG8_LAS unsigned char* lds, const Gemm g, const Sched& S, const Epi& E) {
;     ...
;             PG8_LDB(B0, 1, 0); PG8_LDB(B1, 1, 1); PG8_SCHED; PG8_LDA(At, 1, 0); PG8_STAGE(PG8_SA(0, 1), a2 + hA, voffA);
;             PG8_WAIT_V(8); PG8_WAIT_L(0); PG8_BAR; PG8_MMA(0, 0, At, B0); PG8_MMA(0, 1, At, B1); PG8_BAR; PG8_SCHED;
;             PG8_LDA(At, 1, 1); PG8_STAGE(PG8_SB(1, 0), b3, voffB); PG8_STAGE(PG8_SB(1, 1), b3 + hB, voffB); PG8_STAGE(PG8_SA(1, 0), a3, voffA);
;             PG8_WAIT_V(8); PG8_WAIT_L(0); PG8_BAR; PG8_MMA(1, 0, At, B0); PG8_MMA(1, 1, At, B1); PG8_BAR; PG8_SCHED;
;     ...
;         if constexpr (ALIGN_EPI) { if (wr == 0) PG8_BAR; }
	s_setprio 0
	s_add_i32 s61, 0, 0x18000
	s_add_i32 s62, 0, 0x1c000
	v_add_u32_e32 v14, s61, v188
	v_add_u32_e32 v30, s62, v188
	ds_read_b128 v[2:5], v14
	ds_read_b128 v[6:9], v14 offset:1024
	ds_read_b128 v[10:13], v14 offset:2048
	ds_read_b128 v[14:17], v14 offset:3072
	ds_read_b128 v[18:21], v30
	ds_read_b128 v[22:25], v30 offset:1024
	ds_read_b128 v[26:29], v30 offset:2048
	ds_read_b128 v[30:33], v30 offset:3072
	s_add_u32 s42, s42, 0x80000
	s_addc_u32 s43, s43, 0
	s_mov_b32 m0, s49
	v_lshl_add_u64 v[226:227], s[42:43], 0, v[162:163]
	ds_read_b128 v[194:197], v192 offset:32768
	ds_read_b128 v[198:201], v192 offset:33792
	ds_read_b128 v[202:205], v192 offset:34816
	ds_read_b128 v[206:209], v192 offset:35840
	ds_read_b128 v[210:213], v192 offset:36864
	ds_read_b128 v[214:217], v192 offset:37888
	ds_read_b128 v[218:221], v192 offset:38912
	ds_read_b128 v[222:225], v192 offset:39936
	global_load_lds_dwordx4 v[226:227], off
	v_lshl_add_u64 v[226:227], s[42:43], 0, v[166:167]
	s_mov_b32 m0, s50
	s_nop 0
	global_load_lds_dwordx4 v[226:227], off
	s_setprio 1
	s_waitcnt vmcnt(8)
	s_waitcnt lgkmcnt(0)
	s_barrier
	v_mfma_scale_f32_16x16x128_f8f6f4 v[158:161], v[2:9], v[194:201], v[158:161], v186, v186 op_sel_hi:[0,0,0]
	v_mfma_scale_f32_16x16x128_f8f6f4 v[154:157], v[10:17], v[194:201], v[154:157], v186, v186 op_sel_hi:[0,0,0]
	v_mfma_scale_f32_16x16x128_f8f6f4 v[142:145], v[2:9], v[202:209], v[142:145], v186, v186 op_sel_hi:[0,0,0]
	v_mfma_scale_f32_16x16x128_f8f6f4 v[138:141], v[10:17], v[202:209], v[138:141], v186, v186 op_sel_hi:[0,0,0]
	v_mfma_scale_f32_16x16x128_f8f6f4 v[126:129], v[2:9], v[210:217], v[126:129], v186, v186 op_sel_hi:[0,0,0]
	v_mfma_scale_f32_16x16x128_f8f6f4 v[122:125], v[10:17], v[210:217], v[122:125], v186, v186 op_sel_hi:[0,0,0]
	v_mfma_scale_f32_16x16x128_f8f6f4 v[110:113], v[2:9], v[218:225], v[110:113], v186, v186 op_sel_hi:[0,0,0]
	v_mfma_scale_f32_16x16x128_f8f6f4 v[106:109], v[10:17], v[218:225], v[106:109], v186, v186 op_sel_hi:[0,0,0]
	v_mfma_scale_f32_16x16x128_f8f6f4 v[150:153], v[18:25], v[194:201], v[150:153], v186, v186 op_sel_hi:[0,0,0]
	v_mfma_scale_f32_16x16x128_f8f6f4 v[146:149], v[26:33], v[194:201], v[146:149], v186, v186 op_sel_hi:[0,0,0]
	v_mfma_scale_f32_16x16x128_f8f6f4 v[134:137], v[18:25], v[202:209], v[134:137], v186, v186 op_sel_hi:[0,0,0]
	v_mfma_scale_f32_16x16x128_f8f6f4 v[130:133], v[26:33], v[202:209], v[130:133], v186, v186 op_sel_hi:[0,0,0]
	v_mfma_scale_f32_16x16x128_f8f6f4 v[118:121], v[18:25], v[210:217], v[118:121], v186, v186 op_sel_hi:[0,0,0]
	v_mfma_scale_f32_16x16x128_f8f6f4 v[114:117], v[26:33], v[210:217], v[114:117], v186, v186 op_sel_hi:[0,0,0]
	v_mfma_scale_f32_16x16x128_f8f6f4 v[102:105], v[18:25], v[218:225], v[102:105], v186, v186 op_sel_hi:[0,0,0]
	v_mfma_scale_f32_16x16x128_f8f6f4 v[98:101], v[26:33], v[218:225], v[98:101], v186, v186 op_sel_hi:[0,0,0]
	s_barrier
	s_setprio 0
	s_add_i32 s42, s61, s47
	v_lshl_add_u64 v[178:179], v[178:179], 0, s[22:23]
	s_mov_b32 m0, s42
	ds_read_b128 v[194:197], v192 offset:49152
	ds_read_b128 v[198:201], v192 offset:50176
	ds_read_b128 v[202:205], v192 offset:51200
	ds_read_b128 v[206:209], v192 offset:52224
	ds_read_b128 v[210:213], v192 offset:53248
	ds_read_b128 v[214:217], v192 offset:54272
	ds_read_b128 v[218:221], v192 offset:55296
	ds_read_b128 v[222:225], v192 offset:56320
	global_load_lds_dwordx4 v[178:179], off
	s_add_i32 m0, s42, 0x2000
	s_add_u32 s40, s40, 0x80080
	v_lshl_add_u64 v[178:179], v[180:181], 0, s[22:23]
	s_addc_u32 s41, s41, 0
	s_add_i32 s42, s62, s47
	global_load_lds_dwordx4 v[178:179], off
	v_lshl_add_u64 v[178:179], s[40:41], 0, v[164:165]
	s_mov_b32 m0, s42
	s_nop 0
	global_load_lds_dwordx4 v[178:179], off
	v_lshl_add_u64 v[178:179], s[40:41], 0, v[168:169]
	s_add_i32 m0, s42, 0x2000
	s_nop 0
	global_load_lds_dwordx4 v[178:179], off
	v_lshl_add_u64 v[178:179], v[182:183], 0, s[22:23]
	s_mov_b32 m0, s52
	s_nop 0
	global_load_lds_dwordx4 v[178:179], off
	v_lshl_add_u64 v[178:179], v[184:185], 0, s[22:23]
	s_mov_b32 m0, s53
	s_nop 0
	global_load_lds_dwordx4 v[178:179], off
	s_setprio 1
	s_waitcnt vmcnt(8)
	s_waitcnt lgkmcnt(0)
	s_barrier
	v_mfma_scale_f32_16x16x128_f8f6f4 v[94:97], v[2:9], v[194:201], v[94:97], v186, v186 op_sel_hi:[0,0,0]
	v_mfma_scale_f32_16x16x128_f8f6f4 v[90:93], v[10:17], v[194:201], v[90:93], v186, v186 op_sel_hi:[0,0,0]
	v_mfma_scale_f32_16x16x128_f8f6f4 v[78:81], v[2:9], v[202:209], v[78:81], v186, v186 op_sel_hi:[0,0,0]
	v_mfma_scale_f32_16x16x128_f8f6f4 v[74:77], v[10:17], v[202:209], v[74:77], v186, v186 op_sel_hi:[0,0,0]
	v_mfma_scale_f32_16x16x128_f8f6f4 v[62:65], v[2:9], v[210:217], v[62:65], v186, v186 op_sel_hi:[0,0,0]
	v_mfma_scale_f32_16x16x128_f8f6f4 v[58:61], v[10:17], v[210:217], v[58:61], v186, v186 op_sel_hi:[0,0,0]
	v_mfma_scale_f32_16x16x128_f8f6f4 v[46:49], v[2:9], v[218:225], v[46:49], v186, v186 op_sel_hi:[0,0,0]
	v_mfma_scale_f32_16x16x128_f8f6f4 v[42:45], v[10:17], v[218:225], v[42:45], v186, v186 op_sel_hi:[0,0,0]
	v_mfma_scale_f32_16x16x128_f8f6f4 v[86:89], v[18:25], v[194:201], v[86:89], v186, v186 op_sel_hi:[0,0,0]
	v_mfma_scale_f32_16x16x128_f8f6f4 v[82:85], v[26:33], v[194:201], v[82:85], v186, v186 op_sel_hi:[0,0,0]
	v_mfma_scale_f32_16x16x128_f8f6f4 v[70:73], v[18:25], v[202:209], v[70:73], v186, v186 op_sel_hi:[0,0,0]
	v_mfma_scale_f32_16x16x128_f8f6f4 v[66:69], v[26:33], v[202:209], v[66:69], v186, v186 op_sel_hi:[0,0,0]
	v_mfma_scale_f32_16x16x128_f8f6f4 v[54:57], v[18:25], v[210:217], v[54:57], v186, v186 op_sel_hi:[0,0,0]
	v_mfma_scale_f32_16x16x128_f8f6f4 v[50:53], v[26:33], v[210:217], v[50:53], v186, v186 op_sel_hi:[0,0,0]
	v_mfma_scale_f32_16x16x128_f8f6f4 v[38:41], v[18:25], v[218:225], v[38:41], v186, v186 op_sel_hi:[0,0,0]
	v_mfma_scale_f32_16x16x128_f8f6f4 v[34:37], v[26:33], v[218:225], v[34:37], v186, v186 op_sel_hi:[0,0,0]
	s_barrier
	s_setprio 0
	s_add_i32 s60, s60, 2
	s_add_u32 s45, s45, 0x100
	s_addc_u32 s59, s59, 0
	s_add_u32 s6, s6, 0x100
	s_addc_u32 s7, s7, 0
	s_cmp_gt_u32 s60, 29
	s_cbranch_scc0 .LBB0_146
	s_and_b64 vcc, exec, s[24:25]
	s_cbranch_vccz .LBB0_149
	s_barrier

; #define PG8_STAGE(bufoff, gbase, voff) do { _Pragma("unroll") for (int _i = 0; _i < 2; ++_i) \
;         __builtin_amdgcn_global_load_lds((const unsigned*)((const char*)(gbase) + (voff)[_i]), (PG8_LAS unsigned*)(lds + (bufoff) + ldsw + _i * 8192), 16, 0, 0); } while (0)
; #define PG8_LDA(dst, b, h) do { _Pragma("unroll") for (int m = 0; m < 4; ++m) _Pragma("unroll") for (int k = 0; k < 2; ++k) dst[m][k] = *(const PG8_LAS bf16x8*)(lds + PG8_SA(b, h) + aoff + m * 2048 + k * 1024); } while (0)
; #define PG8_LDB(dst, b, h) do { _Pragma("unroll") for (int n = 0; n < 2; ++n) _Pragma("unroll") for (int k = 0; k < 2; ++k) dst[n][k] = *(const PG8_LAS bf16x8*)(lds + PG8_SB(b, h) + boff + n * 2048 + k * 1024); } while (0)
; #define PG8_WAIT_V(n) asm volatile("s_waitcnt vmcnt(" #n ")" ::: "memory")
; #define PG8_WAIT_L(n) asm volatile("s_waitcnt lgkmcnt(" #n ")" ::: "memory")
; #define PG8_BAR __builtin_amdgcn_s_barrier()
; #define PG8_SCHED __builtin_amdgcn_sched_barrier(0)
; template <class Epi, class Sched, bool ALIGN_EPI = false, bool SP2 = false, bool F8 = false>
; __device__ __forceinline__ void gemm_phase(PG8_LAS unsigned char* lds, const Gemm g, const Sched& S, const Epi& E) {
;     ...
;             PG8_LDB(B0, 0, 0); PG8_LDB(B1, 0, 1); PG8_SCHED; PG8_LDA(At, 0, 0); PG8_STAGE(PG8_SA(1, 1), a1 + hA, voffA);
;             PG8_WAIT_V(8); PG8_WAIT_L(0); PG8_BAR; PG8_MMA(0, 0, At, B0); PG8_MMA(0, 1, At, B1); PG8_BAR; PG8_SCHED;
;             PG8_LDA(At, 0, 1); PG8_STAGE(PG8_SB(0, 0), b2, voffB); PG8_STAGE(PG8_SB(0, 1), b2 + hB, voffB); PG8_STAGE(PG8_SA(0, 0), a2, voffA);
;             PG8_WAIT_V(8); PG8_WAIT_L(0); PG8_BAR; PG8_MMA(1, 0, At, B0); PG8_MMA(1, 1, At, B1); PG8_BAR; PG8_SCHED;
.LBB0_618:
	ds_read_b128 v[130:133], v185
	ds_read_b128 v[134:137], v185 offset:1024
	ds_read_b128 v[138:141], v185 offset:2048
	ds_read_b128 v[142:145], v185 offset:3072
	ds_read_b128 v[146:149], v186
	ds_read_b128 v[150:153], v186 offset:1024
	ds_read_b128 v[154:157], v186 offset:2048
	ds_read_b128 v[174:177], v186 offset:3072
	s_add_u32 s40, s38, 0xfff80080
	s_addc_u32 s41, s39, -1
	s_cmp_eq_u32 s59, 4
	s_cselect_b32 s43, s29, s41
	s_cselect_b32 s42, s55, s40
	s_cselect_b32 s41, s27, s58
	s_cselect_b32 s40, s56, s57
	v_lshl_add_u64 v[216:217], s[38:39], 0, v[168:169]
	s_add_i32 m0, s37, 0xc000
	ds_read_b128 v[178:181], v187
	ds_read_b128 v[188:191], v187 offset:1024
	ds_read_b128 v[192:195], v187 offset:2048
	ds_read_b128 v[196:199], v187 offset:3072
	ds_read_b128 v[200:203], v187 offset:4096
	ds_read_b128 v[204:207], v187 offset:5120
	ds_read_b128 v[208:211], v187 offset:6144
	ds_read_b128 v[212:215], v187 offset:7168
	global_load_lds_dwordx4 v[216:217], off
	v_lshl_add_u64 v[216:217], s[38:39], 0, v[166:167]
	s_add_i32 m0, s37, 0xe000
	s_nop 0
	global_load_lds_dwordx4 v[216:217], off
	s_setprio 1
	s_waitcnt vmcnt(8)
	s_waitcnt lgkmcnt(0)
	s_barrier
	v_mfma_f32_16x16x32_bf16 v[126:129], v[130:133], v[178:181], v[126:129]
	v_mfma_f32_16x16x32_bf16 v[122:125], v[138:141], v[178:181], v[122:125]
	v_mfma_f32_16x16x32_bf16 v[110:113], v[130:133], v[192:195], v[110:113]
	v_mfma_f32_16x16x32_bf16 v[106:109], v[138:141], v[192:195], v[106:109]
	v_mfma_f32_16x16x32_bf16 v[94:97], v[130:133], v[200:203], v[94:97]
	v_mfma_f32_16x16x32_bf16 v[90:93], v[138:141], v[200:203], v[90:93]
	v_mfma_f32_16x16x32_bf16 v[78:81], v[130:133], v[208:211], v[78:81]
	v_mfma_f32_16x16x32_bf16 v[74:77], v[138:141], v[208:211], v[74:77]
	v_mfma_f32_16x16x32_bf16 v[126:129], v[134:137], v[188:191], v[126:129]
	v_mfma_f32_16x16x32_bf16 v[122:125], v[142:145], v[188:191], v[122:125]
	v_mfma_f32_16x16x32_bf16 v[110:113], v[134:137], v[196:199], v[110:113]
	v_mfma_f32_16x16x32_bf16 v[106:109], v[142:145], v[196:199], v[106:109]
	v_mfma_f32_16x16x32_bf16 v[94:97], v[134:137], v[204:207], v[94:97]
	v_mfma_f32_16x16x32_bf16 v[90:93], v[142:145], v[204:207], v[90:93]
	v_mfma_f32_16x16x32_bf16 v[78:81], v[134:137], v[212:215], v[78:81]
	v_mfma_f32_16x16x32_bf16 v[74:77], v[142:145], v[212:215], v[74:77]
	v_mfma_f32_16x16x32_bf16 v[118:121], v[146:149], v[178:181], v[118:121]
	v_mfma_f32_16x16x32_bf16 v[114:117], v[154:157], v[178:181], v[114:117]
	v_mfma_f32_16x16x32_bf16 v[102:105], v[146:149], v[192:195], v[102:105]
	v_mfma_f32_16x16x32_bf16 v[98:101], v[154:157], v[192:195], v[98:101]
	v_mfma_f32_16x16x32_bf16 v[86:89], v[146:149], v[200:203], v[86:89]
	v_mfma_f32_16x16x32_bf16 v[82:85], v[154:157], v[200:203], v[82:85]
	v_mfma_f32_16x16x32_bf16 v[70:73], v[146:149], v[208:211], v[70:73]
	v_mfma_f32_16x16x32_bf16 v[66:69], v[154:157], v[208:211], v[66:69]
	v_mfma_f32_16x16x32_bf16 v[118:121], v[150:153], v[188:191], v[118:121]
	v_mfma_f32_16x16x32_bf16 v[114:117], v[174:177], v[188:191], v[114:117]
	v_mfma_f32_16x16x32_bf16 v[102:105], v[150:153], v[196:199], v[102:105]
	v_mfma_f32_16x16x32_bf16 v[98:101], v[174:177], v[196:199], v[98:101]
	v_mfma_f32_16x16x32_bf16 v[86:89], v[150:153], v[204:207], v[86:89]
	v_mfma_f32_16x16x32_bf16 v[82:85], v[174:177], v[204:207], v[82:85]
	v_mfma_f32_16x16x32_bf16 v[70:73], v[150:153], v[212:215], v[70:73]
	v_mfma_f32_16x16x32_bf16 v[66:69], v[174:177], v[212:215], v[66:69]
	s_barrier
	s_setprio 0
	s_add_i32 s60, s52, s19
	v_lshl_add_u64 v[216:217], s[40:41], 0, v[162:163]
	s_mov_b32 m0, s60
	ds_read_b128 v[178:181], v187 offset:16384
	ds_read_b128 v[188:191], v187 offset:17408
	ds_read_b128 v[192:195], v187 offset:18432
	ds_read_b128 v[196:199], v187 offset:19456
	ds_read_b128 v[200:203], v187 offset:20480
	ds_read_b128 v[204:207], v187 offset:21504
	ds_read_b128 v[208:211], v187 offset:22528
	ds_read_b128 v[212:215], v187 offset:23552
	global_load_lds_dwordx4 v[216:217], off
	s_add_i32 m0, s60, 0x2000
	s_add_u32 s60, s40, 0x20000
	v_lshl_add_u64 v[218:219], s[40:41], 0, v[158:159]
	s_addc_u32 s61, s41, 0
	s_add_i32 s62, s53, s19
	global_load_lds_dwordx4 v[218:219], off
	v_lshl_add_u64 v[220:221], s[60:61], 0, v[162:163]
	s_mov_b32 m0, s62
	v_lshl_add_u64 v[222:223], s[42:43], 0, v[160:161]
	global_load_lds_dwordx4 v[220:221], off
	v_lshl_add_u64 v[220:221], s[60:61], 0, v[158:159]
	s_add_i32 m0, s62, 0x2000
	s_nop 0
	global_load_lds_dwordx4 v[220:221], off
	v_lshl_add_u64 v[220:221], s[42:43], 0, v[164:165]
	s_mov_b32 m0, s37
	s_nop 0
	global_load_lds_dwordx4 v[220:221], off
	s_mov_b32 m0, s45
	s_nop 0
	global_load_lds_dwordx4 v[222:223], off
	s_setprio 1
	s_waitcnt vmcnt(8)
	s_waitcnt lgkmcnt(0)
	s_barrier
; #define PG8_STAGE(bufoff, gbase, voff) do { _Pragma("unroll") for (int _i = 0; _i < 2; ++_i) \
;         __builtin_amdgcn_global_load_lds((const unsigned*)((const char*)(gbase) + (voff)[_i]), (PG8_LAS unsigned*)(lds + (bufoff) + ldsw + _i * 8192), 16, 0, 0); } while (0)
; #define PG8_LDA(dst, b, h) do { _Pragma("unroll") for (int m = 0; m < 4; ++m) _Pragma("unroll") for (int k = 0; k < 2; ++k) dst[m][k] = *(const PG8_LAS bf16x8*)(lds + PG8_SA(b, h) + aoff + m * 2048 + k * 1024); } while (0)
; #define PG8_LDB(dst, b, h) do { _Pragma("unroll") for (int n = 0; n < 2; ++n) _Pragma("unroll") for (int k = 0; k < 2; ++k) dst[n][k] = *(const PG8_LAS bf16x8*)(lds + PG8_SB(b, h) + boff + n * 2048 + k * 1024); } while (0)
; #define PG8_WAIT_V(n) asm volatile("s_waitcnt vmcnt(" #n ")" ::: "memory")
; #define PG8_WAIT_L(n) asm volatile("s_waitcnt lgkmcnt(" #n ")" ::: "memory")
; #define PG8_BAR __builtin_amdgcn_s_barrier()
; #define PG8_SCHED __builtin_amdgcn_sched_barrier(0)
; template <class Epi, class Sched, bool ALIGN_EPI = false, bool SP2 = false, bool F8 = false>
; __device__ __forceinline__ void gemm_phase(PG8_LAS unsigned char* lds, const Gemm g, const Sched& S, const Epi& E) {
;     ...
;             PG8_WAIT_V(8); PG8_WAIT_L(0); PG8_BAR; PG8_MMA(1, 0, At, B0); PG8_MMA(1, 1, At, B1); PG8_BAR; PG8_SCHED;
;             PG8_LDB(B0, 1, 0); PG8_LDB(B1, 1, 1); PG8_SCHED; PG8_LDA(At, 1, 0); PG8_STAGE(PG8_SA(0, 1), a2 + hA, voffA);
;             PG8_WAIT_V(8); PG8_WAIT_L(0); PG8_BAR; PG8_MMA(0, 0, At, B0); PG8_MMA(0, 1, At, B1); PG8_BAR; PG8_SCHED;
	v_mfma_f32_16x16x32_bf16 v[62:65], v[130:133], v[178:181], v[62:65]
	v_mfma_f32_16x16x32_bf16 v[58:61], v[138:141], v[178:181], v[58:61]
	v_mfma_f32_16x16x32_bf16 v[46:49], v[130:133], v[192:195], v[46:49]
	v_mfma_f32_16x16x32_bf16 v[42:45], v[138:141], v[192:195], v[42:45]
	v_mfma_f32_16x16x32_bf16 v[30:33], v[130:133], v[200:203], v[30:33]
	v_mfma_f32_16x16x32_bf16 v[26:29], v[138:141], v[200:203], v[26:29]
	v_mfma_f32_16x16x32_bf16 v[14:17], v[130:133], v[208:211], v[14:17]
	v_mfma_f32_16x16x32_bf16 v[10:13], v[138:141], v[208:211], v[10:13]
	v_mfma_f32_16x16x32_bf16 v[62:65], v[134:137], v[188:191], v[62:65]
	v_mfma_f32_16x16x32_bf16 v[58:61], v[142:145], v[188:191], v[58:61]
	v_mfma_f32_16x16x32_bf16 v[46:49], v[134:137], v[196:199], v[46:49]
	v_mfma_f32_16x16x32_bf16 v[42:45], v[142:145], v[196:199], v[42:45]
	v_mfma_f32_16x16x32_bf16 v[30:33], v[134:137], v[204:207], v[30:33]
	v_mfma_f32_16x16x32_bf16 v[26:29], v[142:145], v[204:207], v[26:29]
	v_mfma_f32_16x16x32_bf16 v[14:17], v[134:137], v[212:215], v[14:17]
	v_mfma_f32_16x16x32_bf16 v[10:13], v[142:145], v[212:215], v[10:13]
	v_mfma_f32_16x16x32_bf16 v[54:57], v[146:149], v[178:181], v[54:57]
	v_mfma_f32_16x16x32_bf16 v[50:53], v[154:157], v[178:181], v[50:53]
	v_mfma_f32_16x16x32_bf16 v[38:41], v[146:149], v[192:195], v[38:41]
	v_mfma_f32_16x16x32_bf16 v[34:37], v[154:157], v[192:195], v[34:37]
	v_mfma_f32_16x16x32_bf16 v[22:25], v[146:149], v[200:203], v[22:25]
	v_mfma_f32_16x16x32_bf16 v[18:21], v[154:157], v[200:203], v[18:21]
	v_mfma_f32_16x16x32_bf16 v[6:9], v[146:149], v[208:211], v[6:9]
	v_mfma_f32_16x16x32_bf16 v[2:5], v[154:157], v[208:211], v[2:5]
	v_mfma_f32_16x16x32_bf16 v[54:57], v[150:153], v[188:191], v[54:57]
	v_mfma_f32_16x16x32_bf16 v[50:53], v[174:177], v[188:191], v[50:53]
	v_mfma_f32_16x16x32_bf16 v[38:41], v[150:153], v[196:199], v[38:41]
	v_mfma_f32_16x16x32_bf16 v[34:37], v[174:177], v[196:199], v[34:37]
	v_mfma_f32_16x16x32_bf16 v[22:25], v[150:153], v[204:207], v[22:25]
	v_mfma_f32_16x16x32_bf16 v[18:21], v[174:177], v[204:207], v[18:21]
	v_mfma_f32_16x16x32_bf16 v[6:9], v[150:153], v[212:215], v[6:9]
	v_mfma_f32_16x16x32_bf16 v[2:5], v[174:177], v[212:215], v[2:5]
	s_barrier
	s_setprio 0
	s_add_i32 s60, 0, 0x18000
	s_add_i32 s61, 0, 0x1c000
	v_add_u32_e32 v142, s60, v183
	v_add_u32_e32 v174, s61, v183
	ds_read_b128 v[130:133], v142
	ds_read_b128 v[134:137], v142 offset:1024
	ds_read_b128 v[138:141], v142 offset:2048
	ds_read_b128 v[142:145], v142 offset:3072
	ds_read_b128 v[146:149], v174
	ds_read_b128 v[150:153], v174 offset:1024
	ds_read_b128 v[154:157], v174 offset:2048
	ds_read_b128 v[174:177], v174 offset:3072
	s_add_u32 s42, s42, 0x80000
	s_addc_u32 s43, s43, 0
	s_mov_b32 m0, s46
	v_lshl_add_u64 v[224:225], s[42:43], 0, v[164:165]
	ds_read_b128 v[178:181], v187 offset:32768
	ds_read_b128 v[188:191], v187 offset:33792
	ds_read_b128 v[192:195], v187 offset:34816
	ds_read_b128 v[196:199], v187 offset:35840
	ds_read_b128 v[200:203], v187 offset:36864
	ds_read_b128 v[204:207], v187 offset:37888
	ds_read_b128 v[208:211], v187 offset:38912
	ds_read_b128 v[212:215], v187 offset:39936
	global_load_lds_dwordx4 v[224:225], off
	v_lshl_add_u64 v[224:225], s[42:43], 0, v[160:161]
	s_mov_b32 m0, s47
	s_nop 0
	global_load_lds_dwordx4 v[224:225], off
	s_setprio 1
	s_waitcnt vmcnt(8)
	s_waitcnt lgkmcnt(0)
	s_barrier
	v_mfma_f32_16x16x32_bf16 v[126:129], v[130:133], v[178:181], v[126:129]
	v_mfma_f32_16x16x32_bf16 v[122:125], v[138:141], v[178:181], v[122:125]
	v_mfma_f32_16x16x32_bf16 v[110:113], v[130:133], v[192:195], v[110:113]
	v_mfma_f32_16x16x32_bf16 v[106:109], v[138:141], v[192:195], v[106:109]
	v_mfma_f32_16x16x32_bf16 v[94:97], v[130:133], v[200:203], v[94:97]
	v_mfma_f32_16x16x32_bf16 v[90:93], v[138:141], v[200:203], v[90:93]
	v_mfma_f32_16x16x32_bf16 v[78:81], v[130:133], v[208:211], v[78:81]
	v_mfma_f32_16x16x32_bf16 v[74:77], v[138:141], v[208:211], v[74:77]
	v_mfma_f32_16x16x32_bf16 v[126:129], v[134:137], v[188:191], v[126:129]
	v_mfma_f32_16x16x32_bf16 v[122:125], v[142:145], v[188:191], v[122:125]
	v_mfma_f32_16x16x32_bf16 v[110:113], v[134:137], v[196:199], v[110:113]
	v_mfma_f32_16x16x32_bf16 v[106:109], v[142:145], v[196:199], v[106:109]
	v_mfma_f32_16x16x32_bf16 v[94:97], v[134:137], v[204:207], v[94:97]
	v_mfma_f32_16x16x32_bf16 v[90:93], v[142:145], v[204:207], v[90:93]
	v_mfma_f32_16x16x32_bf16 v[78:81], v[134:137], v[212:215], v[78:81]
	v_mfma_f32_16x16x32_bf16 v[74:77], v[142:145], v[212:215], v[74:77]
	v_mfma_f32_16x16x32_bf16 v[118:121], v[146:149], v[178:181], v[118:121]
	v_mfma_f32_16x16x32_bf16 v[114:117], v[154:157], v[178:181], v[114:117]
	v_mfma_f32_16x16x32_bf16 v[102:105], v[146:149], v[192:195], v[102:105]
	v_mfma_f32_16x16x32_bf16 v[98:101], v[154:157], v[192:195], v[98:101]
	v_mfma_f32_16x16x32_bf16 v[86:89], v[146:149], v[200:203], v[86:89]
	v_mfma_f32_16x16x32_bf16 v[82:85], v[154:157], v[200:203], v[82:85]
	v_mfma_f32_16x16x32_bf16 v[70:73], v[146:149], v[208:211], v[70:73]
	v_mfma_f32_16x16x32_bf16 v[66:69], v[154:157], v[208:211], v[66:69]
	v_mfma_f32_16x16x32_bf16 v[118:121], v[150:153], v[188:191], v[118:121]
	v_mfma_f32_16x16x32_bf16 v[114:117], v[174:177], v[188:191], v[114:117]
	v_mfma_f32_16x16x32_bf16 v[102:105], v[150:153], v[196:199], v[102:105]
	v_mfma_f32_16x16x32_bf16 v[98:101], v[174:177], v[196:199], v[98:101]
	v_mfma_f32_16x16x32_bf16 v[86:89], v[150:153], v[204:207], v[86:89]
	v_mfma_f32_16x16x32_bf16 v[82:85], v[174:177], v[204:207], v[82:85]
	v_mfma_f32_16x16x32_bf16 v[70:73], v[150:153], v[212:215], v[70:73]
	v_mfma_f32_16x16x32_bf16 v[66:69], v[174:177], v[212:215], v[66:69]
	s_barrier
; #define PG8_GAS __attribute__((address_space(1)))
; #define PG8_STAGE(bufoff, gbase, voff) do { _Pragma("unroll") for (int _i = 0; _i < 2; ++_i) \
;         __builtin_amdgcn_global_load_lds((const unsigned*)((const char*)(gbase) + (voff)[_i]), (PG8_LAS unsigned*)(lds + (bufoff) + ldsw + _i * 8192), 16, 0, 0); } while (0)
; #define PG8_LDA(dst, b, h) do { _Pragma("unroll") for (int m = 0; m < 4; ++m) _Pragma("unroll") for (int k = 0; k < 2; ++k) dst[m][k] = *(const PG8_LAS bf16x8*)(lds + PG8_SA(b, h) + aoff + m * 2048 + k * 1024); } while (0)
; #define PG8_WAIT_V(n) asm volatile("s_waitcnt vmcnt(" #n ")" ::: "memory")
; #define PG8_WAIT_L(n) asm volatile("s_waitcnt lgkmcnt(" #n ")" ::: "memory")
; #define PG8_BAR __builtin_amdgcn_s_barrier()
; #define PG8_SCHED __builtin_amdgcn_sched_barrier(0)
;     __device__ __forceinline__ void operator()(const f32x4 (&acc)[2][2][4][2], const Unit& un, int wr, int wc, int fr, int fq) const {
;         const int row0 = un.pm * BM + wr * 64 + fr, col0 = un.pn * BM + wc * 32 + 8 * fq;
;         f32x4 sc[2][2];
; #pragma unroll
;         for (int bj = 0; bj < 2; ++bj)
; #pragma unroll
;             for (int n = 0; n < 2; ++n) sc[bj][n] = *(const PG8_GAS f32x4*)(ps + col0 + bj * HALF + 4 * n);
; #pragma unroll
;         for (int ai = 0; ai < 2; ++ai) {
;             u32x4 gg[4][2];
; #pragma unroll
;             for (int m = 0; m < 4; ++m)
; #pragma unroll
;                 for (int bj = 0; bj < 2; ++bj) gg[m][bj] = *(const PG8_GAS u32x4*)(sp + (size_t)(row0 + ai * HALF + m * 16) * 4096 + col0 + bj * HALF);
; template <class Epi, class Sched, bool ALIGN_EPI = false, bool SP2 = false, bool F8 = false>
; __device__ __forceinline__ void gemm_phase(PG8_LAS unsigned char* lds, const Gemm g, const Sched& S, const Epi& E) {
;     ...
;             PG8_LDA(At, 1, 1); PG8_STAGE(PG8_SB(1, 0), b3, voffB); PG8_STAGE(PG8_SB(1, 1), b3 + hB, voffB); PG8_STAGE(PG8_SA(1, 0), a3, voffA);
;             PG8_WAIT_V(8); PG8_WAIT_L(0); PG8_BAR; PG8_MMA(1, 0, At, B0); PG8_MMA(1, 1, At, B1); PG8_BAR; PG8_SCHED;
	s_setprio 0
	s_add_i32 s42, s60, s19
	v_lshl_add_u64 v[216:217], v[216:217], 0, s[14:15]
	s_mov_b32 m0, s42
	ds_read_b128 v[178:181], v187 offset:49152
	ds_read_b128 v[188:191], v187 offset:50176
	ds_read_b128 v[192:195], v187 offset:51200
	ds_read_b128 v[196:199], v187 offset:52224
	ds_read_b128 v[200:203], v187 offset:53248
	ds_read_b128 v[204:207], v187 offset:54272
	ds_read_b128 v[208:211], v187 offset:55296
	ds_read_b128 v[212:215], v187 offset:56320
	global_load_lds_dwordx4 v[216:217], off
	s_add_i32 m0, s42, 0x2000
	s_add_u32 s40, s40, 0x20080
	v_lshl_add_u64 v[216:217], v[218:219], 0, s[14:15]
	s_addc_u32 s41, s41, 0
	s_add_i32 s42, s61, s19
	global_load_lds_dwordx4 v[216:217], off
	v_lshl_add_u64 v[216:217], s[40:41], 0, v[162:163]
	s_mov_b32 m0, s42
	s_nop 0
	global_load_lds_dwordx4 v[216:217], off
	v_lshl_add_u64 v[216:217], s[40:41], 0, v[158:159]
	s_add_i32 m0, s42, 0x2000
	s_nop 0
	global_load_lds_dwordx4 v[216:217], off
	v_lshl_add_u64 v[216:217], v[220:221], 0, s[14:15]
	s_mov_b32 m0, s49
	s_nop 0
	global_load_lds_dwordx4 v[216:217], off
	v_lshl_add_u64 v[216:217], v[222:223], 0, s[14:15]
	s_mov_b32 m0, s50
	s_nop 0
	global_load_lds_dwordx4 v[216:217], off
	s_setprio 1
	s_waitcnt vmcnt(8)
	s_waitcnt lgkmcnt(0)
	s_barrier
	v_mfma_f32_16x16x32_bf16 v[62:65], v[130:133], v[178:181], v[62:65]
	v_mfma_f32_16x16x32_bf16 v[58:61], v[138:141], v[178:181], v[58:61]
	v_mfma_f32_16x16x32_bf16 v[46:49], v[130:133], v[192:195], v[46:49]
	v_mfma_f32_16x16x32_bf16 v[42:45], v[138:141], v[192:195], v[42:45]
	v_mfma_f32_16x16x32_bf16 v[30:33], v[130:133], v[200:203], v[30:33]
	v_mfma_f32_16x16x32_bf16 v[26:29], v[138:141], v[200:203], v[26:29]
	v_mfma_f32_16x16x32_bf16 v[14:17], v[130:133], v[208:211], v[14:17]
	v_mfma_f32_16x16x32_bf16 v[10:13], v[138:141], v[208:211], v[10:13]
	v_mfma_f32_16x16x32_bf16 v[62:65], v[134:137], v[188:191], v[62:65]
	v_mfma_f32_16x16x32_bf16 v[58:61], v[142:145], v[188:191], v[58:61]
	v_mfma_f32_16x16x32_bf16 v[46:49], v[134:137], v[196:199], v[46:49]
	v_mfma_f32_16x16x32_bf16 v[42:45], v[142:145], v[196:199], v[42:45]
	v_mfma_f32_16x16x32_bf16 v[30:33], v[134:137], v[204:207], v[30:33]
	v_mfma_f32_16x16x32_bf16 v[26:29], v[142:145], v[204:207], v[26:29]
	v_mfma_f32_16x16x32_bf16 v[14:17], v[134:137], v[212:215], v[14:17]
	v_mfma_f32_16x16x32_bf16 v[10:13], v[142:145], v[212:215], v[10:13]
	v_mfma_f32_16x16x32_bf16 v[54:57], v[146:149], v[178:181], v[54:57]
	v_mfma_f32_16x16x32_bf16 v[50:53], v[154:157], v[178:181], v[50:53]
	v_mfma_f32_16x16x32_bf16 v[38:41], v[146:149], v[192:195], v[38:41]
	v_mfma_f32_16x16x32_bf16 v[34:37], v[154:157], v[192:195], v[34:37]
	v_mfma_f32_16x16x32_bf16 v[22:25], v[146:149], v[200:203], v[22:25]
	v_mfma_f32_16x16x32_bf16 v[18:21], v[154:157], v[200:203], v[18:21]
	v_mfma_f32_16x16x32_bf16 v[6:9], v[146:149], v[208:211], v[6:9]
	v_mfma_f32_16x16x32_bf16 v[2:5], v[154:157], v[208:211], v[2:5]
	v_mfma_f32_16x16x32_bf16 v[54:57], v[150:153], v[188:191], v[54:57]
	v_mfma_f32_16x16x32_bf16 v[50:53], v[174:177], v[188:191], v[50:53]
	v_mfma_f32_16x16x32_bf16 v[38:41], v[150:153], v[196:199], v[38:41]
	v_mfma_f32_16x16x32_bf16 v[34:37], v[174:177], v[196:199], v[34:37]
	v_mfma_f32_16x16x32_bf16 v[22:25], v[150:153], v[204:207], v[22:25]
	v_mfma_f32_16x16x32_bf16 v[18:21], v[174:177], v[204:207], v[18:21]
	v_mfma_f32_16x16x32_bf16 v[6:9], v[150:153], v[212:215], v[6:9]
	v_mfma_f32_16x16x32_bf16 v[2:5], v[174:177], v[212:215], v[2:5]
	s_barrier
	s_setprio 0
	s_add_i32 s59, s59, 2
	s_add_u32 s57, s57, 0x100
	s_addc_u32 s58, s58, 0
	s_add_u32 s38, s38, 0x100
	s_addc_u32 s39, s39, 0
	s_cmp_gt_u32 s59, 5
	s_cbranch_scc0 .LBB0_618
	v_lshl_or_b32 v146, s54, 8, v184
	v_ashrrev_i32_e32 v147, 31, v146
	v_lshl_add_u32 v148, s36, 8, v182
	v_ashrrev_i32_e32 v149, 31, v148
	v_lshlrev_b64 v[174:175], 1, v[146:147]
	v_lshlrev_b64 v[178:179], 13, v[148:149]
	v_lshl_add_u64 v[176:177], s[12:13], 0, v[174:175]
	v_lshl_add_u64 v[130:131], v[146:147], 2, s[10:11]
	v_lshl_add_u64 v[146:147], v[176:177], 0, v[178:179]
	global_load_dwordx4 v[142:145], v[130:131], off
	global_load_dwordx4 v[138:141], v[130:131], off offset:16
	global_load_dwordx4 v[134:137], v[130:131], off offset:512
	s_nop 0
	global_load_dwordx4 v[130:133], v[130:131], off offset:528
	s_nop 0
	global_load_dwordx4 v[188:191], v[146:147], off
	global_load_dwordx4 v[192:195], v[146:147], off offset:256
	v_or_b32_e32 v146, 16, v148
	v_ashrrev_i32_e32 v147, 31, v146
	v_lshlrev_b64 v[208:209], 13, v[146:147]
	v_lshl_add_u64 v[146:147], v[176:177], 0, v[208:209]
	global_load_dwordx4 v[196:199], v[146:147], off
	global_load_dwordx4 v[200:203], v[146:147], off offset:256
	v_or_b32_e32 v150, 32, v148
	v_or_b32_e32 v148, 48, v148
	v_ashrrev_i32_e32 v151, 31, v150
	v_ashrrev_i32_e32 v149, 31, v148
	v_lshlrev_b64 v[210:211], 13, v[150:151]
	v_lshlrev_b64 v[180:181], 13, v[148:149]
	v_lshl_add_u64 v[146:147], s[12:13], 0, v[178:179]
	v_lshl_add_u64 v[148:149], v[176:177], 0, v[210:211]
	v_lshl_add_u64 v[212:213], v[176:177], 0, v[180:181]
	v_lshl_add_u64 v[214:215], v[146:147], 0, v[174:175]
	global_load_dwordx4 v[204:207], v[148:149], off
	global_load_dwordx4 v[154:157], v[148:149], off offset:256
	global_load_dwordx4 v[150:153], v[212:213], off
	s_nop 0
	global_load_dwordx4 v[146:149], v[212:213], off offset:256
	s_and_b64 vcc, exec, s[8:9]
	s_mov_b32 s54, s26
	s_mov_b32 s36, s28
	s_mov_b64 s[38:39], s[34:35]
	s_mov_b64 s[40:41], s[30:31]
	s_waitcnt vmcnt(0)
; #define PG8_GAS __attribute__((address_space(1)))
; __device__ __forceinline__ unsigned cvt_pk_bf16(float lo, float hi) { const f32x2c v = {lo, hi}; return __builtin_bit_cast(unsigned, __builtin_convertvector(v, bf16x2c)); }
; __device__ __forceinline__ float bf_lo(unsigned w) { return __uint_as_float(w << 16); }
; __device__ __forceinline__ float bf_hi(unsigned w) { return __uint_as_float(w & 0xffff0000u); }
;     __device__ __forceinline__ void operator()(const f32x4 (&acc)[2][2][4][2], const Unit& un, int wr, int wc, int fr, int fq) const {
;     ...
;                 for (int bj = 0; bj < 2; ++bj) gg[m][bj] = *(const PG8_GAS u32x4*)(sp + (size_t)(row0 + ai * HALF + m * 16) * 4096 + col0 + bj * HALF);
;             asm volatile("" ::: "memory");
; #pragma unroll
;             for (int m = 0; m < 4; ++m)
; #pragma unroll
;                 for (int bj = 0; bj < 2; ++bj) { const u32x4 g = gg[m][bj];
;                     const f32x4 v0 = acc[ai][bj][m][0] * sc[bj][0], v1 = acc[ai][bj][m][1] * sc[bj][1];
;                     u32x4 w; w.x = cvt_pk_bf16(v0[0] * bf_lo(g.x), v0[1] * bf_hi(g.x)); w.y = cvt_pk_bf16(v0[2] * bf_lo(g.y), v0[3] * bf_hi(g.y));
;                     w.z = cvt_pk_bf16(v1[0] * bf_lo(g.z), v1[1] * bf_hi(g.z)); w.w = cvt_pk_bf16(v1[2] * bf_lo(g.w), v1[3] * bf_hi(g.w));
;                     *(PG8_GAS u32x4*)(sp + (size_t)(row0 + ai * HALF + m * 16) * 4096 + col0 + bj * HALF) = w; }
	v_pk_mul_f32 v[128:129], v[128:129], v[144:145]
	v_pk_mul_f32 v[126:127], v[126:127], v[142:143]
	v_pk_mul_f32 v[124:125], v[124:125], v[140:141]
	v_pk_mul_f32 v[122:123], v[122:123], v[138:139]
	v_pk_mul_f32 v[212:213], v[108:109], v[140:141]
	v_pk_mul_f32 v[216:217], v[106:107], v[138:139]
	v_lshlrev_b32_e32 v106, 16, v188
	v_and_b32_e32 v107, 0xffff0000, v188
	v_lshlrev_b32_e32 v108, 16, v189
	v_and_b32_e32 v109, 0xffff0000, v189
	v_lshlrev_b32_e32 v188, 16, v190
	v_and_b32_e32 v189, 0xffff0000, v190
	v_lshlrev_b32_e32 v190, 16, v191
	v_and_b32_e32 v191, 0xffff0000, v191
	v_pk_mul_f32 v[120:121], v[120:121], v[136:137]
	v_pk_mul_f32 v[118:119], v[118:119], v[134:135]
	v_pk_mul_f32 v[116:117], v[116:117], v[132:133]
	v_pk_mul_f32 v[114:115], v[114:115], v[130:131]
	v_lshlrev_b32_e32 v218, 16, v192
	v_and_b32_e32 v219, 0xffff0000, v192
	v_lshlrev_b32_e32 v192, 16, v193
	v_and_b32_e32 v193, 0xffff0000, v193
	v_lshlrev_b32_e32 v220, 16, v194
	v_and_b32_e32 v221, 0xffff0000, v194
	v_lshlrev_b32_e32 v194, 16, v195
	v_and_b32_e32 v195, 0xffff0000, v195
	v_pk_mul_f32 v[106:107], v[126:127], v[106:107]
	v_pk_mul_f32 v[108:109], v[128:129], v[108:109]
	v_pk_mul_f32 v[122:123], v[122:123], v[188:189]
	v_pk_mul_f32 v[124:125], v[124:125], v[190:191]
	v_pk_mul_f32 v[112:113], v[112:113], v[144:145]
	v_pk_mul_f32 v[110:111], v[110:111], v[142:143]
	v_lshlrev_b32_e32 v222, 16, v196
	v_and_b32_e32 v223, 0xffff0000, v196
	v_lshlrev_b32_e32 v196, 16, v197
	v_and_b32_e32 v197, 0xffff0000, v197
	v_pk_mul_f32 v[118:119], v[118:119], v[218:219]
	v_pk_mul_f32 v[120:121], v[120:121], v[192:193]
	v_pk_mul_f32 v[114:115], v[114:115], v[220:221]
	v_pk_mul_f32 v[116:117], v[116:117], v[194:195]
	v_cvt_pk_bf16_f32 v106, v106, v107
	v_cvt_pk_bf16_f32 v107, v108, v109
	v_cvt_pk_bf16_f32 v108, v122, v123
	v_cvt_pk_bf16_f32 v109, v124, v125
	v_pk_mul_f32 v[126:127], v[110:111], v[222:223]
	v_pk_mul_f32 v[128:129], v[112:113], v[196:197]
	v_cvt_pk_bf16_f32 v110, v118, v119
	v_cvt_pk_bf16_f32 v111, v120, v121
	v_cvt_pk_bf16_f32 v112, v114, v115
	v_cvt_pk_bf16_f32 v113, v116, v117
	global_store_dwordx4 v[214:215], v[106:109], off
	global_store_dwordx4 v[214:215], v[110:113], off offset:256
	v_pk_mul_f32 v[102:103], v[102:103], v[134:135]
	v_pk_mul_f32 v[108:109], v[100:101], v[132:133]
	v_pk_mul_f32 v[100:101], v[98:99], v[130:131]
	v_lshlrev_b32_e32 v98, 16, v200
	v_and_b32_e32 v99, 0xffff0000, v200
	v_lshlrev_b32_e32 v106, 16, v198
	v_and_b32_e32 v107, 0xffff0000, v198
	v_pk_mul_f32 v[104:105], v[104:105], v[136:137]
	v_pk_mul_f32 v[98:99], v[102:103], v[98:99]
	v_lshlrev_b32_e32 v102, 16, v201
	v_and_b32_e32 v103, 0xffff0000, v201
	v_pk_mul_f32 v[106:107], v[216:217], v[106:107]
	v_pk_mul_f32 v[102:103], v[104:105], v[102:103]
	v_cvt_pk_bf16_f32 v116, v106, v107
	v_lshlrev_b32_e32 v106, 16, v199
	v_and_b32_e32 v107, 0xffff0000, v199
	v_cvt_pk_bf16_f32 v98, v98, v99
	v_cvt_pk_bf16_f32 v99, v102, v103
	v_lshlrev_b32_e32 v102, 16, v202
	v_and_b32_e32 v103, 0xffff0000, v202
	v_pk_mul_f32 v[106:107], v[212:213], v[106:107]
	v_pk_mul_f32 v[100:101], v[100:101], v[102:103]
	v_lshlrev_b32_e32 v102, 16, v203
	v_and_b32_e32 v103, 0xffff0000, v203
	v_cvt_pk_bf16_f32 v117, v106, v107
	v_lshl_add_u64 v[106:107], s[12:13], 0, v[208:209]
	v_pk_mul_f32 v[102:103], v[108:109], v[102:103]
	v_lshl_add_u64 v[106:107], v[106:107], 0, v[174:175]
	v_cvt_pk_bf16_f32 v100, v100, v101
	v_cvt_pk_bf16_f32 v101, v102, v103
	global_store_dwordx4 v[106:107], v[98:101], off offset:256
	v_pk_mul_f32 v[94:95], v[94:95], v[142:143]
	v_pk_mul_f32 v[96:97], v[96:97], v[144:145]
	v_pk_mul_f32 v[98:99], v[92:93], v[140:141]
	v_pk_mul_f32 v[92:93], v[90:91], v[138:139]
	v_lshlrev_b32_e32 v90, 16, v204
	v_and_b32_e32 v91, 0xffff0000, v204
	v_pk_mul_f32 v[90:91], v[94:95], v[90:91]
	v_lshlrev_b32_e32 v94, 16, v205
	v_and_b32_e32 v95, 0xffff0000, v205
	v_pk_mul_f32 v[94:95], v[96:97], v[94:95]
	v_cvt_pk_bf16_f32 v90, v90, v91
	v_cvt_pk_bf16_f32 v91, v94, v95
	v_lshlrev_b32_e32 v94, 16, v206
	v_and_b32_e32 v95, 0xffff0000, v206
	v_pk_mul_f32 v[92:93], v[92:93], v[94:95]
	v_lshlrev_b32_e32 v94, 16, v207
	v_and_b32_e32 v95, 0xffff0000, v207
	v_pk_mul_f32 v[94:95], v[98:99], v[94:95]
	v_cvt_pk_bf16_f32 v92, v92, v93
	v_cvt_pk_bf16_f32 v93, v94, v95
	v_lshl_add_u64 v[94:95], s[12:13], 0, v[210:211]
	v_lshl_add_u64 v[102:103], v[178:179], 0, s[16:17]
	v_lshl_add_u64 v[94:95], v[94:95], 0, v[174:175]
	v_pk_mul_f32 v[86:87], v[86:87], v[134:135]
	v_lshl_add_u64 v[96:97], v[176:177], 0, v[102:103]
	v_lshlrev_b32_e32 v98, 16, v154
	v_and_b32_e32 v99, 0xffff0000, v154
	global_store_dwordx4 v[94:95], v[90:93], off
	v_pk_mul_f32 v[88:89], v[88:89], v[136:137]
	v_pk_mul_f32 v[86:87], v[86:87], v[98:99]
	v_pk_mul_f32 v[90:91], v[84:85], v[132:133]
	v_pk_mul_f32 v[92:93], v[82:83], v[130:131]
	global_load_dwordx4 v[82:85], v[96:97], off
	v_lshlrev_b32_e32 v98, 16, v155
	v_and_b32_e32 v99, 0xffff0000, v155
	v_pk_mul_f32 v[88:89], v[88:89], v[98:99]
	v_cvt_pk_bf16_f32 v86, v86, v87
	v_cvt_pk_bf16_f32 v87, v88, v89
	v_lshlrev_b32_e32 v88, 16, v156
	v_and_b32_e32 v89, 0xffff0000, v156
	v_pk_mul_f32 v[88:89], v[92:93], v[88:89]
	v_lshlrev_b32_e32 v92, 16, v157
	v_and_b32_e32 v93, 0xffff0000, v157
	v_pk_mul_f32 v[90:91], v[90:91], v[92:93]
	v_cvt_pk_bf16_f32 v88, v88, v89
	v_cvt_pk_bf16_f32 v89, v90, v91
	global_store_dwordx4 v[94:95], v[86:89], off offset:256
	v_pk_mul_f32 v[80:81], v[80:81], v[144:145]
	v_pk_mul_f32 v[90:91], v[76:77], v[140:141]
	v_pk_mul_f32 v[86:87], v[78:79], v[142:143]
	v_lshlrev_b32_e32 v88, 16, v150
	v_and_b32_e32 v89, 0xffff0000, v150
	v_pk_mul_f32 v[86:87], v[86:87], v[88:89]
	v_lshlrev_b32_e32 v88, 16, v151
; #define PG8_GAS __attribute__((address_space(1)))
; __device__ __forceinline__ unsigned cvt_pk_bf16(float lo, float hi) { const f32x2c v = {lo, hi}; return __builtin_bit_cast(unsigned, __builtin_convertvector(v, bf16x2c)); }
; __device__ __forceinline__ float bf_lo(unsigned w) { return __uint_as_float(w << 16); }
; __device__ __forceinline__ float bf_hi(unsigned w) { return __uint_as_float(w & 0xffff0000u); }
;     __device__ __forceinline__ void operator()(const f32x4 (&acc)[2][2][4][2], const Unit& un, int wr, int wc, int fr, int fq) const {
;     ...
;                 for (int bj = 0; bj < 2; ++bj) gg[m][bj] = *(const PG8_GAS u32x4*)(sp + (size_t)(row0 + ai * HALF + m * 16) * 4096 + col0 + bj * HALF);
;             asm volatile("" ::: "memory");
; #pragma unroll
;             for (int m = 0; m < 4; ++m)
; #pragma unroll
;                 for (int bj = 0; bj < 2; ++bj) { const u32x4 g = gg[m][bj];
;                     const f32x4 v0 = acc[ai][bj][m][0] * sc[bj][0], v1 = acc[ai][bj][m][1] * sc[bj][1];
;                     u32x4 w; w.x = cvt_pk_bf16(v0[0] * bf_lo(g.x), v0[1] * bf_hi(g.x)); w.y = cvt_pk_bf16(v0[2] * bf_lo(g.y), v0[3] * bf_hi(g.y));
;                     w.z = cvt_pk_bf16(v1[0] * bf_lo(g.z), v1[1] * bf_hi(g.z)); w.w = cvt_pk_bf16(v1[2] * bf_lo(g.w), v1[3] * bf_hi(g.w));
;                     *(PG8_GAS u32x4*)(sp + (size_t)(row0 + ai * HALF + m * 16) * 4096 + col0 + bj * HALF) = w; }
	v_and_b32_e32 v89, 0xffff0000, v151
	global_load_dwordx4 v[76:79], v[96:97], off offset:256
	v_pk_mul_f32 v[80:81], v[80:81], v[88:89]
	v_pk_mul_f32 v[74:75], v[74:75], v[138:139]
	v_cvt_pk_bf16_f32 v86, v86, v87
	v_cvt_pk_bf16_f32 v87, v80, v81
	v_lshlrev_b32_e32 v80, 16, v152
	v_and_b32_e32 v81, 0xffff0000, v152
	v_pk_mul_f32 v[74:75], v[74:75], v[80:81]
	v_lshl_add_u64 v[80:81], v[178:179], 0, s[20:21]
	v_cvt_pk_bf16_f32 v88, v74, v75
	v_lshlrev_b32_e32 v74, 16, v153
	v_and_b32_e32 v75, 0xffff0000, v153
	v_pk_mul_f32 v[74:75], v[90:91], v[74:75]
	v_lshl_add_u64 v[90:91], v[176:177], 0, v[80:81]
	v_cvt_pk_bf16_f32 v89, v74, v75
	v_lshl_add_u64 v[74:75], s[12:13], 0, v[180:181]
	v_lshl_add_u64 v[74:75], v[74:75], 0, v[174:175]
	global_store_dwordx4 v[74:75], v[86:89], off
	global_load_dwordx4 v[86:89], v[90:91], off
	v_pk_mul_f32 v[70:71], v[70:71], v[134:135]
	v_pk_mul_f32 v[92:93], v[68:69], v[132:133]
	v_pk_mul_f32 v[68:69], v[66:67], v[130:131]
	v_lshlrev_b32_e32 v66, 16, v146
	v_and_b32_e32 v67, 0xffff0000, v146
	v_pk_mul_f32 v[72:73], v[72:73], v[136:137]
	v_pk_mul_f32 v[66:67], v[70:71], v[66:67]
	v_lshlrev_b32_e32 v70, 16, v147
	v_and_b32_e32 v71, 0xffff0000, v147
	v_pk_mul_f32 v[70:71], v[72:73], v[70:71]
	v_cvt_pk_bf16_f32 v66, v66, v67
	v_cvt_pk_bf16_f32 v67, v70, v71
	v_lshlrev_b32_e32 v70, 16, v148
	v_and_b32_e32 v71, 0xffff0000, v148
	v_pk_mul_f32 v[68:69], v[68:69], v[70:71]
	v_lshlrev_b32_e32 v70, 16, v149
	v_and_b32_e32 v71, 0xffff0000, v149
	v_pk_mul_f32 v[70:71], v[92:93], v[70:71]
	global_load_dwordx4 v[90:93], v[90:91], off offset:256
	v_cvt_pk_bf16_f32 v114, v126, v127
	v_cvt_pk_bf16_f32 v115, v128, v129
	v_cvt_pk_bf16_f32 v68, v68, v69
	v_cvt_pk_bf16_f32 v69, v70, v71
	v_lshl_add_u64 v[104:105], v[178:179], 0, s[22:23]
	global_store_dwordx4 v[106:107], v[114:117], off
	global_store_dwordx4 v[74:75], v[66:69], off offset:256
	v_lshl_add_u64 v[74:75], v[178:179], 0, s[24:25]
	v_pk_mul_f32 v[62:63], v[62:63], v[142:143]
	v_lshl_add_u64 v[66:67], v[176:177], 0, v[104:105]
	global_load_dwordx4 v[94:97], v[66:67], off
	global_load_dwordx4 v[98:101], v[66:67], off offset:256
	v_lshl_add_u64 v[66:67], v[176:177], 0, v[74:75]
	global_load_dwordx4 v[70:73], v[66:67], off
	s_nop 0
	global_load_dwordx4 v[66:69], v[66:67], off offset:256
	v_pk_mul_f32 v[106:107], v[60:61], v[140:141]
	v_pk_mul_f32 v[60:61], v[58:59], v[138:139]
	v_pk_mul_f32 v[64:65], v[64:65], v[144:145]
	v_pk_mul_f32 v[54:55], v[54:55], v[134:135]
	v_pk_mul_f32 v[56:57], v[56:57], v[136:137]
	s_waitcnt vmcnt(11)
	v_lshlrev_b32_e32 v58, 16, v82
	v_and_b32_e32 v59, 0xffff0000, v82
	v_pk_mul_f32 v[58:59], v[62:63], v[58:59]
	v_lshlrev_b32_e32 v62, 16, v83
	v_and_b32_e32 v63, 0xffff0000, v83
	v_pk_mul_f32 v[62:63], v[64:65], v[62:63]
	v_cvt_pk_bf16_f32 v58, v58, v59
	v_cvt_pk_bf16_f32 v59, v62, v63
	v_lshlrev_b32_e32 v62, 16, v84
	v_and_b32_e32 v63, 0xffff0000, v84
	v_pk_mul_f32 v[60:61], v[60:61], v[62:63]
	v_lshlrev_b32_e32 v62, 16, v85
	v_and_b32_e32 v63, 0xffff0000, v85
	v_pk_mul_f32 v[62:63], v[106:107], v[62:63]
	v_cvt_pk_bf16_f32 v60, v60, v61
	v_cvt_pk_bf16_f32 v61, v62, v63
	v_lshl_add_u64 v[62:63], s[12:13], 0, v[102:103]
	v_lshl_add_u64 v[62:63], v[62:63], 0, v[174:175]
	global_store_dwordx4 v[62:63], v[58:61], off
	v_pk_mul_f32 v[46:47], v[46:47], v[142:143]
	v_pk_mul_f32 v[48:49], v[48:49], v[144:145]
	v_pk_mul_f32 v[58:59], v[52:53], v[132:133]
	v_pk_mul_f32 v[52:53], v[50:51], v[130:131]
	s_waitcnt vmcnt(10)
	v_lshlrev_b32_e32 v50, 16, v76
	v_and_b32_e32 v51, 0xffff0000, v76
	v_pk_mul_f32 v[50:51], v[54:55], v[50:51]
	v_lshlrev_b32_e32 v54, 16, v77
	v_and_b32_e32 v55, 0xffff0000, v77
	v_pk_mul_f32 v[54:55], v[56:57], v[54:55]
	v_cvt_pk_bf16_f32 v50, v50, v51
	v_cvt_pk_bf16_f32 v51, v54, v55
	v_lshlrev_b32_e32 v54, 16, v78
	v_and_b32_e32 v55, 0xffff0000, v78
	v_pk_mul_f32 v[52:53], v[52:53], v[54:55]
	v_lshlrev_b32_e32 v54, 16, v79
	v_and_b32_e32 v55, 0xffff0000, v79
	v_pk_mul_f32 v[54:55], v[58:59], v[54:55]
	v_cvt_pk_bf16_f32 v52, v52, v53
	v_cvt_pk_bf16_f32 v53, v54, v55
	global_store_dwordx4 v[62:63], v[50:53], off offset:256
	v_pk_mul_f32 v[38:39], v[38:39], v[134:135]
	v_pk_mul_f32 v[40:41], v[40:41], v[136:137]
	v_pk_mul_f32 v[50:51], v[44:45], v[140:141]
	v_pk_mul_f32 v[44:45], v[42:43], v[138:139]
	s_waitcnt vmcnt(9)
; #define PG8_GAS __attribute__((address_space(1)))
; __device__ __forceinline__ unsigned cvt_pk_bf16(float lo, float hi) { const f32x2c v = {lo, hi}; return __builtin_bit_cast(unsigned, __builtin_convertvector(v, bf16x2c)); }
; __device__ __forceinline__ float bf_lo(unsigned w) { return __uint_as_float(w << 16); }
; __device__ __forceinline__ float bf_hi(unsigned w) { return __uint_as_float(w & 0xffff0000u); }
; #define PG8_WAIT_V(n) asm volatile("s_waitcnt vmcnt(" #n ")" ::: "memory")
; #define PG8_BAR __builtin_amdgcn_s_barrier()
;     __device__ __forceinline__ void operator()(const f32x4 (&acc)[2][2][4][2], const Unit& un, int wr, int wc, int fr, int fq) const {
;     ...
;             for (int m = 0; m < 4; ++m)
; #pragma unroll
;                 for (int bj = 0; bj < 2; ++bj) { const u32x4 g = gg[m][bj];
;                     const f32x4 v0 = acc[ai][bj][m][0] * sc[bj][0], v1 = acc[ai][bj][m][1] * sc[bj][1];
;                     u32x4 w; w.x = cvt_pk_bf16(v0[0] * bf_lo(g.x), v0[1] * bf_hi(g.x)); w.y = cvt_pk_bf16(v0[2] * bf_lo(g.y), v0[3] * bf_hi(g.y));
;                     w.z = cvt_pk_bf16(v1[0] * bf_lo(g.z), v1[1] * bf_hi(g.z)); w.w = cvt_pk_bf16(v1[2] * bf_lo(g.w), v1[3] * bf_hi(g.w));
;                     *(PG8_GAS u32x4*)(sp + (size_t)(row0 + ai * HALF + m * 16) * 4096 + col0 + bj * HALF) = w; }
; template <class Epi, class Sched, bool ALIGN_EPI = false, bool SP2 = false, bool F8 = false>
; __device__ __forceinline__ void gemm_phase(PG8_LAS unsigned char* lds, const Gemm g, const Sched& S, const Epi& E) {
;     ...
;         cur = nxt; cA = nA; cB = nB; ++ui;
;         if constexpr (ALIGN_EPI) { if (wr == 1) PG8_BAR; }
;     }
;     PG8_WAIT_V(0);
;     if constexpr (!ALIGN_EPI) { if (wr == 0) PG8_BAR; }
;     PG8_BAR;
	v_lshlrev_b32_e32 v42, 16, v86
	v_and_b32_e32 v43, 0xffff0000, v86
	v_pk_mul_f32 v[42:43], v[46:47], v[42:43]
	v_lshlrev_b32_e32 v46, 16, v87
	v_and_b32_e32 v47, 0xffff0000, v87
	v_pk_mul_f32 v[46:47], v[48:49], v[46:47]
	v_cvt_pk_bf16_f32 v42, v42, v43
	v_cvt_pk_bf16_f32 v43, v46, v47
	v_lshlrev_b32_e32 v46, 16, v88
	v_and_b32_e32 v47, 0xffff0000, v88
	v_pk_mul_f32 v[44:45], v[44:45], v[46:47]
	v_lshlrev_b32_e32 v46, 16, v89
	v_and_b32_e32 v47, 0xffff0000, v89
	v_pk_mul_f32 v[46:47], v[50:51], v[46:47]
	v_cvt_pk_bf16_f32 v44, v44, v45
	v_cvt_pk_bf16_f32 v45, v46, v47
	v_lshl_add_u64 v[46:47], s[12:13], 0, v[80:81]
	v_lshl_add_u64 v[46:47], v[46:47], 0, v[174:175]
	global_store_dwordx4 v[46:47], v[42:45], off
	v_pk_mul_f32 v[30:31], v[30:31], v[142:143]
	v_pk_mul_f32 v[32:33], v[32:33], v[144:145]
	v_pk_mul_f32 v[42:43], v[36:37], v[132:133]
	v_pk_mul_f32 v[36:37], v[34:35], v[130:131]
	s_waitcnt vmcnt(9)
	v_lshlrev_b32_e32 v34, 16, v90
	v_and_b32_e32 v35, 0xffff0000, v90
	v_pk_mul_f32 v[34:35], v[38:39], v[34:35]
	v_lshlrev_b32_e32 v38, 16, v91
	v_and_b32_e32 v39, 0xffff0000, v91
	v_pk_mul_f32 v[38:39], v[40:41], v[38:39]
	v_cvt_pk_bf16_f32 v34, v34, v35
	v_cvt_pk_bf16_f32 v35, v38, v39
	v_lshlrev_b32_e32 v38, 16, v92
	v_and_b32_e32 v39, 0xffff0000, v92
	v_pk_mul_f32 v[36:37], v[36:37], v[38:39]
	v_lshlrev_b32_e32 v38, 16, v93
	v_and_b32_e32 v39, 0xffff0000, v93
	v_pk_mul_f32 v[38:39], v[42:43], v[38:39]
	v_cvt_pk_bf16_f32 v36, v36, v37
	v_cvt_pk_bf16_f32 v37, v38, v39
	global_store_dwordx4 v[46:47], v[34:37], off offset:256
	v_pk_mul_f32 v[22:23], v[22:23], v[134:135]
	v_pk_mul_f32 v[24:25], v[24:25], v[136:137]
	v_pk_mul_f32 v[34:35], v[28:29], v[140:141]
	v_pk_mul_f32 v[28:29], v[26:27], v[138:139]
	s_waitcnt vmcnt(7)
	v_lshlrev_b32_e32 v26, 16, v94
	v_and_b32_e32 v27, 0xffff0000, v94
	v_pk_mul_f32 v[26:27], v[30:31], v[26:27]
	v_lshlrev_b32_e32 v30, 16, v95
	v_and_b32_e32 v31, 0xffff0000, v95
	v_pk_mul_f32 v[30:31], v[32:33], v[30:31]
	v_cvt_pk_bf16_f32 v26, v26, v27
	v_cvt_pk_bf16_f32 v27, v30, v31
	v_lshlrev_b32_e32 v30, 16, v96
	v_and_b32_e32 v31, 0xffff0000, v96
	v_pk_mul_f32 v[28:29], v[28:29], v[30:31]
	v_lshlrev_b32_e32 v30, 16, v97
	v_and_b32_e32 v31, 0xffff0000, v97
	v_pk_mul_f32 v[30:31], v[34:35], v[30:31]
	v_cvt_pk_bf16_f32 v28, v28, v29
	v_cvt_pk_bf16_f32 v29, v30, v31
	v_lshl_add_u64 v[30:31], s[12:13], 0, v[104:105]
	v_lshl_add_u64 v[30:31], v[30:31], 0, v[174:175]
	global_store_dwordx4 v[30:31], v[26:29], off
	v_pk_mul_f32 v[14:15], v[14:15], v[142:143]
	v_pk_mul_f32 v[16:17], v[16:17], v[144:145]
	v_pk_mul_f32 v[26:27], v[20:21], v[132:133]
	v_pk_mul_f32 v[20:21], v[18:19], v[130:131]
	s_waitcnt vmcnt(7)
	v_lshlrev_b32_e32 v18, 16, v98
	v_and_b32_e32 v19, 0xffff0000, v98
	v_pk_mul_f32 v[18:19], v[22:23], v[18:19]
	v_lshlrev_b32_e32 v22, 16, v99
	v_and_b32_e32 v23, 0xffff0000, v99
	v_pk_mul_f32 v[22:23], v[24:25], v[22:23]
	v_cvt_pk_bf16_f32 v18, v18, v19
	v_cvt_pk_bf16_f32 v19, v22, v23
	v_lshlrev_b32_e32 v22, 16, v100
	v_and_b32_e32 v23, 0xffff0000, v100
	v_pk_mul_f32 v[20:21], v[20:21], v[22:23]
	v_lshlrev_b32_e32 v22, 16, v101
	v_and_b32_e32 v23, 0xffff0000, v101
	v_pk_mul_f32 v[22:23], v[26:27], v[22:23]
	v_cvt_pk_bf16_f32 v20, v20, v21
	v_cvt_pk_bf16_f32 v21, v22, v23
	global_store_dwordx4 v[30:31], v[18:21], off offset:256
	v_pk_mul_f32 v[6:7], v[6:7], v[134:135]
	v_pk_mul_f32 v[8:9], v[8:9], v[136:137]
	v_pk_mul_f32 v[18:19], v[12:13], v[140:141]
	v_pk_mul_f32 v[12:13], v[10:11], v[138:139]
	s_waitcnt vmcnt(7)
	v_lshlrev_b32_e32 v10, 16, v70
	v_and_b32_e32 v11, 0xffff0000, v70
	v_pk_mul_f32 v[10:11], v[14:15], v[10:11]
	v_lshlrev_b32_e32 v14, 16, v71
	v_and_b32_e32 v15, 0xffff0000, v71
	v_pk_mul_f32 v[14:15], v[16:17], v[14:15]
	v_cvt_pk_bf16_f32 v10, v10, v11
	v_cvt_pk_bf16_f32 v11, v14, v15
	v_lshlrev_b32_e32 v14, 16, v72
	v_and_b32_e32 v15, 0xffff0000, v72
	v_pk_mul_f32 v[12:13], v[12:13], v[14:15]
	v_lshlrev_b32_e32 v14, 16, v73
	v_and_b32_e32 v15, 0xffff0000, v73
	v_pk_mul_f32 v[14:15], v[18:19], v[14:15]
	v_cvt_pk_bf16_f32 v12, v12, v13
	v_cvt_pk_bf16_f32 v13, v14, v15
	v_lshl_add_u64 v[14:15], s[12:13], 0, v[74:75]
	v_lshl_add_u64 v[14:15], v[14:15], 0, v[174:175]
	global_store_dwordx4 v[14:15], v[10:13], off
	s_nop 1
	v_pk_mul_f32 v[10:11], v[4:5], v[132:133]
	v_pk_mul_f32 v[4:5], v[2:3], v[130:131]
	s_waitcnt vmcnt(7)
	v_lshlrev_b32_e32 v2, 16, v66
	v_and_b32_e32 v3, 0xffff0000, v66
	v_pk_mul_f32 v[2:3], v[6:7], v[2:3]
	v_lshlrev_b32_e32 v6, 16, v67
	v_and_b32_e32 v7, 0xffff0000, v67
	v_pk_mul_f32 v[6:7], v[8:9], v[6:7]
	v_cvt_pk_bf16_f32 v2, v2, v3
	v_cvt_pk_bf16_f32 v3, v6, v7
	v_lshlrev_b32_e32 v6, 16, v68
	v_and_b32_e32 v7, 0xffff0000, v68
	v_pk_mul_f32 v[4:5], v[4:5], v[6:7]
	v_lshlrev_b32_e32 v6, 16, v69
	v_and_b32_e32 v7, 0xffff0000, v69
	v_pk_mul_f32 v[6:7], v[10:11], v[6:7]
	v_cvt_pk_bf16_f32 v4, v4, v5
	v_cvt_pk_bf16_f32 v5, v6, v7
	global_store_dwordx4 v[14:15], v[2:5], off offset:256
	s_cbranch_vccz .LBB0_615
	s_waitcnt vmcnt(0)
	s_cmpk_gt_u32 s4, 0xff
	s_cbranch_scc1 .LBB0_622
	s_barrier

; #define PG8_STAGE(bufoff, gbase, voff) do { _Pragma("unroll") for (int _i = 0; _i < 2; ++_i) \
;         __builtin_amdgcn_global_load_lds((const unsigned*)((const char*)(gbase) + (voff)[_i]), (PG8_LAS unsigned*)(lds + (bufoff) + ldsw + _i * 8192), 16, 0, 0); } while (0)
; #define PG8_LDA(dst, b, h) do { _Pragma("unroll") for (int m = 0; m < 4; ++m) _Pragma("unroll") for (int k = 0; k < 2; ++k) dst[m][k] = *(const PG8_LAS bf16x8*)(lds + PG8_SA(b, h) + aoff + m * 2048 + k * 1024); } while (0)
; #define PG8_LDB(dst, b, h) do { _Pragma("unroll") for (int n = 0; n < 2; ++n) _Pragma("unroll") for (int k = 0; k < 2; ++k) dst[n][k] = *(const PG8_LAS bf16x8*)(lds + PG8_SB(b, h) + boff + n * 2048 + k * 1024); } while (0)
; #define PG8_WAIT_V(n) asm volatile("s_waitcnt vmcnt(" #n ")" ::: "memory")
; #define PG8_WAIT_L(n) asm volatile("s_waitcnt lgkmcnt(" #n ")" ::: "memory")
; #define PG8_BAR __builtin_amdgcn_s_barrier()
; #define PG8_SCHED __builtin_amdgcn_sched_barrier(0)
; template <class Epi, class Sched, bool ALIGN_EPI = false, bool SP2 = false, bool F8 = false>
; __device__ __forceinline__ void gemm_phase(PG8_LAS unsigned char* lds, const Gemm g, const Sched& S, const Epi& E) {
;     ...
;             PG8_LDB(B0, 0, 0); PG8_LDB(B1, 0, 1); PG8_SCHED; PG8_LDA(At, 0, 0); PG8_STAGE(PG8_SA(1, 1), a1 + hA, voffA);
;             PG8_WAIT_V(8); PG8_WAIT_L(0); PG8_BAR; PG8_MMA(0, 0, At, B0); PG8_MMA(0, 1, At, B1); PG8_BAR; PG8_SCHED;
;             PG8_LDA(At, 0, 1); PG8_STAGE(PG8_SB(0, 0), b2, voffB); PG8_STAGE(PG8_SB(0, 1), b2 + hB, voffB); PG8_STAGE(PG8_SA(0, 0), a2, voffA);
;             PG8_WAIT_V(8); PG8_WAIT_L(0); PG8_BAR; PG8_MMA(1, 0, At, B0); PG8_MMA(1, 1, At, B1); PG8_BAR; PG8_SCHED;
.LBB0_630:
	ds_read_b128 v[26:29], v190
	ds_read_b128 v[30:33], v190 offset:1024
	ds_read_b128 v[18:21], v190 offset:2048
	ds_read_b128 v[22:25], v190 offset:3072
	ds_read_b128 v[10:13], v191
	ds_read_b128 v[14:17], v191 offset:1024
	ds_read_b128 v[2:5], v191 offset:2048
	ds_read_b128 v[6:9], v191 offset:3072
	s_add_u32 s30, s28, 0xfffc0080
	s_addc_u32 s31, s29, -1
	s_cmp_eq_u32 s51, 12
	s_cselect_b32 s35, s21, s31
	s_cselect_b32 s34, s47, s30
	s_cselect_b32 s31, s17, s50
	s_cselect_b32 s30, s48, s49
	v_lshl_add_u64 v[218:219], s[28:29], 0, v[172:173]
	s_add_i32 m0, s27, 0xc000
	ds_read_b128 v[178:181], v192
	ds_read_b128 v[182:185], v192 offset:1024
	ds_read_b128 v[194:197], v192 offset:2048
	ds_read_b128 v[198:201], v192 offset:3072
	ds_read_b128 v[202:205], v192 offset:4096
	ds_read_b128 v[206:209], v192 offset:5120
	ds_read_b128 v[210:213], v192 offset:6144
	ds_read_b128 v[214:217], v192 offset:7168
	global_load_lds_dwordx4 v[218:219], off
	v_lshl_add_u64 v[218:219], s[28:29], 0, v[170:171]
	s_add_i32 m0, s27, 0xe000
	s_nop 0
	global_load_lds_dwordx4 v[218:219], off
	s_setprio 1
	s_waitcnt vmcnt(8)
	s_waitcnt lgkmcnt(0)
	s_barrier
	v_mfma_scale_f32_16x16x128_f8f6f4 v[158:161], v[26:33], v[178:185], v[158:161], v186, v186 op_sel_hi:[0,0,0]
	v_mfma_scale_f32_16x16x128_f8f6f4 v[154:157], v[18:25], v[178:185], v[154:157], v186, v186 op_sel_hi:[0,0,0]
	v_mfma_scale_f32_16x16x128_f8f6f4 v[146:149], v[26:33], v[194:201], v[146:149], v186, v186 op_sel_hi:[0,0,0]
	v_mfma_scale_f32_16x16x128_f8f6f4 v[138:141], v[18:25], v[194:201], v[138:141], v186, v186 op_sel_hi:[0,0,0]
	v_mfma_scale_f32_16x16x128_f8f6f4 v[130:133], v[26:33], v[202:209], v[130:133], v186, v186 op_sel_hi:[0,0,0]
	v_mfma_scale_f32_16x16x128_f8f6f4 v[122:125], v[18:25], v[202:209], v[122:125], v186, v186 op_sel_hi:[0,0,0]
	v_mfma_scale_f32_16x16x128_f8f6f4 v[114:117], v[26:33], v[210:217], v[114:117], v186, v186 op_sel_hi:[0,0,0]
	v_mfma_scale_f32_16x16x128_f8f6f4 v[106:109], v[18:25], v[210:217], v[106:109], v186, v186 op_sel_hi:[0,0,0]
	v_mfma_scale_f32_16x16x128_f8f6f4 v[150:153], v[10:17], v[178:185], v[150:153], v186, v186 op_sel_hi:[0,0,0]
	v_mfma_scale_f32_16x16x128_f8f6f4 v[142:145], v[2:9], v[178:185], v[142:145], v186, v186 op_sel_hi:[0,0,0]
	v_mfma_scale_f32_16x16x128_f8f6f4 v[134:137], v[10:17], v[194:201], v[134:137], v186, v186 op_sel_hi:[0,0,0]
	v_mfma_scale_f32_16x16x128_f8f6f4 v[126:129], v[2:9], v[194:201], v[126:129], v186, v186 op_sel_hi:[0,0,0]
	v_mfma_scale_f32_16x16x128_f8f6f4 v[118:121], v[10:17], v[202:209], v[118:121], v186, v186 op_sel_hi:[0,0,0]
	v_mfma_scale_f32_16x16x128_f8f6f4 v[110:113], v[2:9], v[202:209], v[110:113], v186, v186 op_sel_hi:[0,0,0]
	v_mfma_scale_f32_16x16x128_f8f6f4 v[102:105], v[10:17], v[210:217], v[102:105], v186, v186 op_sel_hi:[0,0,0]
	v_mfma_scale_f32_16x16x128_f8f6f4 v[98:101], v[2:9], v[210:217], v[98:101], v186, v186 op_sel_hi:[0,0,0]
	s_barrier
	s_setprio 0
	s_add_i32 s52, s44, s19
	v_lshl_add_u64 v[178:179], s[30:31], 0, v[166:167]
	s_mov_b32 m0, s52
	ds_read_b128 v[194:197], v192 offset:16384
	ds_read_b128 v[198:201], v192 offset:17408
	ds_read_b128 v[202:205], v192 offset:18432
	ds_read_b128 v[206:209], v192 offset:19456
	ds_read_b128 v[210:213], v192 offset:20480
	ds_read_b128 v[214:217], v192 offset:21504
	ds_read_b128 v[218:221], v192 offset:22528
	ds_read_b128 v[222:225], v192 offset:23552
	global_load_lds_dwordx4 v[178:179], off
	s_add_i32 m0, s52, 0x2000
	s_add_u32 s52, s30, 0x40000
	v_lshl_add_u64 v[180:181], s[30:31], 0, v[162:163]
	s_addc_u32 s53, s31, 0
	s_add_i32 s54, s45, s19
	global_load_lds_dwordx4 v[180:181], off
	v_lshl_add_u64 v[182:183], s[52:53], 0, v[166:167]
	s_mov_b32 m0, s54
	v_lshl_add_u64 v[184:185], s[34:35], 0, v[164:165]
	global_load_lds_dwordx4 v[182:183], off
	v_lshl_add_u64 v[182:183], s[52:53], 0, v[162:163]
	s_add_i32 m0, s54, 0x2000
	s_nop 0
	global_load_lds_dwordx4 v[182:183], off
	v_lshl_add_u64 v[182:183], s[34:35], 0, v[168:169]
	s_mov_b32 m0, s27
	s_nop 0
	global_load_lds_dwordx4 v[182:183], off
	s_mov_b32 m0, s37
	s_nop 0
	global_load_lds_dwordx4 v[184:185], off
	s_setprio 1
	s_waitcnt vmcnt(8)
	s_waitcnt lgkmcnt(0)
	s_barrier
	v_mfma_scale_f32_16x16x128_f8f6f4 v[94:97], v[26:33], v[194:201], v[94:97], v186, v186 op_sel_hi:[0,0,0]
	v_mfma_scale_f32_16x16x128_f8f6f4 v[90:93], v[18:25], v[194:201], v[90:93], v186, v186 op_sel_hi:[0,0,0]
	v_mfma_scale_f32_16x16x128_f8f6f4 v[82:85], v[26:33], v[202:209], v[82:85], v186, v186 op_sel_hi:[0,0,0]
	v_mfma_scale_f32_16x16x128_f8f6f4 v[74:77], v[18:25], v[202:209], v[74:77], v186, v186 op_sel_hi:[0,0,0]
	v_mfma_scale_f32_16x16x128_f8f6f4 v[66:69], v[26:33], v[210:217], v[66:69], v186, v186 op_sel_hi:[0,0,0]
	v_mfma_scale_f32_16x16x128_f8f6f4 v[58:61], v[18:25], v[210:217], v[58:61], v186, v186 op_sel_hi:[0,0,0]
	v_mfma_scale_f32_16x16x128_f8f6f4 v[50:53], v[26:33], v[218:225], v[50:53], v186, v186 op_sel_hi:[0,0,0]
	v_mfma_scale_f32_16x16x128_f8f6f4 v[42:45], v[18:25], v[218:225], v[42:45], v186, v186 op_sel_hi:[0,0,0]
	v_mfma_scale_f32_16x16x128_f8f6f4 v[86:89], v[10:17], v[194:201], v[86:89], v186, v186 op_sel_hi:[0,0,0]
	v_mfma_scale_f32_16x16x128_f8f6f4 v[78:81], v[2:9], v[194:201], v[78:81], v186, v186 op_sel_hi:[0,0,0]
	v_mfma_scale_f32_16x16x128_f8f6f4 v[70:73], v[10:17], v[202:209], v[70:73], v186, v186 op_sel_hi:[0,0,0]
	v_mfma_scale_f32_16x16x128_f8f6f4 v[62:65], v[2:9], v[202:209], v[62:65], v186, v186 op_sel_hi:[0,0,0]
	v_mfma_scale_f32_16x16x128_f8f6f4 v[54:57], v[10:17], v[210:217], v[54:57], v186, v186 op_sel_hi:[0,0,0]
	v_mfma_scale_f32_16x16x128_f8f6f4 v[46:49], v[2:9], v[210:217], v[46:49], v186, v186 op_sel_hi:[0,0,0]
	v_mfma_scale_f32_16x16x128_f8f6f4 v[38:41], v[10:17], v[218:225], v[38:41], v186, v186 op_sel_hi:[0,0,0]
	v_mfma_scale_f32_16x16x128_f8f6f4 v[34:37], v[2:9], v[218:225], v[34:37], v186, v186 op_sel_hi:[0,0,0]
	s_barrier
; #define PG8_STAGE(bufoff, gbase, voff) do { _Pragma("unroll") for (int _i = 0; _i < 2; ++_i) \
;         __builtin_amdgcn_global_load_lds((const unsigned*)((const char*)(gbase) + (voff)[_i]), (PG8_LAS unsigned*)(lds + (bufoff) + ldsw + _i * 8192), 16, 0, 0); } while (0)
; #define PG8_LDA(dst, b, h) do { _Pragma("unroll") for (int m = 0; m < 4; ++m) _Pragma("unroll") for (int k = 0; k < 2; ++k) dst[m][k] = *(const PG8_LAS bf16x8*)(lds + PG8_SA(b, h) + aoff + m * 2048 + k * 1024); } while (0)
; #define PG8_LDB(dst, b, h) do { _Pragma("unroll") for (int n = 0; n < 2; ++n) _Pragma("unroll") for (int k = 0; k < 2; ++k) dst[n][k] = *(const PG8_LAS bf16x8*)(lds + PG8_SB(b, h) + boff + n * 2048 + k * 1024); } while (0)
; #define PG8_WAIT_V(n) asm volatile("s_waitcnt vmcnt(" #n ")" ::: "memory")
; #define PG8_WAIT_L(n) asm volatile("s_waitcnt lgkmcnt(" #n ")" ::: "memory")
; #define PG8_BAR __builtin_amdgcn_s_barrier()
; #define PG8_SCHED __builtin_amdgcn_sched_barrier(0)
; template <class Epi, class Sched, bool ALIGN_EPI = false, bool SP2 = false, bool F8 = false>
; __device__ __forceinline__ void gemm_phase(PG8_LAS unsigned char* lds, const Gemm g, const Sched& S, const Epi& E) {
;     ...
;             PG8_LDB(B0, 1, 0); PG8_LDB(B1, 1, 1); PG8_SCHED; PG8_LDA(At, 1, 0); PG8_STAGE(PG8_SA(0, 1), a2 + hA, voffA);
;             PG8_WAIT_V(8); PG8_WAIT_L(0); PG8_BAR; PG8_MMA(0, 0, At, B0); PG8_MMA(0, 1, At, B1); PG8_BAR; PG8_SCHED;
;             PG8_LDA(At, 1, 1); PG8_STAGE(PG8_SB(1, 0), b3, voffB); PG8_STAGE(PG8_SB(1, 1), b3 + hB, voffB); PG8_STAGE(PG8_SA(1, 0), a3, voffA);
;             PG8_WAIT_V(8); PG8_WAIT_L(0); PG8_BAR; PG8_MMA(1, 0, At, B0); PG8_MMA(1, 1, At, B1); PG8_BAR; PG8_SCHED;
	s_setprio 0
	s_add_i32 s52, 0, 0x18000
	s_add_i32 s53, 0, 0x1c000
	v_add_u32_e32 v14, s52, v188
	v_add_u32_e32 v30, s53, v188
	ds_read_b128 v[2:5], v14
	ds_read_b128 v[6:9], v14 offset:1024
	ds_read_b128 v[10:13], v14 offset:2048
	ds_read_b128 v[14:17], v14 offset:3072
	ds_read_b128 v[18:21], v30
	ds_read_b128 v[22:25], v30 offset:1024
	ds_read_b128 v[26:29], v30 offset:2048
	ds_read_b128 v[30:33], v30 offset:3072
	s_add_u32 s34, s34, 0x40000
	s_addc_u32 s35, s35, 0
	s_mov_b32 m0, s38
	v_lshl_add_u64 v[226:227], s[34:35], 0, v[168:169]
	ds_read_b128 v[194:197], v192 offset:32768
	ds_read_b128 v[198:201], v192 offset:33792
	ds_read_b128 v[202:205], v192 offset:34816
	ds_read_b128 v[206:209], v192 offset:35840
	ds_read_b128 v[210:213], v192 offset:36864
	ds_read_b128 v[214:217], v192 offset:37888
	ds_read_b128 v[218:221], v192 offset:38912
	ds_read_b128 v[222:225], v192 offset:39936
	global_load_lds_dwordx4 v[226:227], off
	v_lshl_add_u64 v[226:227], s[34:35], 0, v[164:165]
	s_mov_b32 m0, s39
	s_nop 0
	global_load_lds_dwordx4 v[226:227], off
	s_setprio 1
	s_waitcnt vmcnt(8)
	s_waitcnt lgkmcnt(0)
	s_barrier
	v_mfma_scale_f32_16x16x128_f8f6f4 v[158:161], v[2:9], v[194:201], v[158:161], v186, v186 op_sel_hi:[0,0,0]
	v_mfma_scale_f32_16x16x128_f8f6f4 v[154:157], v[10:17], v[194:201], v[154:157], v186, v186 op_sel_hi:[0,0,0]
	v_mfma_scale_f32_16x16x128_f8f6f4 v[146:149], v[2:9], v[202:209], v[146:149], v186, v186 op_sel_hi:[0,0,0]
	v_mfma_scale_f32_16x16x128_f8f6f4 v[138:141], v[10:17], v[202:209], v[138:141], v186, v186 op_sel_hi:[0,0,0]
	v_mfma_scale_f32_16x16x128_f8f6f4 v[130:133], v[2:9], v[210:217], v[130:133], v186, v186 op_sel_hi:[0,0,0]
	v_mfma_scale_f32_16x16x128_f8f6f4 v[122:125], v[10:17], v[210:217], v[122:125], v186, v186 op_sel_hi:[0,0,0]
	v_mfma_scale_f32_16x16x128_f8f6f4 v[114:117], v[2:9], v[218:225], v[114:117], v186, v186 op_sel_hi:[0,0,0]
	v_mfma_scale_f32_16x16x128_f8f6f4 v[106:109], v[10:17], v[218:225], v[106:109], v186, v186 op_sel_hi:[0,0,0]
	v_mfma_scale_f32_16x16x128_f8f6f4 v[150:153], v[18:25], v[194:201], v[150:153], v186, v186 op_sel_hi:[0,0,0]
	v_mfma_scale_f32_16x16x128_f8f6f4 v[142:145], v[26:33], v[194:201], v[142:145], v186, v186 op_sel_hi:[0,0,0]
	v_mfma_scale_f32_16x16x128_f8f6f4 v[134:137], v[18:25], v[202:209], v[134:137], v186, v186 op_sel_hi:[0,0,0]
	v_mfma_scale_f32_16x16x128_f8f6f4 v[126:129], v[26:33], v[202:209], v[126:129], v186, v186 op_sel_hi:[0,0,0]
	v_mfma_scale_f32_16x16x128_f8f6f4 v[118:121], v[18:25], v[210:217], v[118:121], v186, v186 op_sel_hi:[0,0,0]
	v_mfma_scale_f32_16x16x128_f8f6f4 v[110:113], v[26:33], v[210:217], v[110:113], v186, v186 op_sel_hi:[0,0,0]
	v_mfma_scale_f32_16x16x128_f8f6f4 v[102:105], v[18:25], v[218:225], v[102:105], v186, v186 op_sel_hi:[0,0,0]
	v_mfma_scale_f32_16x16x128_f8f6f4 v[98:101], v[26:33], v[218:225], v[98:101], v186, v186 op_sel_hi:[0,0,0]
	s_barrier
	s_setprio 0
	s_add_i32 s34, s52, s19
	v_lshl_add_u64 v[178:179], v[178:179], 0, s[14:15]
	s_mov_b32 m0, s34
	ds_read_b128 v[194:197], v192 offset:49152
	ds_read_b128 v[198:201], v192 offset:50176
	ds_read_b128 v[202:205], v192 offset:51200
	ds_read_b128 v[206:209], v192 offset:52224
	ds_read_b128 v[210:213], v192 offset:53248
	ds_read_b128 v[214:217], v192 offset:54272
	ds_read_b128 v[218:221], v192 offset:55296
	ds_read_b128 v[222:225], v192 offset:56320
	global_load_lds_dwordx4 v[178:179], off
	s_add_i32 m0, s34, 0x2000
	s_add_u32 s30, s30, 0x40080
	v_lshl_add_u64 v[178:179], v[180:181], 0, s[14:15]
	s_addc_u32 s31, s31, 0
	s_add_i32 s34, s53, s19
	global_load_lds_dwordx4 v[178:179], off
	v_lshl_add_u64 v[178:179], s[30:31], 0, v[166:167]
	s_mov_b32 m0, s34
	s_nop 0
	global_load_lds_dwordx4 v[178:179], off
	v_lshl_add_u64 v[178:179], s[30:31], 0, v[162:163]
	s_add_i32 m0, s34, 0x2000
	s_nop 0
	global_load_lds_dwordx4 v[178:179], off
	v_lshl_add_u64 v[178:179], v[182:183], 0, s[14:15]
	s_mov_b32 m0, s41
	s_nop 0
	global_load_lds_dwordx4 v[178:179], off
	v_lshl_add_u64 v[178:179], v[184:185], 0, s[14:15]
	s_mov_b32 m0, s42
	s_nop 0
	global_load_lds_dwordx4 v[178:179], off
	s_setprio 1
	s_waitcnt vmcnt(8)
	s_waitcnt lgkmcnt(0)
	s_barrier
	v_mfma_scale_f32_16x16x128_f8f6f4 v[94:97], v[2:9], v[194:201], v[94:97], v186, v186 op_sel_hi:[0,0,0]
	v_mfma_scale_f32_16x16x128_f8f6f4 v[90:93], v[10:17], v[194:201], v[90:93], v186, v186 op_sel_hi:[0,0,0]
	v_mfma_scale_f32_16x16x128_f8f6f4 v[82:85], v[2:9], v[202:209], v[82:85], v186, v186 op_sel_hi:[0,0,0]
	v_mfma_scale_f32_16x16x128_f8f6f4 v[74:77], v[10:17], v[202:209], v[74:77], v186, v186 op_sel_hi:[0,0,0]
	v_mfma_scale_f32_16x16x128_f8f6f4 v[66:69], v[2:9], v[210:217], v[66:69], v186, v186 op_sel_hi:[0,0,0]
	v_mfma_scale_f32_16x16x128_f8f6f4 v[58:61], v[10:17], v[210:217], v[58:61], v186, v186 op_sel_hi:[0,0,0]
	v_mfma_scale_f32_16x16x128_f8f6f4 v[50:53], v[2:9], v[218:225], v[50:53], v186, v186 op_sel_hi:[0,0,0]
	v_mfma_scale_f32_16x16x128_f8f6f4 v[42:45], v[10:17], v[218:225], v[42:45], v186, v186 op_sel_hi:[0,0,0]
	v_mfma_scale_f32_16x16x128_f8f6f4 v[86:89], v[18:25], v[194:201], v[86:89], v186, v186 op_sel_hi:[0,0,0]
	v_mfma_scale_f32_16x16x128_f8f6f4 v[78:81], v[26:33], v[194:201], v[78:81], v186, v186 op_sel_hi:[0,0,0]
	v_mfma_scale_f32_16x16x128_f8f6f4 v[70:73], v[18:25], v[202:209], v[70:73], v186, v186 op_sel_hi:[0,0,0]
	v_mfma_scale_f32_16x16x128_f8f6f4 v[62:65], v[26:33], v[202:209], v[62:65], v186, v186 op_sel_hi:[0,0,0]
	v_mfma_scale_f32_16x16x128_f8f6f4 v[54:57], v[18:25], v[210:217], v[54:57], v186, v186 op_sel_hi:[0,0,0]
	v_mfma_scale_f32_16x16x128_f8f6f4 v[46:49], v[26:33], v[210:217], v[46:49], v186, v186 op_sel_hi:[0,0,0]
	v_mfma_scale_f32_16x16x128_f8f6f4 v[38:41], v[18:25], v[218:225], v[38:41], v186, v186 op_sel_hi:[0,0,0]
	v_mfma_scale_f32_16x16x128_f8f6f4 v[34:37], v[26:33], v[218:225], v[34:37], v186, v186 op_sel_hi:[0,0,0]
	s_barrier
; #define PG8_GAS __attribute__((address_space(1)))
; __device__ __forceinline__ unsigned cvt_pk_bf16(float lo, float hi) { const f32x2c v = {lo, hi}; return __builtin_bit_cast(unsigned, __builtin_convertvector(v, bf16x2c)); }
; __device__ __forceinline__ float bf_lo(unsigned w) { return __uint_as_float(w << 16); }
; __device__ __forceinline__ float bf_hi(unsigned w) { return __uint_as_float(w & 0xffff0000u); }
; #define PG8_BAR __builtin_amdgcn_s_barrier()
;     __device__ __forceinline__ void operator()(const f32x4 (&acc)[2][2][4][2], const Unit& un, int wr, int wc, int fr, int fq) const {
;         const int row0 = un.pm * BM + wr * 64 + fr, col0 = un.pn * BM + wc * 32 + 8 * fq;
; #pragma unroll
;         for (int ai = 0; ai < 2; ++ai) {
;             u32x4 gg[4][2], pp[4][2];
; #pragma unroll
;             for (int m = 0; m < 4; ++m)
; #pragma unroll
;                 for (int bj = 0; bj < 2; ++bj) { const size_t off = (size_t)(row0 + ai * HALF + m * 16) * 4096 + col0 + bj * HALF; gg[m][bj] = *(const PG8_GAS u32x4*)(sa + off); pp[m][bj] = *(const PG8_GAS u32x4*)(P + off); }
;             asm volatile("" ::: "memory");
; #pragma unroll
;             for (int m = 0; m < 4; ++m)
; #pragma unroll
;                 for (int bj = 0; bj < 2; ++bj) { const u32x4 g = gg[m][bj], p = pp[m][bj]; const f32x4 v0 = acc[ai][bj][m][0], v1 = acc[ai][bj][m][1];
;                     u32x4 w; w.x = cvt_pk_bf16(v0[0] * bf_lo(g.x) + bf_lo(p.x), v0[1] * bf_hi(g.x) + bf_hi(p.x)); w.y = cvt_pk_bf16(v0[2] * bf_lo(g.y) + bf_lo(p.y), v0[3] * bf_hi(g.y) + bf_hi(p.y));
;                     w.z = cvt_pk_bf16(v1[0] * bf_lo(g.z) + bf_lo(p.z), v1[1] * bf_hi(g.z) + bf_hi(p.z)); w.w = cvt_pk_bf16(v1[2] * bf_lo(g.w) + bf_lo(p.w), v1[3] * bf_hi(g.w) + bf_hi(p.w));
;                     *(PG8_GAS u32x4*)(sa + (size_t)(row0 + ai * HALF + m * 16) * 4096 + col0 + bj * HALF) = w; }
; template <class Epi, class Sched, bool ALIGN_EPI = false, bool SP2 = false, bool F8 = false>
; __device__ __forceinline__ void gemm_phase(PG8_LAS unsigned char* lds, const Gemm g, const Sched& S, const Epi& E) {
;     ...
;         }
;         if constexpr (ALIGN_EPI) { if (wr == 0) PG8_BAR; }
;         if constexpr (F8) asm volatile("s_nop 15\n\ts_nop 15\n\ts_nop 7" ::: "memory");
	s_setprio 0
	s_add_i32 s51, s51, 2
	s_add_u32 s49, s49, 0x100
	s_addc_u32 s50, s50, 0
	s_add_u32 s28, s28, 0x100
	s_addc_u32 s29, s29, 0
	s_cmp_gt_u32 s51, 13
	s_cbranch_scc0 .LBB0_630
	v_lshl_add_u32 v182, s26, 8, v187
	v_lshl_or_b32 v180, s46, 8, v189
	v_ashrrev_i32_e32 v183, 31, v182
	v_ashrrev_i32_e32 v181, 31, v180
	v_lshlrev_b64 v[2:3], 12, v[182:183]
	v_lshl_add_u64 v[2:3], v[2:3], 0, v[180:181]
	v_lshlrev_b64 v[2:3], 1, v[2:3]
	s_nop 15
	s_nop 15
	s_nop 7
	v_lshl_add_u64 v[4:5], s[10:11], 0, v[2:3]
	global_load_dwordx4 v[30:33], v[4:5], off
	v_lshl_add_u64 v[4:5], s[12:13], 0, v[2:3]
	global_load_dwordx4 v[194:197], v[4:5], off
	v_or_b32_e32 v2, 0x100, v2
	v_lshl_add_u64 v[4:5], s[10:11], 0, v[2:3]
	v_lshl_add_u64 v[2:3], s[12:13], 0, v[2:3]
	global_load_dwordx4 v[198:201], v[4:5], off
	global_load_dwordx4 v[202:205], v[2:3], off
	v_or_b32_e32 v184, 16, v182
	v_ashrrev_i32_e32 v185, 31, v184
	v_lshlrev_b64 v[2:3], 13, v[182:183]
	v_lshlrev_b64 v[4:5], 12, v[184:185]
	v_lshlrev_b64 v[178:179], 1, v[180:181]
	v_lshl_add_u64 v[2:3], s[10:11], 0, v[2:3]
	v_lshl_add_u64 v[4:5], v[4:5], 0, v[180:181]
	v_lshl_add_u64 v[230:231], v[2:3], 0, v[178:179]
	v_lshlrev_b64 v[2:3], 1, v[4:5]
	v_lshl_add_u64 v[4:5], s[10:11], 0, v[2:3]
	global_load_dwordx4 v[206:209], v[4:5], off
	v_lshl_add_u64 v[4:5], s[12:13], 0, v[2:3]
	global_load_dwordx4 v[210:213], v[4:5], off
	v_or_b32_e32 v28, 32, v182
	v_or_b32_e32 v26, 48, v182
	v_ashrrev_i32_e32 v29, 31, v28
	v_ashrrev_i32_e32 v27, 31, v26
	v_lshlrev_b64 v[6:7], 12, v[28:29]
	v_lshlrev_b64 v[8:9], 12, v[26:27]
	v_lshl_add_u64 v[6:7], v[6:7], 0, v[180:181]
	v_lshl_add_u64 v[8:9], v[8:9], 0, v[180:181]
	v_lshlrev_b64 v[4:5], 1, v[6:7]
	v_lshlrev_b64 v[6:7], 1, v[8:9]
	v_or_b32_e32 v2, 0x100, v2
	v_lshl_add_u64 v[8:9], s[10:11], 0, v[4:5]
	v_lshl_add_u64 v[10:11], s[12:13], 0, v[4:5]
	v_or_b32_e32 v4, 0x100, v4
	v_lshl_add_u64 v[12:13], s[10:11], 0, v[6:7]
	v_lshl_add_u64 v[18:19], s[12:13], 0, v[6:7]
	v_or_b32_e32 v6, 0x100, v6
	v_lshl_add_u64 v[20:21], s[10:11], 0, v[2:3]
	v_lshl_add_u64 v[2:3], s[12:13], 0, v[2:3]
	global_load_dwordx4 v[214:217], v[8:9], off
	global_load_dwordx4 v[218:221], v[10:11], off
	v_lshl_add_u64 v[8:9], s[10:11], 0, v[4:5]
	v_lshl_add_u64 v[4:5], s[12:13], 0, v[4:5]
	global_load_dwordx4 v[14:17], v[12:13], off
	s_nop 0
	global_load_dwordx4 v[10:13], v[18:19], off
	v_lshl_add_u64 v[232:233], s[10:11], 0, v[6:7]
	v_lshl_add_u64 v[234:235], s[12:13], 0, v[6:7]
	global_load_dwordx4 v[222:225], v[20:21], off
	global_load_dwordx4 v[226:229], v[2:3], off
	global_load_dwordx4 v[22:25], v[8:9], off
	s_nop 0
	global_load_dwordx4 v[18:21], v[4:5], off
	global_load_dwordx4 v[6:9], v[232:233], off
	s_nop 0
	global_load_dwordx4 v[2:5], v[234:235], off
	s_and_b64 vcc, exec, s[8:9]
	s_mov_b32 s46, s16
	s_mov_b32 s26, s20
	s_mov_b64 s[28:29], s[24:25]
	s_mov_b64 s[30:31], s[22:23]
	s_waitcnt vmcnt(0)
	v_lshlrev_b32_e32 v232, 16, v30
	v_and_b32_e32 v233, 0xffff0000, v30
	v_lshlrev_b32_e32 v234, 16, v194
	v_and_b32_e32 v235, 0xffff0000, v194
	v_lshlrev_b32_e32 v30, 16, v31
	v_and_b32_e32 v31, 0xffff0000, v31
	v_lshlrev_b32_e32 v194, 16, v195
	v_and_b32_e32 v195, 0xffff0000, v195
	v_lshlrev_b32_e32 v236, 16, v32
	v_and_b32_e32 v237, 0xffff0000, v32
	v_lshlrev_b32_e32 v238, 16, v196
	v_and_b32_e32 v239, 0xffff0000, v196
	v_lshlrev_b32_e32 v32, 16, v33
	v_and_b32_e32 v33, 0xffff0000, v33
	v_lshlrev_b32_e32 v196, 16, v197
	v_and_b32_e32 v197, 0xffff0000, v197
	v_pk_fma_f32 v[158:159], v[158:159], v[232:233], v[234:235]
	v_pk_fma_f32 v[160:161], v[160:161], v[30:31], v[194:195]
	v_pk_fma_f32 v[154:155], v[154:155], v[236:237], v[238:239]
	v_pk_fma_f32 v[156:157], v[156:157], v[32:33], v[196:197]
	v_cvt_pk_bf16_f32 v30, v158, v159
	v_cvt_pk_bf16_f32 v31, v160, v161
	v_cvt_pk_bf16_f32 v32, v154, v155
	v_cvt_pk_bf16_f32 v33, v156, v157
	v_lshlrev_b32_e32 v194, 16, v198
	global_store_dwordx4 v[230:231], v[30:33], off
	v_and_b32_e32 v195, 0xffff0000, v198
	s_nop 0
	v_lshlrev_b32_e32 v30, 16, v202
	v_and_b32_e32 v31, 0xffff0000, v202
	v_pk_fma_f32 v[30:31], v[150:151], v[194:195], v[30:31]
	v_lshlrev_b32_e32 v32, 16, v199
	v_and_b32_e32 v33, 0xffff0000, v199
	v_lshlrev_b32_e32 v150, 16, v203
	v_and_b32_e32 v151, 0xffff0000, v203
	v_pk_fma_f32 v[32:33], v[152:153], v[32:33], v[150:151]
	v_cvt_pk_bf16_f32 v30, v30, v31
	v_cvt_pk_bf16_f32 v31, v32, v33
	v_lshlrev_b32_e32 v32, 16, v200
	v_and_b32_e32 v33, 0xffff0000, v200
	v_lshlrev_b32_e32 v150, 16, v204
	v_and_b32_e32 v151, 0xffff0000, v204
	v_pk_fma_f32 v[32:33], v[142:143], v[32:33], v[150:151]
	v_lshlrev_b32_e32 v142, 16, v201
	v_and_b32_e32 v143, 0xffff0000, v201
	v_lshlrev_b32_e32 v150, 16, v205
	v_and_b32_e32 v151, 0xffff0000, v205
	v_pk_fma_f32 v[142:143], v[144:145], v[142:143], v[150:151]
	v_cvt_pk_bf16_f32 v32, v32, v33
	v_cvt_pk_bf16_f32 v33, v142, v143
	global_store_dwordx4 v[230:231], v[30:33], off offset:256
	v_lshlrev_b32_e32 v144, 16, v211
	v_and_b32_e32 v145, 0xffff0000, v211
	v_lshlrev_b32_e32 v30, 16, v206
	v_and_b32_e32 v31, 0xffff0000, v206
	v_lshlrev_b32_e32 v32, 16, v210
	v_and_b32_e32 v33, 0xffff0000, v210
	v_pk_fma_f32 v[30:31], v[146:147], v[30:31], v[32:33]
	v_lshlrev_b32_e32 v32, 16, v207
	v_and_b32_e32 v33, 0xffff0000, v207
	v_pk_fma_f32 v[32:33], v[148:149], v[32:33], v[144:145]
	v_cvt_pk_bf16_f32 v30, v30, v31
	v_cvt_pk_bf16_f32 v31, v32, v33
	v_lshlrev_b32_e32 v32, 16, v208
	v_and_b32_e32 v33, 0xffff0000, v208
	v_lshlrev_b32_e32 v144, 16, v212
	v_and_b32_e32 v145, 0xffff0000, v212
	v_pk_fma_f32 v[32:33], v[138:139], v[32:33], v[144:145]
	v_lshlrev_b32_e32 v138, 16, v209
	v_and_b32_e32 v139, 0xffff0000, v209
; #define PG8_GAS __attribute__((address_space(1)))
; __device__ __forceinline__ unsigned cvt_pk_bf16(float lo, float hi) { const f32x2c v = {lo, hi}; return __builtin_bit_cast(unsigned, __builtin_convertvector(v, bf16x2c)); }
; __device__ __forceinline__ float bf_lo(unsigned w) { return __uint_as_float(w << 16); }
; __device__ __forceinline__ float bf_hi(unsigned w) { return __uint_as_float(w & 0xffff0000u); }
;     __device__ __forceinline__ void operator()(const f32x4 (&acc)[2][2][4][2], const Unit& un, int wr, int wc, int fr, int fq) const {
;     ...
;             for (int m = 0; m < 4; ++m)
; #pragma unroll
;                 for (int bj = 0; bj < 2; ++bj) { const u32x4 g = gg[m][bj], p = pp[m][bj]; const f32x4 v0 = acc[ai][bj][m][0], v1 = acc[ai][bj][m][1];
;                     u32x4 w; w.x = cvt_pk_bf16(v0[0] * bf_lo(g.x) + bf_lo(p.x), v0[1] * bf_hi(g.x) + bf_hi(p.x)); w.y = cvt_pk_bf16(v0[2] * bf_lo(g.y) + bf_lo(p.y), v0[3] * bf_hi(g.y) + bf_hi(p.y));
;                     w.z = cvt_pk_bf16(v1[0] * bf_lo(g.z) + bf_lo(p.z), v1[1] * bf_hi(g.z) + bf_hi(p.z)); w.w = cvt_pk_bf16(v1[2] * bf_lo(g.w) + bf_lo(p.w), v1[3] * bf_hi(g.w) + bf_hi(p.w));
;                     *(PG8_GAS u32x4*)(sa + (size_t)(row0 + ai * HALF + m * 16) * 4096 + col0 + bj * HALF) = w; }
	v_lshlrev_b32_e32 v144, 16, v213
	v_and_b32_e32 v145, 0xffff0000, v213
	v_lshlrev_b64 v[142:143], 13, v[184:185]
	v_pk_fma_f32 v[138:139], v[140:141], v[138:139], v[144:145]
	v_cvt_pk_bf16_f32 v32, v32, v33
	v_cvt_pk_bf16_f32 v33, v138, v139
	v_lshl_add_u64 v[138:139], s[10:11], 0, v[142:143]
	v_lshl_add_u64 v[138:139], v[138:139], 0, v[178:179]
	global_store_dwordx4 v[138:139], v[30:33], off
	s_nop 1
	v_lshlrev_b32_e32 v30, 16, v222
	v_and_b32_e32 v31, 0xffff0000, v222
	v_lshlrev_b32_e32 v32, 16, v226
	v_and_b32_e32 v33, 0xffff0000, v226
	v_pk_fma_f32 v[30:31], v[134:135], v[30:31], v[32:33]
	v_lshlrev_b32_e32 v32, 16, v223
	v_and_b32_e32 v33, 0xffff0000, v223
	v_lshlrev_b32_e32 v134, 16, v227
	v_and_b32_e32 v135, 0xffff0000, v227
	v_pk_fma_f32 v[32:33], v[136:137], v[32:33], v[134:135]
	v_cvt_pk_bf16_f32 v30, v30, v31
	v_cvt_pk_bf16_f32 v31, v32, v33
	v_lshlrev_b32_e32 v32, 16, v224
	v_and_b32_e32 v33, 0xffff0000, v224
	v_lshlrev_b32_e32 v134, 16, v228
	v_and_b32_e32 v135, 0xffff0000, v228
	v_pk_fma_f32 v[32:33], v[126:127], v[32:33], v[134:135]
	v_lshlrev_b32_e32 v126, 16, v225
	v_and_b32_e32 v127, 0xffff0000, v225
	v_lshlrev_b32_e32 v134, 16, v229
	v_and_b32_e32 v135, 0xffff0000, v229
	v_pk_fma_f32 v[126:127], v[128:129], v[126:127], v[134:135]
	v_cvt_pk_bf16_f32 v32, v32, v33
	v_cvt_pk_bf16_f32 v33, v126, v127
	global_store_dwordx4 v[138:139], v[30:33], off offset:256
	v_lshlrev_b32_e32 v126, 16, v219
	v_and_b32_e32 v127, 0xffff0000, v219
	v_lshlrev_b64 v[32:33], 13, v[28:29]
	v_lshlrev_b32_e32 v28, 16, v214
	v_and_b32_e32 v29, 0xffff0000, v214
	v_lshlrev_b32_e32 v30, 16, v218
	v_and_b32_e32 v31, 0xffff0000, v218
	v_pk_fma_f32 v[28:29], v[130:131], v[28:29], v[30:31]
	v_lshlrev_b32_e32 v30, 16, v215
	v_and_b32_e32 v31, 0xffff0000, v215
	v_pk_fma_f32 v[30:31], v[132:133], v[30:31], v[126:127]
	v_cvt_pk_bf16_f32 v28, v28, v29
	v_cvt_pk_bf16_f32 v29, v30, v31
	v_lshlrev_b32_e32 v30, 16, v216
	v_and_b32_e32 v31, 0xffff0000, v216
	v_lshlrev_b32_e32 v126, 16, v220
	v_and_b32_e32 v127, 0xffff0000, v220
	v_pk_fma_f32 v[30:31], v[122:123], v[30:31], v[126:127]
	v_lshlrev_b32_e32 v122, 16, v217
	v_and_b32_e32 v123, 0xffff0000, v217
	v_lshlrev_b32_e32 v126, 16, v221
	v_and_b32_e32 v127, 0xffff0000, v221
	v_pk_fma_f32 v[122:123], v[124:125], v[122:123], v[126:127]
	v_lshl_add_u64 v[32:33], s[10:11], 0, v[32:33]
	v_cvt_pk_bf16_f32 v30, v30, v31
	v_cvt_pk_bf16_f32 v31, v122, v123
	v_lshl_add_u64 v[32:33], v[32:33], 0, v[178:179]
	global_store_dwordx4 v[32:33], v[28:31], off
	v_add_u32_e32 v132, 0x80, v182
	v_ashrrev_i32_e32 v133, 31, v132
	v_lshlrev_b32_e32 v28, 16, v22
	v_and_b32_e32 v29, 0xffff0000, v22
	v_lshlrev_b32_e32 v30, 16, v18
	v_and_b32_e32 v31, 0xffff0000, v18
	v_pk_fma_f32 v[28:29], v[118:119], v[28:29], v[30:31]
	v_lshlrev_b32_e32 v22, 16, v23
	v_cvt_pk_bf16_f32 v18, v28, v29
	v_and_b32_e32 v23, 0xffff0000, v23
	v_lshlrev_b32_e32 v28, 16, v19
	v_and_b32_e32 v29, 0xffff0000, v19
	v_pk_fma_f32 v[22:23], v[120:121], v[22:23], v[28:29]
	v_lshlrev_b32_e32 v28, 16, v20
	v_cvt_pk_bf16_f32 v19, v22, v23
	v_lshlrev_b32_e32 v22, 16, v24
	v_and_b32_e32 v23, 0xffff0000, v24
	v_and_b32_e32 v29, 0xffff0000, v20
	v_pk_fma_f32 v[22:23], v[110:111], v[22:23], v[28:29]
	v_lshlrev_b32_e32 v24, 16, v21
	v_cvt_pk_bf16_f32 v20, v22, v23
	v_lshlrev_b32_e32 v22, 16, v25
	v_and_b32_e32 v23, 0xffff0000, v25
	v_and_b32_e32 v25, 0xffff0000, v21
	v_pk_fma_f32 v[22:23], v[112:113], v[22:23], v[24:25]
	v_add_u32_e32 v134, 0x90, v182
	v_cvt_pk_bf16_f32 v21, v22, v23
	global_store_dwordx4 v[32:33], v[18:21], off offset:256
	v_lshlrev_b32_e32 v22, 16, v10
	v_and_b32_e32 v23, 0xffff0000, v10
	v_lshlrev_b32_e32 v20, 16, v14
	v_and_b32_e32 v21, 0xffff0000, v14
	v_pk_fma_f32 v[20:21], v[114:115], v[20:21], v[22:23]
	v_lshlrev_b32_e32 v14, 16, v15
	v_cvt_pk_bf16_f32 v10, v20, v21
	v_and_b32_e32 v15, 0xffff0000, v15
	v_lshlrev_b32_e32 v20, 16, v11
	v_and_b32_e32 v21, 0xffff0000, v11
	v_pk_fma_f32 v[14:15], v[116:117], v[14:15], v[20:21]
	v_lshlrev_b32_e32 v20, 16, v12
	v_cvt_pk_bf16_f32 v11, v14, v15
	v_lshlrev_b32_e32 v14, 16, v16
	v_and_b32_e32 v15, 0xffff0000, v16
	v_and_b32_e32 v21, 0xffff0000, v12
	v_pk_fma_f32 v[14:15], v[106:107], v[14:15], v[20:21]
	v_lshlrev_b32_e32 v16, 16, v13
	v_cvt_pk_bf16_f32 v12, v14, v15
	v_lshlrev_b32_e32 v14, 16, v17
	v_and_b32_e32 v15, 0xffff0000, v17
	v_and_b32_e32 v17, 0xffff0000, v13
	v_lshlrev_b64 v[18:19], 13, v[26:27]
	v_pk_fma_f32 v[14:15], v[108:109], v[14:15], v[16:17]
	v_ashrrev_i32_e32 v135, 31, v134
	v_cvt_pk_bf16_f32 v13, v14, v15
	v_lshl_add_u64 v[14:15], s[10:11], 0, v[18:19]
	v_lshl_add_u64 v[14:15], v[14:15], 0, v[178:179]
	global_store_dwordx4 v[14:15], v[10:13], off
	v_add_u32_e32 v136, 0xa0, v182
	v_ashrrev_i32_e32 v137, 31, v136
	v_lshlrev_b32_e32 v10, 16, v6
	v_and_b32_e32 v11, 0xffff0000, v6
	v_lshlrev_b32_e32 v12, 16, v2
	v_and_b32_e32 v13, 0xffff0000, v2
	v_pk_fma_f32 v[10:11], v[102:103], v[10:11], v[12:13]
	v_lshlrev_b32_e32 v6, 16, v7
	v_cvt_pk_bf16_f32 v2, v10, v11
	v_and_b32_e32 v7, 0xffff0000, v7
	v_lshlrev_b32_e32 v10, 16, v3
	v_and_b32_e32 v11, 0xffff0000, v3
	v_pk_fma_f32 v[6:7], v[104:105], v[6:7], v[10:11]
	v_lshlrev_b32_e32 v10, 16, v4
	v_cvt_pk_bf16_f32 v3, v6, v7
	v_lshlrev_b32_e32 v6, 16, v8
	v_and_b32_e32 v7, 0xffff0000, v8
	v_and_b32_e32 v11, 0xffff0000, v4
	v_pk_fma_f32 v[6:7], v[98:99], v[6:7], v[10:11]
	v_lshlrev_b32_e32 v8, 16, v5
	v_cvt_pk_bf16_f32 v4, v6, v7
	v_lshlrev_b32_e32 v6, 16, v9
	v_and_b32_e32 v7, 0xffff0000, v9
	v_and_b32_e32 v9, 0xffff0000, v5
	v_pk_fma_f32 v[6:7], v[100:101], v[6:7], v[8:9]
	v_add_u32_e32 v98, 0xb0, v182
	v_cvt_pk_bf16_f32 v5, v6, v7
; #define PG8_GAS __attribute__((address_space(1)))
; __device__ __forceinline__ unsigned cvt_pk_bf16(float lo, float hi) { const f32x2c v = {lo, hi}; return __builtin_bit_cast(unsigned, __builtin_convertvector(v, bf16x2c)); }
; __device__ __forceinline__ float bf_lo(unsigned w) { return __uint_as_float(w << 16); }
; __device__ __forceinline__ float bf_hi(unsigned w) { return __uint_as_float(w & 0xffff0000u); }
;     __device__ __forceinline__ void operator()(const f32x4 (&acc)[2][2][4][2], const Unit& un, int wr, int wc, int fr, int fq) const {
;     ...
;             for (int m = 0; m < 4; ++m)
; #pragma unroll
;                 for (int bj = 0; bj < 2; ++bj) { const size_t off = (size_t)(row0 + ai * HALF + m * 16) * 4096 + col0 + bj * HALF; gg[m][bj] = *(const PG8_GAS u32x4*)(sa + off); pp[m][bj] = *(const PG8_GAS u32x4*)(P + off); }
;             asm volatile("" ::: "memory");
; #pragma unroll
;             for (int m = 0; m < 4; ++m)
; #pragma unroll
;                 for (int bj = 0; bj < 2; ++bj) { const u32x4 g = gg[m][bj], p = pp[m][bj]; const f32x4 v0 = acc[ai][bj][m][0], v1 = acc[ai][bj][m][1];
;                     u32x4 w; w.x = cvt_pk_bf16(v0[0] * bf_lo(g.x) + bf_lo(p.x), v0[1] * bf_hi(g.x) + bf_hi(p.x)); w.y = cvt_pk_bf16(v0[2] * bf_lo(g.y) + bf_lo(p.y), v0[3] * bf_hi(g.y) + bf_hi(p.y));
;                     w.z = cvt_pk_bf16(v1[0] * bf_lo(g.z) + bf_lo(p.z), v1[1] * bf_hi(g.z) + bf_hi(p.z)); w.w = cvt_pk_bf16(v1[2] * bf_lo(g.w) + bf_lo(p.w), v1[3] * bf_hi(g.w) + bf_hi(p.w));
;                     *(PG8_GAS u32x4*)(sa + (size_t)(row0 + ai * HALF + m * 16) * 4096 + col0 + bj * HALF) = w; }
	global_store_dwordx4 v[14:15], v[2:5], off offset:256
	v_ashrrev_i32_e32 v99, 31, v98
	s_nop 0
	v_lshlrev_b64 v[2:3], 12, v[132:133]
	v_lshl_add_u64 v[2:3], v[2:3], 0, v[180:181]
	v_lshlrev_b64 v[2:3], 1, v[2:3]
	v_lshl_add_u64 v[4:5], s[10:11], 0, v[2:3]
	global_load_dwordx4 v[100:103], v[4:5], off
	v_lshl_add_u64 v[4:5], s[12:13], 0, v[2:3]
	global_load_dwordx4 v[104:107], v[4:5], off
	v_or_b32_e32 v2, 0x100, v2
	v_lshl_add_u64 v[4:5], s[10:11], 0, v[2:3]
	v_lshl_add_u64 v[2:3], s[12:13], 0, v[2:3]
	global_load_dwordx4 v[108:111], v[4:5], off
	global_load_dwordx4 v[112:115], v[2:3], off
	v_lshlrev_b64 v[2:3], 12, v[134:135]
	v_lshl_add_u64 v[2:3], v[2:3], 0, v[180:181]
	v_lshlrev_b64 v[2:3], 1, v[2:3]
	v_lshl_add_u64 v[4:5], s[10:11], 0, v[2:3]
	v_lshl_add_u64 v[6:7], s[12:13], 0, v[2:3]
	global_load_dwordx4 v[116:119], v[4:5], off
	global_load_dwordx4 v[120:123], v[6:7], off
	v_or_b32_e32 v2, 0x100, v2
	v_lshl_add_u64 v[4:5], s[10:11], 0, v[2:3]
	v_lshl_add_u64 v[2:3], s[12:13], 0, v[2:3]
	global_load_dwordx4 v[124:127], v[4:5], off
	global_load_dwordx4 v[128:131], v[2:3], off
	v_lshlrev_b64 v[2:3], 12, v[136:137]
	v_lshl_add_u64 v[2:3], v[2:3], 0, v[180:181]
	v_lshlrev_b64 v[2:3], 1, v[2:3]
	v_lshl_add_u64 v[4:5], s[10:11], 0, v[2:3]
	v_lshl_add_u64 v[6:7], s[12:13], 0, v[2:3]
	global_load_dwordx4 v[30:33], v[4:5], off
	global_load_dwordx4 v[26:29], v[6:7], off
	v_or_b32_e32 v2, 0x100, v2
	v_lshl_add_u64 v[4:5], s[10:11], 0, v[2:3]
	v_lshl_add_u64 v[2:3], s[12:13], 0, v[2:3]
	global_load_dwordx4 v[22:25], v[4:5], off
	global_load_dwordx4 v[18:21], v[2:3], off
	v_lshlrev_b64 v[2:3], 12, v[98:99]
	v_lshl_add_u64 v[2:3], v[2:3], 0, v[180:181]
	v_lshlrev_b64 v[2:3], 1, v[2:3]
	v_lshl_add_u64 v[4:5], s[10:11], 0, v[2:3]
	v_lshl_add_u64 v[6:7], s[12:13], 0, v[2:3]
	global_load_dwordx4 v[14:17], v[4:5], off
	global_load_dwordx4 v[10:13], v[6:7], off
	v_or_b32_e32 v2, 0x100, v2
	v_lshl_add_u64 v[4:5], s[10:11], 0, v[2:3]
	v_lshl_add_u64 v[2:3], s[12:13], 0, v[2:3]
	global_load_dwordx4 v[6:9], v[4:5], off
	s_nop 0
	global_load_dwordx4 v[2:5], v[2:3], off
	v_lshlrev_b64 v[132:133], 13, v[132:133]
	s_waitcnt vmcnt(15)
	v_lshlrev_b32_e32 v138, 16, v100
	v_and_b32_e32 v139, 0xffff0000, v100
	s_waitcnt vmcnt(14)
	v_lshlrev_b32_e32 v140, 16, v104
	v_and_b32_e32 v141, 0xffff0000, v104
	v_lshlrev_b32_e32 v100, 16, v101
	v_and_b32_e32 v101, 0xffff0000, v101
	v_lshlrev_b32_e32 v104, 16, v105
	v_and_b32_e32 v105, 0xffff0000, v105
	v_pk_fma_f32 v[94:95], v[94:95], v[138:139], v[140:141]
	v_pk_fma_f32 v[96:97], v[96:97], v[100:101], v[104:105]
	v_cvt_pk_bf16_f32 v94, v94, v95
	v_cvt_pk_bf16_f32 v95, v96, v97
	v_lshlrev_b32_e32 v96, 16, v102
	v_and_b32_e32 v97, 0xffff0000, v102
	v_lshlrev_b32_e32 v100, 16, v106
	v_and_b32_e32 v101, 0xffff0000, v106
	v_pk_fma_f32 v[90:91], v[90:91], v[96:97], v[100:101]
	v_lshlrev_b32_e32 v100, 16, v107
	v_cvt_pk_bf16_f32 v96, v90, v91
	v_lshlrev_b32_e32 v90, 16, v103
	v_and_b32_e32 v91, 0xffff0000, v103
	v_and_b32_e32 v101, 0xffff0000, v107
	v_pk_fma_f32 v[90:91], v[92:93], v[90:91], v[100:101]
	s_waitcnt vmcnt(13)
	v_lshlrev_b32_e32 v92, 16, v108
	v_cvt_pk_bf16_f32 v97, v90, v91
	v_lshl_add_u64 v[90:91], s[10:11], 0, v[132:133]
	v_lshl_add_u64 v[90:91], v[90:91], 0, v[178:179]
	global_store_dwordx4 v[90:91], v[94:97], off
	v_and_b32_e32 v93, 0xffff0000, v108
	s_waitcnt vmcnt(13)
	v_lshlrev_b32_e32 v94, 16, v112
	v_and_b32_e32 v95, 0xffff0000, v112
	v_pk_fma_f32 v[86:87], v[86:87], v[92:93], v[94:95]
	v_lshlrev_b32_e32 v92, 16, v109
	v_and_b32_e32 v93, 0xffff0000, v109
	v_lshlrev_b32_e32 v94, 16, v113
	v_and_b32_e32 v95, 0xffff0000, v113
	v_pk_fma_f32 v[88:89], v[88:89], v[92:93], v[94:95]
	v_cvt_pk_bf16_f32 v86, v86, v87
	v_cvt_pk_bf16_f32 v87, v88, v89
	v_lshlrev_b32_e32 v88, 16, v110
	v_and_b32_e32 v89, 0xffff0000, v110
	v_lshlrev_b32_e32 v92, 16, v114
	v_and_b32_e32 v93, 0xffff0000, v114
	v_pk_fma_f32 v[78:79], v[78:79], v[88:89], v[92:93]
	v_lshlrev_b32_e32 v92, 16, v115
	v_cvt_pk_bf16_f32 v88, v78, v79
	v_lshlrev_b32_e32 v78, 16, v111
	v_and_b32_e32 v79, 0xffff0000, v111
	v_and_b32_e32 v93, 0xffff0000, v115
	v_pk_fma_f32 v[78:79], v[80:81], v[78:79], v[92:93]
	s_waitcnt vmcnt(11)
	v_lshlrev_b32_e32 v80, 16, v120
	v_cvt_pk_bf16_f32 v89, v78, v79
	v_lshlrev_b32_e32 v78, 16, v116
	v_and_b32_e32 v79, 0xffff0000, v116
	v_and_b32_e32 v81, 0xffff0000, v120
	v_pk_fma_f32 v[78:79], v[82:83], v[78:79], v[80:81]
	v_lshlrev_b32_e32 v80, 16, v117
	v_and_b32_e32 v81, 0xffff0000, v117
	v_lshlrev_b32_e32 v82, 16, v121
	v_and_b32_e32 v83, 0xffff0000, v121
	v_pk_fma_f32 v[80:81], v[84:85], v[80:81], v[82:83]
	v_cvt_pk_bf16_f32 v78, v78, v79
	v_cvt_pk_bf16_f32 v79, v80, v81
	v_lshlrev_b32_e32 v80, 16, v118
	v_and_b32_e32 v81, 0xffff0000, v118
	v_lshlrev_b32_e32 v82, 16, v122
	v_and_b32_e32 v83, 0xffff0000, v122
	v_pk_fma_f32 v[74:75], v[74:75], v[80:81], v[82:83]
	v_lshlrev_b32_e32 v82, 16, v123
	v_cvt_pk_bf16_f32 v80, v74, v75
	v_lshlrev_b32_e32 v74, 16, v119
	v_and_b32_e32 v75, 0xffff0000, v119
	v_and_b32_e32 v83, 0xffff0000, v123
	global_store_dwordx4 v[90:91], v[86:89], off offset:256
	v_pk_fma_f32 v[74:75], v[76:77], v[74:75], v[82:83]
	s_waitcnt vmcnt(11)
	v_lshlrev_b32_e32 v76, 16, v124
	v_lshlrev_b64 v[86:87], 13, v[134:135]
	v_cvt_pk_bf16_f32 v81, v74, v75
	v_lshl_add_u64 v[74:75], s[10:11], 0, v[86:87]
	v_lshl_add_u64 v[74:75], v[74:75], 0, v[178:179]
	global_store_dwordx4 v[74:75], v[78:81], off
	v_and_b32_e32 v77, 0xffff0000, v124
	s_waitcnt vmcnt(11)
; #define PG8_GAS __attribute__((address_space(1)))
; __device__ __forceinline__ unsigned cvt_pk_bf16(float lo, float hi) { const f32x2c v = {lo, hi}; return __builtin_bit_cast(unsigned, __builtin_convertvector(v, bf16x2c)); }
; __device__ __forceinline__ float bf_lo(unsigned w) { return __uint_as_float(w << 16); }
; __device__ __forceinline__ float bf_hi(unsigned w) { return __uint_as_float(w & 0xffff0000u); }
; #define PG8_WAIT_V(n) asm volatile("s_waitcnt vmcnt(" #n ")" ::: "memory")
; #define PG8_BAR __builtin_amdgcn_s_barrier()
;     __device__ __forceinline__ void operator()(const f32x4 (&acc)[2][2][4][2], const Unit& un, int wr, int wc, int fr, int fq) const {
;     ...
;             for (int m = 0; m < 4; ++m)
; #pragma unroll
;                 for (int bj = 0; bj < 2; ++bj) { const u32x4 g = gg[m][bj], p = pp[m][bj]; const f32x4 v0 = acc[ai][bj][m][0], v1 = acc[ai][bj][m][1];
;                     u32x4 w; w.x = cvt_pk_bf16(v0[0] * bf_lo(g.x) + bf_lo(p.x), v0[1] * bf_hi(g.x) + bf_hi(p.x)); w.y = cvt_pk_bf16(v0[2] * bf_lo(g.y) + bf_lo(p.y), v0[3] * bf_hi(g.y) + bf_hi(p.y));
;                     w.z = cvt_pk_bf16(v1[0] * bf_lo(g.z) + bf_lo(p.z), v1[1] * bf_hi(g.z) + bf_hi(p.z)); w.w = cvt_pk_bf16(v1[2] * bf_lo(g.w) + bf_lo(p.w), v1[3] * bf_hi(g.w) + bf_hi(p.w));
;                     *(PG8_GAS u32x4*)(sa + (size_t)(row0 + ai * HALF + m * 16) * 4096 + col0 + bj * HALF) = w; }
; template <class Epi, class Sched, bool ALIGN_EPI = false, bool SP2 = false, bool F8 = false>
; __device__ __forceinline__ void gemm_phase(PG8_LAS unsigned char* lds, const Gemm g, const Sched& S, const Epi& E) {
;     ...
;         cur = nxt; cA = nA; cB = nB; ++ui;
;         if constexpr (ALIGN_EPI) { if (wr == 1) PG8_BAR; }
;     }
;     PG8_WAIT_V(0);
;     if constexpr (!ALIGN_EPI) { if (wr == 0) PG8_BAR; }
;     PG8_BAR;
	v_lshlrev_b32_e32 v78, 16, v128
	v_and_b32_e32 v79, 0xffff0000, v128
	v_pk_fma_f32 v[70:71], v[70:71], v[76:77], v[78:79]
	v_lshlrev_b32_e32 v76, 16, v125
	v_and_b32_e32 v77, 0xffff0000, v125
	v_lshlrev_b32_e32 v78, 16, v129
	v_and_b32_e32 v79, 0xffff0000, v129
	v_pk_fma_f32 v[72:73], v[72:73], v[76:77], v[78:79]
	v_cvt_pk_bf16_f32 v70, v70, v71
	v_cvt_pk_bf16_f32 v71, v72, v73
	v_lshlrev_b32_e32 v72, 16, v126
	v_and_b32_e32 v73, 0xffff0000, v126
	v_lshlrev_b32_e32 v76, 16, v130
	v_and_b32_e32 v77, 0xffff0000, v130
	v_pk_fma_f32 v[62:63], v[62:63], v[72:73], v[76:77]
	v_lshlrev_b32_e32 v76, 16, v131
	v_cvt_pk_bf16_f32 v72, v62, v63
	v_lshlrev_b32_e32 v62, 16, v127
	v_and_b32_e32 v63, 0xffff0000, v127
	v_and_b32_e32 v77, 0xffff0000, v131
	v_pk_fma_f32 v[62:63], v[64:65], v[62:63], v[76:77]
	s_waitcnt vmcnt(10)
	v_lshlrev_b32_e32 v64, 16, v30
	v_cvt_pk_bf16_f32 v73, v62, v63
	global_store_dwordx4 v[74:75], v[70:73], off offset:256
	v_and_b32_e32 v65, 0xffff0000, v30
	v_lshlrev_b32_e32 v30, 16, v31
	s_waitcnt vmcnt(10)
	v_lshlrev_b32_e32 v70, 16, v26
	v_and_b32_e32 v71, 0xffff0000, v26
	v_pk_fma_f32 v[64:65], v[66:67], v[64:65], v[70:71]
	v_and_b32_e32 v31, 0xffff0000, v31
	v_cvt_pk_bf16_f32 v26, v64, v65
	v_lshlrev_b32_e32 v64, 16, v27
	v_and_b32_e32 v65, 0xffff0000, v27
	v_pk_fma_f32 v[30:31], v[68:69], v[30:31], v[64:65]
	v_lshlrev_b32_e32 v64, 16, v28
	v_cvt_pk_bf16_f32 v27, v30, v31
	v_lshlrev_b32_e32 v30, 16, v32
	v_and_b32_e32 v31, 0xffff0000, v32
	v_and_b32_e32 v65, 0xffff0000, v28
	v_pk_fma_f32 v[30:31], v[58:59], v[30:31], v[64:65]
	v_lshlrev_b32_e32 v32, 16, v29
	v_cvt_pk_bf16_f32 v28, v30, v31
	v_lshlrev_b32_e32 v30, 16, v33
	v_and_b32_e32 v31, 0xffff0000, v33
	v_and_b32_e32 v33, 0xffff0000, v29
	v_lshlrev_b64 v[62:63], 13, v[136:137]
	v_pk_fma_f32 v[30:31], v[60:61], v[30:31], v[32:33]
	s_nop 0
	v_cvt_pk_bf16_f32 v29, v30, v31
	v_lshl_add_u64 v[30:31], s[10:11], 0, v[62:63]
	v_lshl_add_u64 v[30:31], v[30:31], 0, v[178:179]
	global_store_dwordx4 v[30:31], v[26:29], off
	s_waitcnt vmcnt(10)
	s_nop 0
	v_lshlrev_b32_e32 v26, 16, v22
	v_and_b32_e32 v27, 0xffff0000, v22
	s_waitcnt vmcnt(9)
	v_lshlrev_b32_e32 v28, 16, v18
	v_and_b32_e32 v29, 0xffff0000, v18
	v_pk_fma_f32 v[26:27], v[54:55], v[26:27], v[28:29]
	v_lshlrev_b32_e32 v22, 16, v23
	v_cvt_pk_bf16_f32 v18, v26, v27
	v_and_b32_e32 v23, 0xffff0000, v23
	v_lshlrev_b32_e32 v26, 16, v19
	v_and_b32_e32 v27, 0xffff0000, v19
	v_pk_fma_f32 v[22:23], v[56:57], v[22:23], v[26:27]
	v_lshlrev_b32_e32 v26, 16, v20
	v_cvt_pk_bf16_f32 v19, v22, v23
	v_lshlrev_b32_e32 v22, 16, v24
	v_and_b32_e32 v23, 0xffff0000, v24
	v_and_b32_e32 v27, 0xffff0000, v20
	v_pk_fma_f32 v[22:23], v[46:47], v[22:23], v[26:27]
	v_lshlrev_b32_e32 v24, 16, v21
	v_cvt_pk_bf16_f32 v20, v22, v23
	v_lshlrev_b32_e32 v22, 16, v25
	v_and_b32_e32 v23, 0xffff0000, v25
	v_and_b32_e32 v25, 0xffff0000, v21
	v_pk_fma_f32 v[22:23], v[48:49], v[22:23], v[24:25]
	s_nop 0
	v_cvt_pk_bf16_f32 v21, v22, v23
	global_store_dwordx4 v[30:31], v[18:21], off offset:256
	s_waitcnt vmcnt(8)
	v_lshlrev_b32_e32 v22, 16, v10
	v_and_b32_e32 v23, 0xffff0000, v10
	v_lshlrev_b32_e32 v20, 16, v14
	v_and_b32_e32 v21, 0xffff0000, v14
	v_pk_fma_f32 v[20:21], v[50:51], v[20:21], v[22:23]
	v_lshlrev_b32_e32 v14, 16, v15
	v_cvt_pk_bf16_f32 v10, v20, v21
	v_and_b32_e32 v15, 0xffff0000, v15
	v_lshlrev_b32_e32 v20, 16, v11
	v_and_b32_e32 v21, 0xffff0000, v11
	v_pk_fma_f32 v[14:15], v[52:53], v[14:15], v[20:21]
	v_lshlrev_b32_e32 v20, 16, v12
	v_cvt_pk_bf16_f32 v11, v14, v15
	v_lshlrev_b32_e32 v14, 16, v16
	v_and_b32_e32 v15, 0xffff0000, v16
	v_and_b32_e32 v21, 0xffff0000, v12
	v_pk_fma_f32 v[14:15], v[42:43], v[14:15], v[20:21]
	v_lshlrev_b32_e32 v16, 16, v13
	v_cvt_pk_bf16_f32 v12, v14, v15
	v_lshlrev_b32_e32 v14, 16, v17
	v_and_b32_e32 v15, 0xffff0000, v17
	v_and_b32_e32 v17, 0xffff0000, v13
	v_lshlrev_b64 v[18:19], 13, v[98:99]
	v_pk_fma_f32 v[14:15], v[44:45], v[14:15], v[16:17]
	s_nop 0
	v_cvt_pk_bf16_f32 v13, v14, v15
	v_lshl_add_u64 v[14:15], s[10:11], 0, v[18:19]
	v_lshl_add_u64 v[14:15], v[14:15], 0, v[178:179]
	global_store_dwordx4 v[14:15], v[10:13], off
	s_waitcnt vmcnt(8)
	s_nop 0
	v_lshlrev_b32_e32 v10, 16, v6
	v_and_b32_e32 v11, 0xffff0000, v6
	s_waitcnt vmcnt(7)
	v_lshlrev_b32_e32 v12, 16, v2
	v_and_b32_e32 v13, 0xffff0000, v2
	v_pk_fma_f32 v[10:11], v[38:39], v[10:11], v[12:13]
	v_lshlrev_b32_e32 v6, 16, v7
	v_cvt_pk_bf16_f32 v2, v10, v11
	v_and_b32_e32 v7, 0xffff0000, v7
	v_lshlrev_b32_e32 v10, 16, v3
	v_and_b32_e32 v11, 0xffff0000, v3
	v_pk_fma_f32 v[6:7], v[40:41], v[6:7], v[10:11]
	v_lshlrev_b32_e32 v10, 16, v4
	v_cvt_pk_bf16_f32 v3, v6, v7
	v_lshlrev_b32_e32 v6, 16, v8
	v_and_b32_e32 v7, 0xffff0000, v8
	v_and_b32_e32 v11, 0xffff0000, v4
	v_pk_fma_f32 v[6:7], v[34:35], v[6:7], v[10:11]
	v_lshlrev_b32_e32 v8, 16, v5
	v_cvt_pk_bf16_f32 v4, v6, v7
	v_lshlrev_b32_e32 v6, 16, v9
	v_and_b32_e32 v7, 0xffff0000, v9
	v_and_b32_e32 v9, 0xffff0000, v5
	v_pk_fma_f32 v[6:7], v[36:37], v[6:7], v[8:9]
	s_nop 0
	v_cvt_pk_bf16_f32 v5, v6, v7
	global_store_dwordx4 v[14:15], v[2:5], off offset:256
	s_cbranch_vccz .LBB0_627
	s_waitcnt vmcnt(0)
	s_cmpk_gt_u32 s4, 0xff
	s_cbranch_scc1 .LBB0_634
	s_barrier

; #define PG8_STAGE(bufoff, gbase, voff) do { _Pragma("unroll") for (int _i = 0; _i < 2; ++_i) \
;         __builtin_amdgcn_global_load_lds((const unsigned*)((const char*)(gbase) + (voff)[_i]), (PG8_LAS unsigned*)(lds + (bufoff) + ldsw + _i * 8192), 16, 0, 0); } while (0)
; #define PG8_LDA(dst, b, h) do { _Pragma("unroll") for (int m = 0; m < 4; ++m) _Pragma("unroll") for (int k = 0; k < 2; ++k) dst[m][k] = *(const PG8_LAS bf16x8*)(lds + PG8_SA(b, h) + aoff + m * 2048 + k * 1024); } while (0)
; #define PG8_LDB(dst, b, h) do { _Pragma("unroll") for (int n = 0; n < 2; ++n) _Pragma("unroll") for (int k = 0; k < 2; ++k) dst[n][k] = *(const PG8_LAS bf16x8*)(lds + PG8_SB(b, h) + boff + n * 2048 + k * 1024); } while (0)
; #define PG8_WAIT_V(n) asm volatile("s_waitcnt vmcnt(" #n ")" ::: "memory")
; #define PG8_WAIT_L(n) asm volatile("s_waitcnt lgkmcnt(" #n ")" ::: "memory")
; #define PG8_BAR __builtin_amdgcn_s_barrier()
; #define PG8_SCHED __builtin_amdgcn_sched_barrier(0)
; template <class Epi, class Sched, bool ALIGN_EPI = false, bool SP2 = false, bool F8 = false>
; __device__ __forceinline__ void gemm_phase(PG8_LAS unsigned char* lds, const Gemm g, const Sched& S, const Epi& E) {
;     ...
;             PG8_LDB(B0, 0, 0); PG8_LDB(B1, 0, 1); PG8_SCHED; PG8_LDA(At, 0, 0); PG8_STAGE(PG8_SA(1, 1), a1 + hA, voffA);
;             PG8_WAIT_V(8); PG8_WAIT_L(0); PG8_BAR; PG8_MMA(0, 0, At, B0); PG8_MMA(0, 1, At, B1); PG8_BAR; PG8_SCHED;
;             PG8_LDA(At, 0, 1); PG8_STAGE(PG8_SB(0, 0), b2, voffB); PG8_STAGE(PG8_SB(0, 1), b2 + hB, voffB); PG8_STAGE(PG8_SA(0, 0), a2, voffA);
;             PG8_WAIT_V(8); PG8_WAIT_L(0); PG8_BAR; PG8_MMA(1, 0, At, B0); PG8_MMA(1, 1, At, B1); PG8_BAR; PG8_SCHED;
.LBB0_689:
	ds_read_b128 v[130:133], v210
	ds_read_b128 v[134:137], v210 offset:1024
	ds_read_b128 v[138:141], v210 offset:2048
	ds_read_b128 v[142:145], v210 offset:3072
	ds_read_b128 v[146:149], v211
	ds_read_b128 v[150:153], v211 offset:1024
	ds_read_b128 v[154:157], v211 offset:2048
	ds_read_b128 v[158:161], v211 offset:3072
	s_add_u32 s38, s36, 0xfff00080
	s_addc_u32 s39, s37, -1
	s_cmp_eq_u32 s61, 60
	s_cselect_b32 s41, s17, s39
	s_cselect_b32 s40, s20, s38
	s_cselect_b32 s39, s25, s60
	s_cselect_b32 s38, s27, s35
	v_lshl_add_u64 v[218:219], s[36:37], 0, v[188:189]
	s_add_i32 m0, s33, 0xc000
	ds_read_b128 v[162:165], v212
	ds_read_b128 v[166:169], v212 offset:1024
	ds_read_b128 v[170:173], v212 offset:2048
	ds_read_b128 v[174:177], v212 offset:3072
	ds_read_b128 v[194:197], v212 offset:4096
	ds_read_b128 v[198:201], v212 offset:5120
	ds_read_b128 v[202:205], v212 offset:6144
	ds_read_b128 v[214:217], v212 offset:7168
	global_load_lds_dwordx4 v[218:219], off
	v_lshl_add_u64 v[218:219], s[36:37], 0, v[186:187]
	s_add_i32 m0, s33, 0xe000
	s_nop 0
	global_load_lds_dwordx4 v[218:219], off
	s_setprio 1
	s_waitcnt vmcnt(8)
	s_waitcnt lgkmcnt(0)
	s_barrier
	v_mfma_f32_16x16x32_bf16 v[126:129], v[130:133], v[162:165], v[126:129]
	v_mfma_f32_16x16x32_bf16 v[122:125], v[138:141], v[162:165], v[122:125]
	v_mfma_f32_16x16x32_bf16 v[110:113], v[130:133], v[170:173], v[110:113]
	v_mfma_f32_16x16x32_bf16 v[106:109], v[138:141], v[170:173], v[106:109]
	v_mfma_f32_16x16x32_bf16 v[94:97], v[130:133], v[194:197], v[94:97]
	v_mfma_f32_16x16x32_bf16 v[90:93], v[138:141], v[194:197], v[90:93]
	v_mfma_f32_16x16x32_bf16 v[78:81], v[130:133], v[202:205], v[78:81]
	v_mfma_f32_16x16x32_bf16 v[74:77], v[138:141], v[202:205], v[74:77]
	v_mfma_f32_16x16x32_bf16 v[126:129], v[134:137], v[166:169], v[126:129]
	v_mfma_f32_16x16x32_bf16 v[122:125], v[142:145], v[166:169], v[122:125]
	v_mfma_f32_16x16x32_bf16 v[110:113], v[134:137], v[174:177], v[110:113]
	v_mfma_f32_16x16x32_bf16 v[106:109], v[142:145], v[174:177], v[106:109]
	v_mfma_f32_16x16x32_bf16 v[94:97], v[134:137], v[198:201], v[94:97]
	v_mfma_f32_16x16x32_bf16 v[90:93], v[142:145], v[198:201], v[90:93]
	v_mfma_f32_16x16x32_bf16 v[78:81], v[134:137], v[214:217], v[78:81]
	v_mfma_f32_16x16x32_bf16 v[74:77], v[142:145], v[214:217], v[74:77]
	v_mfma_f32_16x16x32_bf16 v[118:121], v[146:149], v[162:165], v[118:121]
	v_mfma_f32_16x16x32_bf16 v[114:117], v[154:157], v[162:165], v[114:117]
	v_mfma_f32_16x16x32_bf16 v[102:105], v[146:149], v[170:173], v[102:105]
	v_mfma_f32_16x16x32_bf16 v[98:101], v[154:157], v[170:173], v[98:101]
	v_mfma_f32_16x16x32_bf16 v[86:89], v[146:149], v[194:197], v[86:89]
	v_mfma_f32_16x16x32_bf16 v[82:85], v[154:157], v[194:197], v[82:85]
	v_mfma_f32_16x16x32_bf16 v[70:73], v[146:149], v[202:205], v[70:73]
	v_mfma_f32_16x16x32_bf16 v[66:69], v[154:157], v[202:205], v[66:69]
	v_mfma_f32_16x16x32_bf16 v[118:121], v[150:153], v[166:169], v[118:121]
	v_mfma_f32_16x16x32_bf16 v[114:117], v[158:161], v[166:169], v[114:117]
	v_mfma_f32_16x16x32_bf16 v[102:105], v[150:153], v[174:177], v[102:105]
	v_mfma_f32_16x16x32_bf16 v[98:101], v[158:161], v[174:177], v[98:101]
	v_mfma_f32_16x16x32_bf16 v[86:89], v[150:153], v[198:201], v[86:89]
	v_mfma_f32_16x16x32_bf16 v[82:85], v[158:161], v[198:201], v[82:85]
	v_mfma_f32_16x16x32_bf16 v[70:73], v[150:153], v[214:217], v[70:73]
	v_mfma_f32_16x16x32_bf16 v[66:69], v[158:161], v[214:217], v[66:69]
	s_barrier
	s_setprio 0
	s_add_i32 s62, s56, s19
	v_lshl_add_u64 v[218:219], s[38:39], 0, v[180:181]
	s_mov_b32 m0, s62
	ds_read_b128 v[162:165], v212 offset:16384
	ds_read_b128 v[166:169], v212 offset:17408
	ds_read_b128 v[170:173], v212 offset:18432
	ds_read_b128 v[174:177], v212 offset:19456
	ds_read_b128 v[194:197], v212 offset:20480
	ds_read_b128 v[198:201], v212 offset:21504
	ds_read_b128 v[202:205], v212 offset:22528
	ds_read_b128 v[214:217], v212 offset:23552
	global_load_lds_dwordx4 v[218:219], off
	s_add_i32 m0, s62, 0x2000
	s_add_u32 s62, s38, 0x100000
	v_lshl_add_u64 v[220:221], s[38:39], 0, v[184:185]
	s_addc_u32 s63, s39, 0
	s_add_i32 s64, s57, s19
	global_load_lds_dwordx4 v[220:221], off
	v_lshl_add_u64 v[222:223], s[62:63], 0, v[180:181]
	s_mov_b32 m0, s64
	v_lshl_add_u64 v[224:225], s[40:41], 0, v[182:183]
	global_load_lds_dwordx4 v[222:223], off
	v_lshl_add_u64 v[222:223], s[62:63], 0, v[184:185]
	s_add_i32 m0, s64, 0x2000
	s_nop 0
	global_load_lds_dwordx4 v[222:223], off
	v_lshl_add_u64 v[222:223], s[40:41], 0, v[178:179]
	s_mov_b32 m0, s33
	s_nop 0
	global_load_lds_dwordx4 v[222:223], off
	s_mov_b32 m0, s42
	s_nop 0
	global_load_lds_dwordx4 v[224:225], off
	s_setprio 1
	s_waitcnt vmcnt(8)
	s_waitcnt lgkmcnt(0)
	s_barrier
; #define PG8_STAGE(bufoff, gbase, voff) do { _Pragma("unroll") for (int _i = 0; _i < 2; ++_i) \
;         __builtin_amdgcn_global_load_lds((const unsigned*)((const char*)(gbase) + (voff)[_i]), (PG8_LAS unsigned*)(lds + (bufoff) + ldsw + _i * 8192), 16, 0, 0); } while (0)
; #define PG8_LDA(dst, b, h) do { _Pragma("unroll") for (int m = 0; m < 4; ++m) _Pragma("unroll") for (int k = 0; k < 2; ++k) dst[m][k] = *(const PG8_LAS bf16x8*)(lds + PG8_SA(b, h) + aoff + m * 2048 + k * 1024); } while (0)
; #define PG8_LDB(dst, b, h) do { _Pragma("unroll") for (int n = 0; n < 2; ++n) _Pragma("unroll") for (int k = 0; k < 2; ++k) dst[n][k] = *(const PG8_LAS bf16x8*)(lds + PG8_SB(b, h) + boff + n * 2048 + k * 1024); } while (0)
; #define PG8_WAIT_V(n) asm volatile("s_waitcnt vmcnt(" #n ")" ::: "memory")
; #define PG8_WAIT_L(n) asm volatile("s_waitcnt lgkmcnt(" #n ")" ::: "memory")
; #define PG8_BAR __builtin_amdgcn_s_barrier()
; #define PG8_SCHED __builtin_amdgcn_sched_barrier(0)
; template <class Epi, class Sched, bool ALIGN_EPI = false, bool SP2 = false, bool F8 = false>
; __device__ __forceinline__ void gemm_phase(PG8_LAS unsigned char* lds, const Gemm g, const Sched& S, const Epi& E) {
;     ...
;             PG8_WAIT_V(8); PG8_WAIT_L(0); PG8_BAR; PG8_MMA(1, 0, At, B0); PG8_MMA(1, 1, At, B1); PG8_BAR; PG8_SCHED;
;             PG8_LDB(B0, 1, 0); PG8_LDB(B1, 1, 1); PG8_SCHED; PG8_LDA(At, 1, 0); PG8_STAGE(PG8_SA(0, 1), a2 + hA, voffA);
;             PG8_WAIT_V(8); PG8_WAIT_L(0); PG8_BAR; PG8_MMA(0, 0, At, B0); PG8_MMA(0, 1, At, B1); PG8_BAR; PG8_SCHED;
	v_mfma_f32_16x16x32_bf16 v[62:65], v[130:133], v[162:165], v[62:65]
	v_mfma_f32_16x16x32_bf16 v[58:61], v[138:141], v[162:165], v[58:61]
	v_mfma_f32_16x16x32_bf16 v[46:49], v[130:133], v[170:173], v[46:49]
	v_mfma_f32_16x16x32_bf16 v[42:45], v[138:141], v[170:173], v[42:45]
	v_mfma_f32_16x16x32_bf16 v[30:33], v[130:133], v[194:197], v[30:33]
	v_mfma_f32_16x16x32_bf16 v[26:29], v[138:141], v[194:197], v[26:29]
	v_mfma_f32_16x16x32_bf16 v[14:17], v[130:133], v[202:205], v[14:17]
	v_mfma_f32_16x16x32_bf16 v[10:13], v[138:141], v[202:205], v[10:13]
	v_mfma_f32_16x16x32_bf16 v[62:65], v[134:137], v[166:169], v[62:65]
	v_mfma_f32_16x16x32_bf16 v[58:61], v[142:145], v[166:169], v[58:61]
	v_mfma_f32_16x16x32_bf16 v[46:49], v[134:137], v[174:177], v[46:49]
	v_mfma_f32_16x16x32_bf16 v[42:45], v[142:145], v[174:177], v[42:45]
	v_mfma_f32_16x16x32_bf16 v[30:33], v[134:137], v[198:201], v[30:33]
	v_mfma_f32_16x16x32_bf16 v[26:29], v[142:145], v[198:201], v[26:29]
	v_mfma_f32_16x16x32_bf16 v[14:17], v[134:137], v[214:217], v[14:17]
	v_mfma_f32_16x16x32_bf16 v[10:13], v[142:145], v[214:217], v[10:13]
	v_mfma_f32_16x16x32_bf16 v[54:57], v[146:149], v[162:165], v[54:57]
	v_mfma_f32_16x16x32_bf16 v[50:53], v[154:157], v[162:165], v[50:53]
	v_mfma_f32_16x16x32_bf16 v[38:41], v[146:149], v[170:173], v[38:41]
	v_mfma_f32_16x16x32_bf16 v[34:37], v[154:157], v[170:173], v[34:37]
	v_mfma_f32_16x16x32_bf16 v[22:25], v[146:149], v[194:197], v[22:25]
	v_mfma_f32_16x16x32_bf16 v[18:21], v[154:157], v[194:197], v[18:21]
	v_mfma_f32_16x16x32_bf16 v[6:9], v[146:149], v[202:205], v[6:9]
	v_mfma_f32_16x16x32_bf16 v[2:5], v[154:157], v[202:205], v[2:5]
	v_mfma_f32_16x16x32_bf16 v[54:57], v[150:153], v[166:169], v[54:57]
	v_mfma_f32_16x16x32_bf16 v[50:53], v[158:161], v[166:169], v[50:53]
	v_mfma_f32_16x16x32_bf16 v[38:41], v[150:153], v[174:177], v[38:41]
	v_mfma_f32_16x16x32_bf16 v[34:37], v[158:161], v[174:177], v[34:37]
	v_mfma_f32_16x16x32_bf16 v[22:25], v[150:153], v[198:201], v[22:25]
	v_mfma_f32_16x16x32_bf16 v[18:21], v[158:161], v[198:201], v[18:21]
	v_mfma_f32_16x16x32_bf16 v[6:9], v[150:153], v[214:217], v[6:9]
	v_mfma_f32_16x16x32_bf16 v[2:5], v[158:161], v[214:217], v[2:5]
	s_barrier
	s_setprio 0
	s_add_i32 s62, 0, 0x18000
	s_add_i32 s63, 0, 0x1c000
	v_add_u32_e32 v142, s62, v207
	v_add_u32_e32 v158, s63, v207
	ds_read_b128 v[130:133], v142
	ds_read_b128 v[134:137], v142 offset:1024
	ds_read_b128 v[138:141], v142 offset:2048
	ds_read_b128 v[142:145], v142 offset:3072
	ds_read_b128 v[146:149], v158
	ds_read_b128 v[150:153], v158 offset:1024
	ds_read_b128 v[154:157], v158 offset:2048
	ds_read_b128 v[158:161], v158 offset:3072
	s_add_u32 s40, s40, 0x100000
	s_addc_u32 s41, s41, 0
	s_mov_b32 m0, s43
	v_lshl_add_u64 v[226:227], s[40:41], 0, v[178:179]
	ds_read_b128 v[162:165], v212 offset:32768
	ds_read_b128 v[166:169], v212 offset:33792
	ds_read_b128 v[170:173], v212 offset:34816
	ds_read_b128 v[174:177], v212 offset:35840
	ds_read_b128 v[194:197], v212 offset:36864
	ds_read_b128 v[198:201], v212 offset:37888
	ds_read_b128 v[202:205], v212 offset:38912
	ds_read_b128 v[214:217], v212 offset:39936
	global_load_lds_dwordx4 v[226:227], off
	v_lshl_add_u64 v[226:227], s[40:41], 0, v[182:183]
	s_mov_b32 m0, s44
	s_nop 0
	global_load_lds_dwordx4 v[226:227], off
	s_setprio 1
	s_waitcnt vmcnt(8)
	s_waitcnt lgkmcnt(0)
	s_barrier
	v_mfma_f32_16x16x32_bf16 v[126:129], v[130:133], v[162:165], v[126:129]
	v_mfma_f32_16x16x32_bf16 v[122:125], v[138:141], v[162:165], v[122:125]
	v_mfma_f32_16x16x32_bf16 v[110:113], v[130:133], v[170:173], v[110:113]
	v_mfma_f32_16x16x32_bf16 v[106:109], v[138:141], v[170:173], v[106:109]
	v_mfma_f32_16x16x32_bf16 v[94:97], v[130:133], v[194:197], v[94:97]
	v_mfma_f32_16x16x32_bf16 v[90:93], v[138:141], v[194:197], v[90:93]
	v_mfma_f32_16x16x32_bf16 v[78:81], v[130:133], v[202:205], v[78:81]
	v_mfma_f32_16x16x32_bf16 v[74:77], v[138:141], v[202:205], v[74:77]
	v_mfma_f32_16x16x32_bf16 v[126:129], v[134:137], v[166:169], v[126:129]
	v_mfma_f32_16x16x32_bf16 v[122:125], v[142:145], v[166:169], v[122:125]
	v_mfma_f32_16x16x32_bf16 v[110:113], v[134:137], v[174:177], v[110:113]
	v_mfma_f32_16x16x32_bf16 v[106:109], v[142:145], v[174:177], v[106:109]
	v_mfma_f32_16x16x32_bf16 v[94:97], v[134:137], v[198:201], v[94:97]
	v_mfma_f32_16x16x32_bf16 v[90:93], v[142:145], v[198:201], v[90:93]
	v_mfma_f32_16x16x32_bf16 v[78:81], v[134:137], v[214:217], v[78:81]
	v_mfma_f32_16x16x32_bf16 v[74:77], v[142:145], v[214:217], v[74:77]
	v_mfma_f32_16x16x32_bf16 v[118:121], v[146:149], v[162:165], v[118:121]
	v_mfma_f32_16x16x32_bf16 v[114:117], v[154:157], v[162:165], v[114:117]
	v_mfma_f32_16x16x32_bf16 v[102:105], v[146:149], v[170:173], v[102:105]
	v_mfma_f32_16x16x32_bf16 v[98:101], v[154:157], v[170:173], v[98:101]
	v_mfma_f32_16x16x32_bf16 v[86:89], v[146:149], v[194:197], v[86:89]
	v_mfma_f32_16x16x32_bf16 v[82:85], v[154:157], v[194:197], v[82:85]
	v_mfma_f32_16x16x32_bf16 v[70:73], v[146:149], v[202:205], v[70:73]
	v_mfma_f32_16x16x32_bf16 v[66:69], v[154:157], v[202:205], v[66:69]
	v_mfma_f32_16x16x32_bf16 v[118:121], v[150:153], v[166:169], v[118:121]
	v_mfma_f32_16x16x32_bf16 v[114:117], v[158:161], v[166:169], v[114:117]
	v_mfma_f32_16x16x32_bf16 v[102:105], v[150:153], v[174:177], v[102:105]
	v_mfma_f32_16x16x32_bf16 v[98:101], v[158:161], v[174:177], v[98:101]
	v_mfma_f32_16x16x32_bf16 v[86:89], v[150:153], v[198:201], v[86:89]
	v_mfma_f32_16x16x32_bf16 v[82:85], v[158:161], v[198:201], v[82:85]
	v_mfma_f32_16x16x32_bf16 v[70:73], v[150:153], v[214:217], v[70:73]
	v_mfma_f32_16x16x32_bf16 v[66:69], v[158:161], v[214:217], v[66:69]
	s_barrier
; #define PG8_STAGE(bufoff, gbase, voff) do { _Pragma("unroll") for (int _i = 0; _i < 2; ++_i) \
;         __builtin_amdgcn_global_load_lds((const unsigned*)((const char*)(gbase) + (voff)[_i]), (PG8_LAS unsigned*)(lds + (bufoff) + ldsw + _i * 8192), 16, 0, 0); } while (0)
; #define PG8_LDA(dst, b, h) do { _Pragma("unroll") for (int m = 0; m < 4; ++m) _Pragma("unroll") for (int k = 0; k < 2; ++k) dst[m][k] = *(const PG8_LAS bf16x8*)(lds + PG8_SA(b, h) + aoff + m * 2048 + k * 1024); } while (0)
; #define PG8_WAIT_V(n) asm volatile("s_waitcnt vmcnt(" #n ")" ::: "memory")
; #define PG8_WAIT_L(n) asm volatile("s_waitcnt lgkmcnt(" #n ")" ::: "memory")
; #define PG8_BAR __builtin_amdgcn_s_barrier()
; #define PG8_SCHED __builtin_amdgcn_sched_barrier(0)
;     __device__ __forceinline__ void run(const f32x4 (&acc)[2][2][4][2], const Unit& un, int wr, int wc, int fr, int fq, PG8_LAS unsigned char* xl) const {
;         asm volatile("" : "+v"(fr));
;         const int rloc = wr * 64 + fr, col0 = un.pn * BM + wc * 32 + 8 * fq;
;         const float* bs = un.pm < split_pm ? base + (size_t)un.pm * BM * 4096 : base2 + (size_t)(un.pm - split_pm) * BM * 4096;
; template <class Epi, class Sched, bool ALIGN_EPI = false, bool SP2 = false, bool F8 = false>
; __device__ __forceinline__ void gemm_phase(PG8_LAS unsigned char* lds, const Gemm g, const Sched& S, const Epi& E) {
;     ...
;             PG8_LDA(At, 1, 1); PG8_STAGE(PG8_SB(1, 0), b3, voffB); PG8_STAGE(PG8_SB(1, 1), b3 + hB, voffB); PG8_STAGE(PG8_SA(1, 0), a3, voffA);
;             PG8_WAIT_V(8); PG8_WAIT_L(0); PG8_BAR; PG8_MMA(1, 0, At, B0); PG8_MMA(1, 1, At, B1); PG8_BAR; PG8_SCHED;
	s_setprio 0
	s_add_i32 s40, s62, s19
	v_lshl_add_u64 v[218:219], v[218:219], 0, s[22:23]
	s_mov_b32 m0, s40
	ds_read_b128 v[162:165], v212 offset:49152
	ds_read_b128 v[166:169], v212 offset:50176
	ds_read_b128 v[170:173], v212 offset:51200
	ds_read_b128 v[174:177], v212 offset:52224
	ds_read_b128 v[194:197], v212 offset:53248
	ds_read_b128 v[198:201], v212 offset:54272
	ds_read_b128 v[202:205], v212 offset:55296
	ds_read_b128 v[214:217], v212 offset:56320
	global_load_lds_dwordx4 v[218:219], off
	s_add_i32 m0, s40, 0x2000
	s_add_u32 s38, s38, 0x100080
	v_lshl_add_u64 v[218:219], v[220:221], 0, s[22:23]
	s_addc_u32 s39, s39, 0
	s_add_i32 s40, s63, s19
	global_load_lds_dwordx4 v[218:219], off
	v_lshl_add_u64 v[218:219], s[38:39], 0, v[180:181]
	s_mov_b32 m0, s40
	s_nop 0
	global_load_lds_dwordx4 v[218:219], off
	v_lshl_add_u64 v[218:219], s[38:39], 0, v[184:185]
	s_add_i32 m0, s40, 0x2000
	s_nop 0
	global_load_lds_dwordx4 v[218:219], off
	v_lshl_add_u64 v[218:219], v[222:223], 0, s[22:23]
	s_mov_b32 m0, s50
	s_nop 0
	global_load_lds_dwordx4 v[218:219], off
	v_lshl_add_u64 v[218:219], v[224:225], 0, s[22:23]
	s_mov_b32 m0, s51
	s_nop 0
	global_load_lds_dwordx4 v[218:219], off
	s_setprio 1
	s_waitcnt vmcnt(8)
	s_waitcnt lgkmcnt(0)
	s_barrier
	v_mfma_f32_16x16x32_bf16 v[62:65], v[130:133], v[162:165], v[62:65]
	v_mfma_f32_16x16x32_bf16 v[58:61], v[138:141], v[162:165], v[58:61]
	v_mfma_f32_16x16x32_bf16 v[46:49], v[130:133], v[170:173], v[46:49]
	v_mfma_f32_16x16x32_bf16 v[42:45], v[138:141], v[170:173], v[42:45]
	v_mfma_f32_16x16x32_bf16 v[30:33], v[130:133], v[194:197], v[30:33]
	v_mfma_f32_16x16x32_bf16 v[26:29], v[138:141], v[194:197], v[26:29]
	v_mfma_f32_16x16x32_bf16 v[14:17], v[130:133], v[202:205], v[14:17]
	v_mfma_f32_16x16x32_bf16 v[10:13], v[138:141], v[202:205], v[10:13]
	v_mfma_f32_16x16x32_bf16 v[62:65], v[134:137], v[166:169], v[62:65]
	v_mfma_f32_16x16x32_bf16 v[58:61], v[142:145], v[166:169], v[58:61]
	v_mfma_f32_16x16x32_bf16 v[46:49], v[134:137], v[174:177], v[46:49]
	v_mfma_f32_16x16x32_bf16 v[42:45], v[142:145], v[174:177], v[42:45]
	v_mfma_f32_16x16x32_bf16 v[30:33], v[134:137], v[198:201], v[30:33]
	v_mfma_f32_16x16x32_bf16 v[26:29], v[142:145], v[198:201], v[26:29]
	v_mfma_f32_16x16x32_bf16 v[14:17], v[134:137], v[214:217], v[14:17]
	v_mfma_f32_16x16x32_bf16 v[10:13], v[142:145], v[214:217], v[10:13]
	v_mfma_f32_16x16x32_bf16 v[54:57], v[146:149], v[162:165], v[54:57]
	v_mfma_f32_16x16x32_bf16 v[50:53], v[154:157], v[162:165], v[50:53]
	v_mfma_f32_16x16x32_bf16 v[38:41], v[146:149], v[170:173], v[38:41]
	v_mfma_f32_16x16x32_bf16 v[34:37], v[154:157], v[170:173], v[34:37]
	v_mfma_f32_16x16x32_bf16 v[22:25], v[146:149], v[194:197], v[22:25]
	v_mfma_f32_16x16x32_bf16 v[18:21], v[154:157], v[194:197], v[18:21]
	v_mfma_f32_16x16x32_bf16 v[6:9], v[146:149], v[202:205], v[6:9]
	v_mfma_f32_16x16x32_bf16 v[2:5], v[154:157], v[202:205], v[2:5]
	v_mfma_f32_16x16x32_bf16 v[54:57], v[150:153], v[166:169], v[54:57]
	v_mfma_f32_16x16x32_bf16 v[50:53], v[158:161], v[166:169], v[50:53]
	v_mfma_f32_16x16x32_bf16 v[38:41], v[150:153], v[174:177], v[38:41]
	v_mfma_f32_16x16x32_bf16 v[34:37], v[158:161], v[174:177], v[34:37]
	v_mfma_f32_16x16x32_bf16 v[22:25], v[150:153], v[198:201], v[22:25]
	v_mfma_f32_16x16x32_bf16 v[18:21], v[158:161], v[198:201], v[18:21]
	v_mfma_f32_16x16x32_bf16 v[6:9], v[150:153], v[214:217], v[6:9]
	v_mfma_f32_16x16x32_bf16 v[2:5], v[158:161], v[214:217], v[2:5]
	s_barrier
	s_setprio 0
	s_add_i32 s61, s61, 2
	s_add_u32 s35, s35, 0x100
	s_addc_u32 s60, s60, 0
	s_add_u32 s36, s36, 0x100
	s_addc_u32 s37, s37, 0
	s_cmp_gt_u32 s61, 61
	s_cbranch_scc0 .LBB0_689
	v_mov_b32_e32 v214, v206
	s_cmp_gt_i32 s16, 63
	s_mov_b64 s[38:39], -1
	s_cbranch_scc0 .LBB0_692
	s_sub_i32 s20, s16, 64
	s_lshl_b64 s[36:37], s[20:21], 22
	s_add_u32 s36, s14, s36
	s_addc_u32 s37, s15, s37
	s_mov_b32 s17, s21
	s_mov_b64 s[38:39], 0

; #define PG8_STAGE(bufoff, gbase, voff) do { _Pragma("unroll") for (int _i = 0; _i < 2; ++_i) \
;         __builtin_amdgcn_global_load_lds((const unsigned*)((const char*)(gbase) + (voff)[_i]), (PG8_LAS unsigned*)(lds + (bufoff) + ldsw + _i * 8192), 16, 0, 0); } while (0)
; #define PG8_LDA(dst, b, h) do { _Pragma("unroll") for (int m = 0; m < 4; ++m) _Pragma("unroll") for (int k = 0; k < 2; ++k) dst[m][k] = *(const PG8_LAS bf16x8*)(lds + PG8_SA(b, h) + aoff + m * 2048 + k * 1024); } while (0)
; #define PG8_LDB(dst, b, h) do { _Pragma("unroll") for (int n = 0; n < 2; ++n) _Pragma("unroll") for (int k = 0; k < 2; ++k) dst[n][k] = *(const PG8_LAS bf16x8*)(lds + PG8_SB(b, h) + boff + n * 2048 + k * 1024); } while (0)
; #define PG8_WAIT_V(n) asm volatile("s_waitcnt vmcnt(" #n ")" ::: "memory")
; #define PG8_WAIT_L(n) asm volatile("s_waitcnt lgkmcnt(" #n ")" ::: "memory")
; #define PG8_BAR __builtin_amdgcn_s_barrier()
; #define PG8_SCHED __builtin_amdgcn_sched_barrier(0)
; template <class Epi, class Sched, bool ALIGN_EPI = false, bool SP2 = false, bool F8 = false>
; __device__ __forceinline__ void gemm_phase(PG8_LAS unsigned char* lds, const Gemm g, const Sched& S, const Epi& E) {
;     ...
;             PG8_LDB(B0, 0, 0); PG8_LDB(B1, 0, 1); PG8_SCHED; PG8_LDA(At, 0, 0); PG8_STAGE(PG8_SA(1, 1), a1 + hA, voffA);
;             PG8_WAIT_V(8); PG8_WAIT_L(0); PG8_BAR; PG8_MMA(0, 0, At, B0); PG8_MMA(0, 1, At, B1); PG8_BAR; PG8_SCHED;
;             PG8_LDA(At, 0, 1); PG8_STAGE(PG8_SB(0, 0), b2, voffB); PG8_STAGE(PG8_SB(0, 1), b2 + hB, voffB); PG8_STAGE(PG8_SA(0, 0), a2, voffA);
;             PG8_WAIT_V(8); PG8_WAIT_L(0); PG8_BAR; PG8_MMA(1, 0, At, B0); PG8_MMA(1, 1, At, B1); PG8_BAR; PG8_SCHED;
.LBB0_770:
	ds_read_b128 v[130:133], v241
	ds_read_b128 v[134:137], v241 offset:1024
	ds_read_b128 v[138:141], v241 offset:2048
	ds_read_b128 v[142:145], v241 offset:3072
	ds_read_b128 v[146:149], v242
	ds_read_b128 v[150:153], v242 offset:1024
	ds_read_b128 v[154:157], v242 offset:2048
	ds_read_b128 v[158:161], v242 offset:3072
	s_add_u32 s14, s12, 0xfff00080
	s_addc_u32 s15, s13, -1
	s_cmp_eq_u32 s80, 60
	s_cselect_b32 s17, s11, s15
	s_cselect_b32 s16, s63, s14
	s_cselect_b32 s15, s61, s79
	s_cselect_b32 s14, s77, s78
	v_lshl_add_u64 v[208:209], s[12:13], 0, v[188:189]
	s_add_i32 m0, s7, 0xc000
	ds_read_b128 v[162:165], v243
	ds_read_b128 v[166:169], v243 offset:1024
	ds_read_b128 v[170:173], v243 offset:2048
	ds_read_b128 v[174:177], v243 offset:3072
	ds_read_b128 v[192:195], v243 offset:4096
	ds_read_b128 v[196:199], v243 offset:5120
	ds_read_b128 v[200:203], v243 offset:6144
	ds_read_b128 v[204:207], v243 offset:7168
	global_load_lds_dwordx4 v[208:209], off
	v_lshl_add_u64 v[208:209], s[12:13], 0, v[186:187]
	s_add_i32 m0, s7, 0xe000
	s_nop 0
	global_load_lds_dwordx4 v[208:209], off
	s_setprio 1
	s_waitcnt vmcnt(8)
	s_waitcnt lgkmcnt(0)
	s_barrier
	v_mfma_f32_16x16x32_bf16 v[126:129], v[130:133], v[162:165], v[126:129]
	v_mfma_f32_16x16x32_bf16 v[90:93], v[138:141], v[162:165], v[90:93]
	v_mfma_f32_16x16x32_bf16 v[110:113], v[130:133], v[170:173], v[110:113]
	v_mfma_f32_16x16x32_bf16 v[86:89], v[138:141], v[170:173], v[86:89]
	v_mfma_f32_16x16x32_bf16 v[106:109], v[130:133], v[192:195], v[106:109]
	v_mfma_f32_16x16x32_bf16 v[82:85], v[138:141], v[192:195], v[82:85]
	v_mfma_f32_16x16x32_bf16 v[118:121], v[130:133], v[200:203], v[118:121]
	v_mfma_f32_16x16x32_bf16 v[122:125], v[138:141], v[200:203], v[122:125]
	v_mfma_f32_16x16x32_bf16 v[126:129], v[134:137], v[166:169], v[126:129]
	v_mfma_f32_16x16x32_bf16 v[90:93], v[142:145], v[166:169], v[90:93]
	v_mfma_f32_16x16x32_bf16 v[110:113], v[134:137], v[174:177], v[110:113]
	v_mfma_f32_16x16x32_bf16 v[86:89], v[142:145], v[174:177], v[86:89]
	v_mfma_f32_16x16x32_bf16 v[106:109], v[134:137], v[196:199], v[106:109]
	v_mfma_f32_16x16x32_bf16 v[82:85], v[142:145], v[196:199], v[82:85]
	v_mfma_f32_16x16x32_bf16 v[118:121], v[134:137], v[204:207], v[118:121]
	v_mfma_f32_16x16x32_bf16 v[122:125], v[142:145], v[204:207], v[122:125]
	v_mfma_f32_16x16x32_bf16 v[94:97], v[146:149], v[162:165], v[94:97]
	v_mfma_f32_16x16x32_bf16 v[66:69], v[154:157], v[162:165], v[66:69]
	v_mfma_f32_16x16x32_bf16 v[102:105], v[146:149], v[170:173], v[102:105]
	v_mfma_f32_16x16x32_bf16 v[78:81], v[154:157], v[170:173], v[78:81]
	v_mfma_f32_16x16x32_bf16 v[98:101], v[146:149], v[192:195], v[98:101]
	v_mfma_f32_16x16x32_bf16 v[74:77], v[154:157], v[192:195], v[74:77]
	v_mfma_f32_16x16x32_bf16 v[70:73], v[146:149], v[200:203], v[70:73]
	v_mfma_f32_16x16x32_bf16 v[58:61], v[154:157], v[200:203], v[58:61]
	v_mfma_f32_16x16x32_bf16 v[94:97], v[150:153], v[166:169], v[94:97]
	v_mfma_f32_16x16x32_bf16 v[66:69], v[158:161], v[166:169], v[66:69]
	v_mfma_f32_16x16x32_bf16 v[102:105], v[150:153], v[174:177], v[102:105]
	v_mfma_f32_16x16x32_bf16 v[78:81], v[158:161], v[174:177], v[78:81]
	v_mfma_f32_16x16x32_bf16 v[98:101], v[150:153], v[196:199], v[98:101]
	v_mfma_f32_16x16x32_bf16 v[74:77], v[158:161], v[196:199], v[74:77]
	v_mfma_f32_16x16x32_bf16 v[70:73], v[150:153], v[204:207], v[70:73]
	v_mfma_f32_16x16x32_bf16 v[58:61], v[158:161], v[204:207], v[58:61]
	s_barrier
	s_setprio 0
	s_add_i32 s81, s97, s6
	v_lshl_add_u64 v[208:209], s[14:15], 0, v[180:181]
	s_mov_b32 m0, s81
	ds_read_b128 v[162:165], v243 offset:16384
	ds_read_b128 v[166:169], v243 offset:17408
	ds_read_b128 v[170:173], v243 offset:18432
	ds_read_b128 v[174:177], v243 offset:19456
	ds_read_b128 v[192:195], v243 offset:20480
	ds_read_b128 v[196:199], v243 offset:21504
	ds_read_b128 v[200:203], v243 offset:22528
	ds_read_b128 v[204:207], v243 offset:23552
	global_load_lds_dwordx4 v[208:209], off
	s_add_i32 m0, s81, 0x2000
	s_add_u32 vcc_lo, s14, 0x100000
	v_lshl_add_u64 v[210:211], s[14:15], 0, v[184:185]
	s_addc_u32 vcc_hi, s15, 0
	s_add_i32 s81, s86, s6
	global_load_lds_dwordx4 v[210:211], off
	v_lshl_add_u64 v[212:213], vcc, 0, v[180:181]
	s_mov_b32 m0, s81
	v_lshl_add_u64 v[214:215], s[16:17], 0, v[182:183]
	global_load_lds_dwordx4 v[212:213], off
	v_lshl_add_u64 v[212:213], vcc, 0, v[184:185]
	s_add_i32 m0, s81, 0x2000
	s_nop 0
	global_load_lds_dwordx4 v[212:213], off
	v_lshl_add_u64 v[212:213], s[16:17], 0, v[178:179]
	s_mov_b32 m0, s7
	s_nop 0
	global_load_lds_dwordx4 v[212:213], off
	s_mov_b32 m0, s18
	s_nop 0
	global_load_lds_dwordx4 v[214:215], off
	s_setprio 1
	s_waitcnt vmcnt(8)
	s_waitcnt lgkmcnt(0)
	s_barrier
; #define PG8_STAGE(bufoff, gbase, voff) do { _Pragma("unroll") for (int _i = 0; _i < 2; ++_i) \
;         __builtin_amdgcn_global_load_lds((const unsigned*)((const char*)(gbase) + (voff)[_i]), (PG8_LAS unsigned*)(lds + (bufoff) + ldsw + _i * 8192), 16, 0, 0); } while (0)
; #define PG8_LDA(dst, b, h) do { _Pragma("unroll") for (int m = 0; m < 4; ++m) _Pragma("unroll") for (int k = 0; k < 2; ++k) dst[m][k] = *(const PG8_LAS bf16x8*)(lds + PG8_SA(b, h) + aoff + m * 2048 + k * 1024); } while (0)
; #define PG8_LDB(dst, b, h) do { _Pragma("unroll") for (int n = 0; n < 2; ++n) _Pragma("unroll") for (int k = 0; k < 2; ++k) dst[n][k] = *(const PG8_LAS bf16x8*)(lds + PG8_SB(b, h) + boff + n * 2048 + k * 1024); } while (0)
; #define PG8_WAIT_V(n) asm volatile("s_waitcnt vmcnt(" #n ")" ::: "memory")
; #define PG8_WAIT_L(n) asm volatile("s_waitcnt lgkmcnt(" #n ")" ::: "memory")
; #define PG8_BAR __builtin_amdgcn_s_barrier()
; #define PG8_SCHED __builtin_amdgcn_sched_barrier(0)
; template <class Epi, class Sched, bool ALIGN_EPI = false, bool SP2 = false, bool F8 = false>
; __device__ __forceinline__ void gemm_phase(PG8_LAS unsigned char* lds, const Gemm g, const Sched& S, const Epi& E) {
;     ...
;             PG8_WAIT_V(8); PG8_WAIT_L(0); PG8_BAR; PG8_MMA(1, 0, At, B0); PG8_MMA(1, 1, At, B1); PG8_BAR; PG8_SCHED;
;             PG8_LDB(B0, 1, 0); PG8_LDB(B1, 1, 1); PG8_SCHED; PG8_LDA(At, 1, 0); PG8_STAGE(PG8_SA(0, 1), a2 + hA, voffA);
;             PG8_WAIT_V(8); PG8_WAIT_L(0); PG8_BAR; PG8_MMA(0, 0, At, B0); PG8_MMA(0, 1, At, B1); PG8_BAR; PG8_SCHED;
	v_mfma_f32_16x16x32_bf16 v[62:65], v[130:133], v[162:165], v[62:65]
	v_mfma_f32_16x16x32_bf16 v[38:41], v[138:141], v[162:165], v[38:41]
	v_mfma_f32_16x16x32_bf16 v[42:45], v[130:133], v[170:173], v[42:45]
	v_mfma_f32_16x16x32_bf16 v[14:17], v[138:141], v[170:173], v[14:17]
	v_mfma_f32_16x16x32_bf16 v[34:37], v[130:133], v[192:195], v[34:37]
	v_mfma_f32_16x16x32_bf16 v[10:13], v[138:141], v[192:195], v[10:13]
	v_mfma_f32_16x16x32_bf16 v[50:53], v[130:133], v[200:203], v[50:53]
	v_mfma_f32_16x16x32_bf16 v[114:117], v[138:141], v[200:203], v[114:117]
	v_mfma_f32_16x16x32_bf16 v[62:65], v[134:137], v[166:169], v[62:65]
	v_mfma_f32_16x16x32_bf16 v[38:41], v[142:145], v[166:169], v[38:41]
	v_mfma_f32_16x16x32_bf16 v[42:45], v[134:137], v[174:177], v[42:45]
	v_mfma_f32_16x16x32_bf16 v[14:17], v[142:145], v[174:177], v[14:17]
	v_mfma_f32_16x16x32_bf16 v[34:37], v[134:137], v[196:199], v[34:37]
	v_mfma_f32_16x16x32_bf16 v[10:13], v[142:145], v[196:199], v[10:13]
	v_mfma_f32_16x16x32_bf16 v[50:53], v[134:137], v[204:207], v[50:53]
	v_mfma_f32_16x16x32_bf16 v[114:117], v[142:145], v[204:207], v[114:117]
	v_mfma_f32_16x16x32_bf16 v[46:49], v[146:149], v[162:165], v[46:49]
	v_mfma_f32_16x16x32_bf16 v[22:25], v[154:157], v[162:165], v[22:25]
	v_mfma_f32_16x16x32_bf16 v[30:33], v[146:149], v[170:173], v[30:33]
	v_mfma_f32_16x16x32_bf16 v[6:9], v[154:157], v[170:173], v[6:9]
	v_mfma_f32_16x16x32_bf16 v[26:29], v[146:149], v[192:195], v[26:29]
	v_mfma_f32_16x16x32_bf16 v[2:5], v[154:157], v[192:195], v[2:5]
	v_mfma_f32_16x16x32_bf16 v[54:57], v[146:149], v[200:203], v[54:57]
	v_mfma_f32_16x16x32_bf16 v[18:21], v[154:157], v[200:203], v[18:21]
	v_mfma_f32_16x16x32_bf16 v[46:49], v[150:153], v[166:169], v[46:49]
	v_mfma_f32_16x16x32_bf16 v[22:25], v[158:161], v[166:169], v[22:25]
	v_mfma_f32_16x16x32_bf16 v[30:33], v[150:153], v[174:177], v[30:33]
	v_mfma_f32_16x16x32_bf16 v[6:9], v[158:161], v[174:177], v[6:9]
	v_mfma_f32_16x16x32_bf16 v[26:29], v[150:153], v[196:199], v[26:29]
	v_mfma_f32_16x16x32_bf16 v[2:5], v[158:161], v[196:199], v[2:5]
	v_mfma_f32_16x16x32_bf16 v[54:57], v[150:153], v[204:207], v[54:57]
	v_mfma_f32_16x16x32_bf16 v[18:21], v[158:161], v[204:207], v[18:21]
	s_barrier
	s_setprio 0
	s_add_i32 s81, 0, 0x18000
	s_add_i32 vcc_lo, 0, 0x1c000
	v_add_u32_e32 v142, s81, v240
	v_add_u32_e32 v158, vcc_lo, v240
	ds_read_b128 v[130:133], v142
	ds_read_b128 v[134:137], v142 offset:1024
	ds_read_b128 v[138:141], v142 offset:2048
	ds_read_b128 v[142:145], v142 offset:3072
	ds_read_b128 v[146:149], v158
	ds_read_b128 v[150:153], v158 offset:1024
	ds_read_b128 v[154:157], v158 offset:2048
	ds_read_b128 v[158:161], v158 offset:3072
	s_add_u32 s16, s16, 0x100000
	s_addc_u32 s17, s17, 0
	s_mov_b32 m0, s19
	v_lshl_add_u64 v[216:217], s[16:17], 0, v[178:179]
	ds_read_b128 v[162:165], v243 offset:32768
	ds_read_b128 v[166:169], v243 offset:33792
	ds_read_b128 v[170:173], v243 offset:34816
	ds_read_b128 v[174:177], v243 offset:35840
	ds_read_b128 v[192:195], v243 offset:36864
	ds_read_b128 v[196:199], v243 offset:37888
	ds_read_b128 v[200:203], v243 offset:38912
	ds_read_b128 v[204:207], v243 offset:39936
	global_load_lds_dwordx4 v[216:217], off
	v_lshl_add_u64 v[216:217], s[16:17], 0, v[182:183]
	s_mov_b32 m0, s33
	s_nop 0
	global_load_lds_dwordx4 v[216:217], off
	s_setprio 1
	s_waitcnt vmcnt(8)
	s_waitcnt lgkmcnt(0)
	s_barrier
	v_mfma_f32_16x16x32_bf16 v[126:129], v[130:133], v[162:165], v[126:129]
	v_mfma_f32_16x16x32_bf16 v[90:93], v[138:141], v[162:165], v[90:93]
	v_mfma_f32_16x16x32_bf16 v[110:113], v[130:133], v[170:173], v[110:113]
	v_mfma_f32_16x16x32_bf16 v[86:89], v[138:141], v[170:173], v[86:89]
	v_mfma_f32_16x16x32_bf16 v[106:109], v[130:133], v[192:195], v[106:109]
	v_mfma_f32_16x16x32_bf16 v[82:85], v[138:141], v[192:195], v[82:85]
	v_mfma_f32_16x16x32_bf16 v[118:121], v[130:133], v[200:203], v[118:121]
	v_mfma_f32_16x16x32_bf16 v[122:125], v[138:141], v[200:203], v[122:125]
	v_mfma_f32_16x16x32_bf16 v[126:129], v[134:137], v[166:169], v[126:129]
	v_mfma_f32_16x16x32_bf16 v[90:93], v[142:145], v[166:169], v[90:93]
	v_mfma_f32_16x16x32_bf16 v[110:113], v[134:137], v[174:177], v[110:113]
	v_mfma_f32_16x16x32_bf16 v[86:89], v[142:145], v[174:177], v[86:89]
	v_mfma_f32_16x16x32_bf16 v[106:109], v[134:137], v[196:199], v[106:109]
	v_mfma_f32_16x16x32_bf16 v[82:85], v[142:145], v[196:199], v[82:85]
	v_mfma_f32_16x16x32_bf16 v[118:121], v[134:137], v[204:207], v[118:121]
	v_mfma_f32_16x16x32_bf16 v[122:125], v[142:145], v[204:207], v[122:125]
	v_mfma_f32_16x16x32_bf16 v[94:97], v[146:149], v[162:165], v[94:97]
	v_mfma_f32_16x16x32_bf16 v[66:69], v[154:157], v[162:165], v[66:69]
	v_mfma_f32_16x16x32_bf16 v[102:105], v[146:149], v[170:173], v[102:105]
	v_mfma_f32_16x16x32_bf16 v[78:81], v[154:157], v[170:173], v[78:81]
	v_mfma_f32_16x16x32_bf16 v[98:101], v[146:149], v[192:195], v[98:101]
	v_mfma_f32_16x16x32_bf16 v[74:77], v[154:157], v[192:195], v[74:77]
	v_mfma_f32_16x16x32_bf16 v[70:73], v[146:149], v[200:203], v[70:73]
	v_mfma_f32_16x16x32_bf16 v[58:61], v[154:157], v[200:203], v[58:61]
	v_mfma_f32_16x16x32_bf16 v[94:97], v[150:153], v[166:169], v[94:97]
	v_mfma_f32_16x16x32_bf16 v[66:69], v[158:161], v[166:169], v[66:69]
	v_mfma_f32_16x16x32_bf16 v[102:105], v[150:153], v[174:177], v[102:105]
	v_mfma_f32_16x16x32_bf16 v[78:81], v[158:161], v[174:177], v[78:81]
	v_mfma_f32_16x16x32_bf16 v[98:101], v[150:153], v[196:199], v[98:101]
	v_mfma_f32_16x16x32_bf16 v[74:77], v[158:161], v[196:199], v[74:77]
	v_mfma_f32_16x16x32_bf16 v[70:73], v[150:153], v[204:207], v[70:73]
	v_mfma_f32_16x16x32_bf16 v[58:61], v[158:161], v[204:207], v[58:61]
	s_barrier
; #define PG8_STAGE(bufoff, gbase, voff) do { _Pragma("unroll") for (int _i = 0; _i < 2; ++_i) \
;         __builtin_amdgcn_global_load_lds((const unsigned*)((const char*)(gbase) + (voff)[_i]), (PG8_LAS unsigned*)(lds + (bufoff) + ldsw + _i * 8192), 16, 0, 0); } while (0)
; #define PG8_LDA(dst, b, h) do { _Pragma("unroll") for (int m = 0; m < 4; ++m) _Pragma("unroll") for (int k = 0; k < 2; ++k) dst[m][k] = *(const PG8_LAS bf16x8*)(lds + PG8_SA(b, h) + aoff + m * 2048 + k * 1024); } while (0)
; #define PG8_WAIT_V(n) asm volatile("s_waitcnt vmcnt(" #n ")" ::: "memory")
; #define PG8_WAIT_L(n) asm volatile("s_waitcnt lgkmcnt(" #n ")" ::: "memory")
; #define PG8_BAR __builtin_amdgcn_s_barrier()
; #define PG8_SCHED __builtin_amdgcn_sched_barrier(0)
; template <class Epi, class Sched, bool ALIGN_EPI = false, bool SP2 = false, bool F8 = false>
; __device__ __forceinline__ void gemm_phase(PG8_LAS unsigned char* lds, const Gemm g, const Sched& S, const Epi& E) {
;     ...
;             PG8_LDA(At, 1, 1); PG8_STAGE(PG8_SB(1, 0), b3, voffB); PG8_STAGE(PG8_SB(1, 1), b3 + hB, voffB); PG8_STAGE(PG8_SA(1, 0), a3, voffA);
;             PG8_WAIT_V(8); PG8_WAIT_L(0); PG8_BAR; PG8_MMA(1, 0, At, B0); PG8_MMA(1, 1, At, B1); PG8_BAR; PG8_SCHED;
;     ...
;         if constexpr (ALIGN_EPI) { if (wr == 0) PG8_BAR; }
	s_setprio 0
	s_add_i32 s16, s81, s6
	v_lshl_add_u64 v[208:209], v[208:209], 0, s[36:37]
	s_mov_b32 m0, s16
	ds_read_b128 v[162:165], v243 offset:49152
	ds_read_b128 v[166:169], v243 offset:50176
	ds_read_b128 v[170:173], v243 offset:51200
	ds_read_b128 v[174:177], v243 offset:52224
	ds_read_b128 v[192:195], v243 offset:53248
	ds_read_b128 v[196:199], v243 offset:54272
	ds_read_b128 v[200:203], v243 offset:55296
	ds_read_b128 v[204:207], v243 offset:56320
	global_load_lds_dwordx4 v[208:209], off
	s_add_i32 m0, s16, 0x2000
	s_add_u32 s14, s14, 0x100080
	v_lshl_add_u64 v[208:209], v[210:211], 0, s[36:37]
	s_addc_u32 s15, s15, 0
	s_add_i32 s16, vcc_lo, s6
	global_load_lds_dwordx4 v[208:209], off
	v_lshl_add_u64 v[208:209], s[14:15], 0, v[180:181]
	s_mov_b32 m0, s16
	s_nop 0
	global_load_lds_dwordx4 v[208:209], off
	v_lshl_add_u64 v[208:209], s[14:15], 0, v[184:185]
	s_add_i32 m0, s16, 0x2000
	s_nop 0
	global_load_lds_dwordx4 v[208:209], off
	v_lshl_add_u64 v[208:209], v[212:213], 0, s[36:37]
	s_mov_b32 m0, s71
	s_nop 0
	global_load_lds_dwordx4 v[208:209], off
	v_lshl_add_u64 v[208:209], v[214:215], 0, s[36:37]
	s_mov_b32 m0, s74
	s_nop 0
	global_load_lds_dwordx4 v[208:209], off
	s_setprio 1
	s_waitcnt vmcnt(8)
	s_waitcnt lgkmcnt(0)
	s_barrier
	v_mfma_f32_16x16x32_bf16 v[62:65], v[130:133], v[162:165], v[62:65]
	v_mfma_f32_16x16x32_bf16 v[38:41], v[138:141], v[162:165], v[38:41]
	v_mfma_f32_16x16x32_bf16 v[42:45], v[130:133], v[170:173], v[42:45]
	v_mfma_f32_16x16x32_bf16 v[14:17], v[138:141], v[170:173], v[14:17]
	v_mfma_f32_16x16x32_bf16 v[34:37], v[130:133], v[192:195], v[34:37]
	v_mfma_f32_16x16x32_bf16 v[10:13], v[138:141], v[192:195], v[10:13]
	v_mfma_f32_16x16x32_bf16 v[50:53], v[130:133], v[200:203], v[50:53]
	v_mfma_f32_16x16x32_bf16 v[114:117], v[138:141], v[200:203], v[114:117]
	v_mfma_f32_16x16x32_bf16 v[62:65], v[134:137], v[166:169], v[62:65]
	v_mfma_f32_16x16x32_bf16 v[38:41], v[142:145], v[166:169], v[38:41]
	v_mfma_f32_16x16x32_bf16 v[42:45], v[134:137], v[174:177], v[42:45]
	v_mfma_f32_16x16x32_bf16 v[14:17], v[142:145], v[174:177], v[14:17]
	v_mfma_f32_16x16x32_bf16 v[34:37], v[134:137], v[196:199], v[34:37]
	v_mfma_f32_16x16x32_bf16 v[10:13], v[142:145], v[196:199], v[10:13]
	v_mfma_f32_16x16x32_bf16 v[50:53], v[134:137], v[204:207], v[50:53]
	v_mfma_f32_16x16x32_bf16 v[114:117], v[142:145], v[204:207], v[114:117]
	v_mfma_f32_16x16x32_bf16 v[46:49], v[146:149], v[162:165], v[46:49]
	v_mfma_f32_16x16x32_bf16 v[22:25], v[154:157], v[162:165], v[22:25]
	v_mfma_f32_16x16x32_bf16 v[30:33], v[146:149], v[170:173], v[30:33]
	v_mfma_f32_16x16x32_bf16 v[6:9], v[154:157], v[170:173], v[6:9]
	v_mfma_f32_16x16x32_bf16 v[26:29], v[146:149], v[192:195], v[26:29]
	v_mfma_f32_16x16x32_bf16 v[2:5], v[154:157], v[192:195], v[2:5]
	v_mfma_f32_16x16x32_bf16 v[54:57], v[146:149], v[200:203], v[54:57]
	v_mfma_f32_16x16x32_bf16 v[18:21], v[154:157], v[200:203], v[18:21]
	v_mfma_f32_16x16x32_bf16 v[46:49], v[150:153], v[166:169], v[46:49]
	v_mfma_f32_16x16x32_bf16 v[22:25], v[158:161], v[166:169], v[22:25]
	v_mfma_f32_16x16x32_bf16 v[30:33], v[150:153], v[174:177], v[30:33]
	v_mfma_f32_16x16x32_bf16 v[6:9], v[158:161], v[174:177], v[6:9]
	v_mfma_f32_16x16x32_bf16 v[26:29], v[150:153], v[196:199], v[26:29]
	v_mfma_f32_16x16x32_bf16 v[2:5], v[158:161], v[196:199], v[2:5]
	v_mfma_f32_16x16x32_bf16 v[54:57], v[150:153], v[204:207], v[54:57]
	v_mfma_f32_16x16x32_bf16 v[18:21], v[158:161], v[204:207], v[18:21]
	s_barrier
	s_setprio 0
	s_add_i32 s80, s80, 2
	s_add_u32 s78, s78, 0x100
	s_addc_u32 s79, s79, 0
	s_add_u32 s12, s12, 0x100
	s_addc_u32 s13, s13, 0
	s_cmp_gt_u32 s80, 61
	s_cbranch_scc0 .LBB0_770
	s_and_b64 vcc, exec, s[38:39]
	s_cbranch_vccz .LBB0_773
	s_barrier

; #define PG8_STAGE(bufoff, gbase, voff) do { _Pragma("unroll") for (int _i = 0; _i < 2; ++_i) \
;         __builtin_amdgcn_global_load_lds((const unsigned*)((const char*)(gbase) + (voff)[_i]), (PG8_LAS unsigned*)(lds + (bufoff) + ldsw + _i * 8192), 16, 0, 0); } while (0)
; #define PG8_LDA(dst, b, h) do { _Pragma("unroll") for (int m = 0; m < 4; ++m) _Pragma("unroll") for (int k = 0; k < 2; ++k) dst[m][k] = *(const PG8_LAS bf16x8*)(lds + PG8_SA(b, h) + aoff + m * 2048 + k * 1024); } while (0)
; #define PG8_LDB(dst, b, h) do { _Pragma("unroll") for (int n = 0; n < 2; ++n) _Pragma("unroll") for (int k = 0; k < 2; ++k) dst[n][k] = *(const PG8_LAS bf16x8*)(lds + PG8_SB(b, h) + boff + n * 2048 + k * 1024); } while (0)
; #define PG8_WAIT_V(n) asm volatile("s_waitcnt vmcnt(" #n ")" ::: "memory")
; #define PG8_WAIT_L(n) asm volatile("s_waitcnt lgkmcnt(" #n ")" ::: "memory")
; #define PG8_BAR __builtin_amdgcn_s_barrier()
; #define PG8_SCHED __builtin_amdgcn_sched_barrier(0)
; template <class Epi, class Sched, bool ALIGN_EPI = false, bool SP2 = false, bool F8 = false>
; __device__ __forceinline__ void gemm_phase(PG8_LAS unsigned char* lds, const Gemm g, const Sched& S, const Epi& E) {
;     ...
;             PG8_LDB(B0, 0, 0); PG8_LDB(B1, 0, 1); PG8_SCHED; PG8_LDA(At, 0, 0); PG8_STAGE(PG8_SA(1, 1), a1 + hA, voffA);
;             PG8_WAIT_V(8); PG8_WAIT_L(0); PG8_BAR; PG8_MMA(0, 0, At, B0); PG8_MMA(0, 1, At, B1); PG8_BAR; PG8_SCHED;
;             PG8_LDA(At, 0, 1); PG8_STAGE(PG8_SB(0, 0), b2, voffB); PG8_STAGE(PG8_SB(0, 1), b2 + hB, voffB); PG8_STAGE(PG8_SA(0, 0), a2, voffA);
;             PG8_WAIT_V(8); PG8_WAIT_L(0); PG8_BAR; PG8_MMA(1, 0, At, B0); PG8_MMA(1, 1, At, B1); PG8_BAR; PG8_SCHED;
.LBB0_825:
	ds_read_b128 v[130:133], v241
	ds_read_b128 v[134:137], v241 offset:1024
	ds_read_b128 v[138:141], v241 offset:2048
	ds_read_b128 v[142:145], v241 offset:3072
	ds_read_b128 v[146:149], v242
	ds_read_b128 v[150:153], v242 offset:1024
	ds_read_b128 v[154:157], v242 offset:2048
	ds_read_b128 v[158:161], v242 offset:3072
	s_add_u32 s14, s12, 0xfff00080
	s_addc_u32 s15, s13, -1
	s_cmp_eq_u32 s82, 60
	s_cselect_b32 s17, s11, s15
	s_cselect_b32 s16, s63, s14
	s_cselect_b32 s15, s65, s81
	s_cselect_b32 s14, s79, s80
	v_lshl_add_u64 v[208:209], s[12:13], 0, v[188:189]
	s_add_i32 m0, s7, 0xc000
	ds_read_b128 v[162:165], v243
	ds_read_b128 v[166:169], v243 offset:1024
	ds_read_b128 v[170:173], v243 offset:2048
	ds_read_b128 v[174:177], v243 offset:3072
	ds_read_b128 v[192:195], v243 offset:4096
	ds_read_b128 v[196:199], v243 offset:5120
	ds_read_b128 v[200:203], v243 offset:6144
	ds_read_b128 v[204:207], v243 offset:7168
	global_load_lds_dwordx4 v[208:209], off
	v_lshl_add_u64 v[208:209], s[12:13], 0, v[186:187]
	s_add_i32 m0, s7, 0xe000
	s_nop 0
	global_load_lds_dwordx4 v[208:209], off
	s_setprio 1
	s_waitcnt vmcnt(8)
	s_waitcnt lgkmcnt(0)
	s_barrier
	v_mfma_f32_16x16x32_bf16 v[126:129], v[130:133], v[162:165], v[126:129]
	v_mfma_f32_16x16x32_bf16 v[90:93], v[138:141], v[162:165], v[90:93]
	v_mfma_f32_16x16x32_bf16 v[110:113], v[130:133], v[170:173], v[110:113]
	v_mfma_f32_16x16x32_bf16 v[86:89], v[138:141], v[170:173], v[86:89]
	v_mfma_f32_16x16x32_bf16 v[106:109], v[130:133], v[192:195], v[106:109]
	v_mfma_f32_16x16x32_bf16 v[82:85], v[138:141], v[192:195], v[82:85]
	v_mfma_f32_16x16x32_bf16 v[118:121], v[130:133], v[200:203], v[118:121]
	v_mfma_f32_16x16x32_bf16 v[122:125], v[138:141], v[200:203], v[122:125]
	v_mfma_f32_16x16x32_bf16 v[126:129], v[134:137], v[166:169], v[126:129]
	v_mfma_f32_16x16x32_bf16 v[90:93], v[142:145], v[166:169], v[90:93]
	v_mfma_f32_16x16x32_bf16 v[110:113], v[134:137], v[174:177], v[110:113]
	v_mfma_f32_16x16x32_bf16 v[86:89], v[142:145], v[174:177], v[86:89]
	v_mfma_f32_16x16x32_bf16 v[106:109], v[134:137], v[196:199], v[106:109]
	v_mfma_f32_16x16x32_bf16 v[82:85], v[142:145], v[196:199], v[82:85]
	v_mfma_f32_16x16x32_bf16 v[118:121], v[134:137], v[204:207], v[118:121]
	v_mfma_f32_16x16x32_bf16 v[122:125], v[142:145], v[204:207], v[122:125]
	v_mfma_f32_16x16x32_bf16 v[94:97], v[146:149], v[162:165], v[94:97]
	v_mfma_f32_16x16x32_bf16 v[66:69], v[154:157], v[162:165], v[66:69]
	v_mfma_f32_16x16x32_bf16 v[102:105], v[146:149], v[170:173], v[102:105]
	v_mfma_f32_16x16x32_bf16 v[78:81], v[154:157], v[170:173], v[78:81]
	v_mfma_f32_16x16x32_bf16 v[98:101], v[146:149], v[192:195], v[98:101]
	v_mfma_f32_16x16x32_bf16 v[74:77], v[154:157], v[192:195], v[74:77]
	v_mfma_f32_16x16x32_bf16 v[70:73], v[146:149], v[200:203], v[70:73]
	v_mfma_f32_16x16x32_bf16 v[58:61], v[154:157], v[200:203], v[58:61]
	v_mfma_f32_16x16x32_bf16 v[94:97], v[150:153], v[166:169], v[94:97]
	v_mfma_f32_16x16x32_bf16 v[66:69], v[158:161], v[166:169], v[66:69]
	v_mfma_f32_16x16x32_bf16 v[102:105], v[150:153], v[174:177], v[102:105]
	v_mfma_f32_16x16x32_bf16 v[78:81], v[158:161], v[174:177], v[78:81]
	v_mfma_f32_16x16x32_bf16 v[98:101], v[150:153], v[196:199], v[98:101]
	v_mfma_f32_16x16x32_bf16 v[74:77], v[158:161], v[196:199], v[74:77]
	v_mfma_f32_16x16x32_bf16 v[70:73], v[150:153], v[204:207], v[70:73]
	v_mfma_f32_16x16x32_bf16 v[58:61], v[158:161], v[204:207], v[58:61]
	s_barrier
	s_setprio 0
	s_add_i32 s83, s30, s5
	v_lshl_add_u64 v[208:209], s[14:15], 0, v[180:181]
	s_mov_b32 m0, s83
	ds_read_b128 v[162:165], v243 offset:16384
	ds_read_b128 v[166:169], v243 offset:17408
	ds_read_b128 v[170:173], v243 offset:18432
	ds_read_b128 v[174:177], v243 offset:19456
	ds_read_b128 v[192:195], v243 offset:20480
	ds_read_b128 v[196:199], v243 offset:21504
	ds_read_b128 v[200:203], v243 offset:22528
	ds_read_b128 v[204:207], v243 offset:23552
	global_load_lds_dwordx4 v[208:209], off
	s_add_i32 m0, s83, 0x2000
	s_add_u32 vcc_lo, s14, 0x100000
	v_lshl_add_u64 v[210:211], s[14:15], 0, v[184:185]
	s_addc_u32 vcc_hi, s15, 0
	s_add_i32 s83, s86, s5
	global_load_lds_dwordx4 v[210:211], off
	v_lshl_add_u64 v[212:213], vcc, 0, v[180:181]
	s_mov_b32 m0, s83
	v_lshl_add_u64 v[214:215], s[16:17], 0, v[182:183]
	global_load_lds_dwordx4 v[212:213], off
	v_lshl_add_u64 v[212:213], vcc, 0, v[184:185]
	s_add_i32 m0, s83, 0x2000
	s_nop 0
	global_load_lds_dwordx4 v[212:213], off
	v_lshl_add_u64 v[212:213], s[16:17], 0, v[178:179]
	s_mov_b32 m0, s7
	s_nop 0
	global_load_lds_dwordx4 v[212:213], off
	s_mov_b32 m0, s18
	s_nop 0
	global_load_lds_dwordx4 v[214:215], off
	s_setprio 1
	s_waitcnt vmcnt(8)
	s_waitcnt lgkmcnt(0)
	s_barrier
; #define PG8_STAGE(bufoff, gbase, voff) do { _Pragma("unroll") for (int _i = 0; _i < 2; ++_i) \
;         __builtin_amdgcn_global_load_lds((const unsigned*)((const char*)(gbase) + (voff)[_i]), (PG8_LAS unsigned*)(lds + (bufoff) + ldsw + _i * 8192), 16, 0, 0); } while (0)
; #define PG8_LDA(dst, b, h) do { _Pragma("unroll") for (int m = 0; m < 4; ++m) _Pragma("unroll") for (int k = 0; k < 2; ++k) dst[m][k] = *(const PG8_LAS bf16x8*)(lds + PG8_SA(b, h) + aoff + m * 2048 + k * 1024); } while (0)
; #define PG8_LDB(dst, b, h) do { _Pragma("unroll") for (int n = 0; n < 2; ++n) _Pragma("unroll") for (int k = 0; k < 2; ++k) dst[n][k] = *(const PG8_LAS bf16x8*)(lds + PG8_SB(b, h) + boff + n * 2048 + k * 1024); } while (0)
; #define PG8_WAIT_V(n) asm volatile("s_waitcnt vmcnt(" #n ")" ::: "memory")
; #define PG8_WAIT_L(n) asm volatile("s_waitcnt lgkmcnt(" #n ")" ::: "memory")
; #define PG8_BAR __builtin_amdgcn_s_barrier()
; #define PG8_SCHED __builtin_amdgcn_sched_barrier(0)
; template <class Epi, class Sched, bool ALIGN_EPI = false, bool SP2 = false, bool F8 = false>
; __device__ __forceinline__ void gemm_phase(PG8_LAS unsigned char* lds, const Gemm g, const Sched& S, const Epi& E) {
;     ...
;             PG8_WAIT_V(8); PG8_WAIT_L(0); PG8_BAR; PG8_MMA(1, 0, At, B0); PG8_MMA(1, 1, At, B1); PG8_BAR; PG8_SCHED;
;             PG8_LDB(B0, 1, 0); PG8_LDB(B1, 1, 1); PG8_SCHED; PG8_LDA(At, 1, 0); PG8_STAGE(PG8_SA(0, 1), a2 + hA, voffA);
;             PG8_WAIT_V(8); PG8_WAIT_L(0); PG8_BAR; PG8_MMA(0, 0, At, B0); PG8_MMA(0, 1, At, B1); PG8_BAR; PG8_SCHED;
	v_mfma_f32_16x16x32_bf16 v[62:65], v[130:133], v[162:165], v[62:65]
	v_mfma_f32_16x16x32_bf16 v[38:41], v[138:141], v[162:165], v[38:41]
	v_mfma_f32_16x16x32_bf16 v[42:45], v[130:133], v[170:173], v[42:45]
	v_mfma_f32_16x16x32_bf16 v[14:17], v[138:141], v[170:173], v[14:17]
	v_mfma_f32_16x16x32_bf16 v[34:37], v[130:133], v[192:195], v[34:37]
	v_mfma_f32_16x16x32_bf16 v[10:13], v[138:141], v[192:195], v[10:13]
	v_mfma_f32_16x16x32_bf16 v[50:53], v[130:133], v[200:203], v[50:53]
	v_mfma_f32_16x16x32_bf16 v[114:117], v[138:141], v[200:203], v[114:117]
	v_mfma_f32_16x16x32_bf16 v[62:65], v[134:137], v[166:169], v[62:65]
	v_mfma_f32_16x16x32_bf16 v[38:41], v[142:145], v[166:169], v[38:41]
	v_mfma_f32_16x16x32_bf16 v[42:45], v[134:137], v[174:177], v[42:45]
	v_mfma_f32_16x16x32_bf16 v[14:17], v[142:145], v[174:177], v[14:17]
	v_mfma_f32_16x16x32_bf16 v[34:37], v[134:137], v[196:199], v[34:37]
	v_mfma_f32_16x16x32_bf16 v[10:13], v[142:145], v[196:199], v[10:13]
	v_mfma_f32_16x16x32_bf16 v[50:53], v[134:137], v[204:207], v[50:53]
	v_mfma_f32_16x16x32_bf16 v[114:117], v[142:145], v[204:207], v[114:117]
	v_mfma_f32_16x16x32_bf16 v[46:49], v[146:149], v[162:165], v[46:49]
	v_mfma_f32_16x16x32_bf16 v[22:25], v[154:157], v[162:165], v[22:25]
	v_mfma_f32_16x16x32_bf16 v[30:33], v[146:149], v[170:173], v[30:33]
	v_mfma_f32_16x16x32_bf16 v[6:9], v[154:157], v[170:173], v[6:9]
	v_mfma_f32_16x16x32_bf16 v[26:29], v[146:149], v[192:195], v[26:29]
	v_mfma_f32_16x16x32_bf16 v[2:5], v[154:157], v[192:195], v[2:5]
	v_mfma_f32_16x16x32_bf16 v[54:57], v[146:149], v[200:203], v[54:57]
	v_mfma_f32_16x16x32_bf16 v[18:21], v[154:157], v[200:203], v[18:21]
	v_mfma_f32_16x16x32_bf16 v[46:49], v[150:153], v[166:169], v[46:49]
	v_mfma_f32_16x16x32_bf16 v[22:25], v[158:161], v[166:169], v[22:25]
	v_mfma_f32_16x16x32_bf16 v[30:33], v[150:153], v[174:177], v[30:33]
	v_mfma_f32_16x16x32_bf16 v[6:9], v[158:161], v[174:177], v[6:9]
	v_mfma_f32_16x16x32_bf16 v[26:29], v[150:153], v[196:199], v[26:29]
	v_mfma_f32_16x16x32_bf16 v[2:5], v[158:161], v[196:199], v[2:5]
	v_mfma_f32_16x16x32_bf16 v[54:57], v[150:153], v[204:207], v[54:57]
	v_mfma_f32_16x16x32_bf16 v[18:21], v[158:161], v[204:207], v[18:21]
	s_barrier
	s_setprio 0
	s_add_i32 s83, 0, 0x18000
	s_add_i32 vcc_lo, 0, 0x1c000
	v_add_u32_e32 v142, s83, v240
	v_add_u32_e32 v158, vcc_lo, v240
	ds_read_b128 v[130:133], v142
	ds_read_b128 v[134:137], v142 offset:1024
	ds_read_b128 v[138:141], v142 offset:2048
	ds_read_b128 v[142:145], v142 offset:3072
	ds_read_b128 v[146:149], v158
	ds_read_b128 v[150:153], v158 offset:1024
	ds_read_b128 v[154:157], v158 offset:2048
	ds_read_b128 v[158:161], v158 offset:3072
	s_add_u32 s16, s16, 0x100000
	s_addc_u32 s17, s17, 0
	s_mov_b32 m0, s19
	v_lshl_add_u64 v[216:217], s[16:17], 0, v[178:179]
	ds_read_b128 v[162:165], v243 offset:32768
	ds_read_b128 v[166:169], v243 offset:33792
	ds_read_b128 v[170:173], v243 offset:34816
	ds_read_b128 v[174:177], v243 offset:35840
	ds_read_b128 v[192:195], v243 offset:36864
	ds_read_b128 v[196:199], v243 offset:37888
	ds_read_b128 v[200:203], v243 offset:38912
	ds_read_b128 v[204:207], v243 offset:39936
	global_load_lds_dwordx4 v[216:217], off
	v_lshl_add_u64 v[216:217], s[16:17], 0, v[182:183]
	s_mov_b32 m0, s29
	s_nop 0
	global_load_lds_dwordx4 v[216:217], off
	s_setprio 1
	s_waitcnt vmcnt(8)
	s_waitcnt lgkmcnt(0)
	s_barrier
	v_mfma_f32_16x16x32_bf16 v[126:129], v[130:133], v[162:165], v[126:129]
	v_mfma_f32_16x16x32_bf16 v[90:93], v[138:141], v[162:165], v[90:93]
	v_mfma_f32_16x16x32_bf16 v[110:113], v[130:133], v[170:173], v[110:113]
	v_mfma_f32_16x16x32_bf16 v[86:89], v[138:141], v[170:173], v[86:89]
	v_mfma_f32_16x16x32_bf16 v[106:109], v[130:133], v[192:195], v[106:109]
	v_mfma_f32_16x16x32_bf16 v[82:85], v[138:141], v[192:195], v[82:85]
	v_mfma_f32_16x16x32_bf16 v[118:121], v[130:133], v[200:203], v[118:121]
	v_mfma_f32_16x16x32_bf16 v[122:125], v[138:141], v[200:203], v[122:125]
	v_mfma_f32_16x16x32_bf16 v[126:129], v[134:137], v[166:169], v[126:129]
	v_mfma_f32_16x16x32_bf16 v[90:93], v[142:145], v[166:169], v[90:93]
	v_mfma_f32_16x16x32_bf16 v[110:113], v[134:137], v[174:177], v[110:113]
	v_mfma_f32_16x16x32_bf16 v[86:89], v[142:145], v[174:177], v[86:89]
	v_mfma_f32_16x16x32_bf16 v[106:109], v[134:137], v[196:199], v[106:109]
	v_mfma_f32_16x16x32_bf16 v[82:85], v[142:145], v[196:199], v[82:85]
	v_mfma_f32_16x16x32_bf16 v[118:121], v[134:137], v[204:207], v[118:121]
	v_mfma_f32_16x16x32_bf16 v[122:125], v[142:145], v[204:207], v[122:125]
	v_mfma_f32_16x16x32_bf16 v[94:97], v[146:149], v[162:165], v[94:97]
	v_mfma_f32_16x16x32_bf16 v[66:69], v[154:157], v[162:165], v[66:69]
	v_mfma_f32_16x16x32_bf16 v[102:105], v[146:149], v[170:173], v[102:105]
	v_mfma_f32_16x16x32_bf16 v[78:81], v[154:157], v[170:173], v[78:81]
	v_mfma_f32_16x16x32_bf16 v[98:101], v[146:149], v[192:195], v[98:101]
	v_mfma_f32_16x16x32_bf16 v[74:77], v[154:157], v[192:195], v[74:77]
	v_mfma_f32_16x16x32_bf16 v[70:73], v[146:149], v[200:203], v[70:73]
	v_mfma_f32_16x16x32_bf16 v[58:61], v[154:157], v[200:203], v[58:61]
	v_mfma_f32_16x16x32_bf16 v[94:97], v[150:153], v[166:169], v[94:97]
	v_mfma_f32_16x16x32_bf16 v[66:69], v[158:161], v[166:169], v[66:69]
	v_mfma_f32_16x16x32_bf16 v[102:105], v[150:153], v[174:177], v[102:105]
	v_mfma_f32_16x16x32_bf16 v[78:81], v[158:161], v[174:177], v[78:81]
	v_mfma_f32_16x16x32_bf16 v[98:101], v[150:153], v[196:199], v[98:101]
	v_mfma_f32_16x16x32_bf16 v[74:77], v[158:161], v[196:199], v[74:77]
	v_mfma_f32_16x16x32_bf16 v[70:73], v[150:153], v[204:207], v[70:73]
	v_mfma_f32_16x16x32_bf16 v[58:61], v[158:161], v[204:207], v[58:61]
	s_barrier
; #define PG8_STAGE(bufoff, gbase, voff) do { _Pragma("unroll") for (int _i = 0; _i < 2; ++_i) \
;         __builtin_amdgcn_global_load_lds((const unsigned*)((const char*)(gbase) + (voff)[_i]), (PG8_LAS unsigned*)(lds + (bufoff) + ldsw + _i * 8192), 16, 0, 0); } while (0)
; #define PG8_LDA(dst, b, h) do { _Pragma("unroll") for (int m = 0; m < 4; ++m) _Pragma("unroll") for (int k = 0; k < 2; ++k) dst[m][k] = *(const PG8_LAS bf16x8*)(lds + PG8_SA(b, h) + aoff + m * 2048 + k * 1024); } while (0)
; #define PG8_WAIT_V(n) asm volatile("s_waitcnt vmcnt(" #n ")" ::: "memory")
; #define PG8_WAIT_L(n) asm volatile("s_waitcnt lgkmcnt(" #n ")" ::: "memory")
; #define PG8_BAR __builtin_amdgcn_s_barrier()
; #define PG8_SCHED __builtin_amdgcn_sched_barrier(0)
; template <class Epi, class Sched, bool ALIGN_EPI = false, bool SP2 = false, bool F8 = false>
; __device__ __forceinline__ void gemm_phase(PG8_LAS unsigned char* lds, const Gemm g, const Sched& S, const Epi& E) {
;     ...
;             PG8_LDA(At, 1, 1); PG8_STAGE(PG8_SB(1, 0), b3, voffB); PG8_STAGE(PG8_SB(1, 1), b3 + hB, voffB); PG8_STAGE(PG8_SA(1, 0), a3, voffA);
;             PG8_WAIT_V(8); PG8_WAIT_L(0); PG8_BAR; PG8_MMA(1, 0, At, B0); PG8_MMA(1, 1, At, B1); PG8_BAR; PG8_SCHED;
	s_setprio 0
	s_add_i32 s16, s83, s5
	v_lshl_add_u64 v[208:209], v[208:209], 0, s[38:39]
	s_mov_b32 m0, s16
	ds_read_b128 v[162:165], v243 offset:49152
	ds_read_b128 v[166:169], v243 offset:50176
	ds_read_b128 v[170:173], v243 offset:51200
	ds_read_b128 v[174:177], v243 offset:52224
	ds_read_b128 v[192:195], v243 offset:53248
	ds_read_b128 v[196:199], v243 offset:54272
	ds_read_b128 v[200:203], v243 offset:55296
	ds_read_b128 v[204:207], v243 offset:56320
	global_load_lds_dwordx4 v[208:209], off
	s_add_i32 m0, s16, 0x2000
	s_add_u32 s14, s14, 0x100080
	v_lshl_add_u64 v[208:209], v[210:211], 0, s[38:39]
	s_addc_u32 s15, s15, 0
	s_add_i32 s16, vcc_lo, s5
	global_load_lds_dwordx4 v[208:209], off
	v_lshl_add_u64 v[208:209], s[14:15], 0, v[180:181]
	s_mov_b32 m0, s16
	s_nop 0
	global_load_lds_dwordx4 v[208:209], off
	v_lshl_add_u64 v[208:209], s[14:15], 0, v[184:185]
	s_add_i32 m0, s16, 0x2000
	s_nop 0
	global_load_lds_dwordx4 v[208:209], off
	v_lshl_add_u64 v[208:209], v[212:213], 0, s[38:39]
	s_mov_b32 m0, s70
	s_nop 0
	global_load_lds_dwordx4 v[208:209], off
	v_lshl_add_u64 v[208:209], v[214:215], 0, s[38:39]
	s_mov_b32 m0, s71
	s_nop 0
	global_load_lds_dwordx4 v[208:209], off
	s_setprio 1
	s_waitcnt vmcnt(8)
	s_waitcnt lgkmcnt(0)
	s_barrier
	v_mfma_f32_16x16x32_bf16 v[62:65], v[130:133], v[162:165], v[62:65]
	v_mfma_f32_16x16x32_bf16 v[38:41], v[138:141], v[162:165], v[38:41]
	v_mfma_f32_16x16x32_bf16 v[42:45], v[130:133], v[170:173], v[42:45]
	v_mfma_f32_16x16x32_bf16 v[14:17], v[138:141], v[170:173], v[14:17]
	v_mfma_f32_16x16x32_bf16 v[34:37], v[130:133], v[192:195], v[34:37]
	v_mfma_f32_16x16x32_bf16 v[10:13], v[138:141], v[192:195], v[10:13]
	v_mfma_f32_16x16x32_bf16 v[50:53], v[130:133], v[200:203], v[50:53]
	v_mfma_f32_16x16x32_bf16 v[114:117], v[138:141], v[200:203], v[114:117]
	v_mfma_f32_16x16x32_bf16 v[62:65], v[134:137], v[166:169], v[62:65]
	v_mfma_f32_16x16x32_bf16 v[38:41], v[142:145], v[166:169], v[38:41]
	v_mfma_f32_16x16x32_bf16 v[42:45], v[134:137], v[174:177], v[42:45]
	v_mfma_f32_16x16x32_bf16 v[14:17], v[142:145], v[174:177], v[14:17]
	v_mfma_f32_16x16x32_bf16 v[34:37], v[134:137], v[196:199], v[34:37]
	v_mfma_f32_16x16x32_bf16 v[10:13], v[142:145], v[196:199], v[10:13]
	v_mfma_f32_16x16x32_bf16 v[50:53], v[134:137], v[204:207], v[50:53]
	v_mfma_f32_16x16x32_bf16 v[114:117], v[142:145], v[204:207], v[114:117]
	v_mfma_f32_16x16x32_bf16 v[46:49], v[146:149], v[162:165], v[46:49]
	v_mfma_f32_16x16x32_bf16 v[22:25], v[154:157], v[162:165], v[22:25]
	v_mfma_f32_16x16x32_bf16 v[30:33], v[146:149], v[170:173], v[30:33]
	v_mfma_f32_16x16x32_bf16 v[6:9], v[154:157], v[170:173], v[6:9]
	v_mfma_f32_16x16x32_bf16 v[26:29], v[146:149], v[192:195], v[26:29]
	v_mfma_f32_16x16x32_bf16 v[2:5], v[154:157], v[192:195], v[2:5]
	v_mfma_f32_16x16x32_bf16 v[54:57], v[146:149], v[200:203], v[54:57]
	v_mfma_f32_16x16x32_bf16 v[18:21], v[154:157], v[200:203], v[18:21]
	v_mfma_f32_16x16x32_bf16 v[46:49], v[150:153], v[166:169], v[46:49]
	v_mfma_f32_16x16x32_bf16 v[22:25], v[158:161], v[166:169], v[22:25]
	v_mfma_f32_16x16x32_bf16 v[30:33], v[150:153], v[174:177], v[30:33]
	v_mfma_f32_16x16x32_bf16 v[6:9], v[158:161], v[174:177], v[6:9]
	v_mfma_f32_16x16x32_bf16 v[26:29], v[150:153], v[196:199], v[26:29]
	v_mfma_f32_16x16x32_bf16 v[2:5], v[158:161], v[196:199], v[2:5]
	v_mfma_f32_16x16x32_bf16 v[54:57], v[150:153], v[204:207], v[54:57]
	v_mfma_f32_16x16x32_bf16 v[18:21], v[158:161], v[204:207], v[18:21]
	s_barrier
	s_setprio 0
	s_add_i32 s82, s82, 2
	s_add_u32 s80, s80, 0x100
	s_addc_u32 s81, s81, 0
	s_add_u32 s12, s12, 0x100
	s_addc_u32 s13, s13, 0
	s_cmp_gt_u32 s82, 61
	s_cbranch_scc0 .LBB0_825
	s_and_b64 vcc, exec, s[40:41]
	s_cbranch_vccz .LBB0_828
	s_barrier

; #define PG8_STAGE(bufoff, gbase, voff) do { _Pragma("unroll") for (int _i = 0; _i < 2; ++_i) \
;         __builtin_amdgcn_global_load_lds((const unsigned*)((const char*)(gbase) + (voff)[_i]), (PG8_LAS unsigned*)(lds + (bufoff) + ldsw + _i * 8192), 16, 0, 0); } while (0)
; #define PG8_LDA(dst, b, h) do { _Pragma("unroll") for (int m = 0; m < 4; ++m) _Pragma("unroll") for (int k = 0; k < 2; ++k) dst[m][k] = *(const PG8_LAS bf16x8*)(lds + PG8_SA(b, h) + aoff + m * 2048 + k * 1024); } while (0)
; #define PG8_LDB(dst, b, h) do { _Pragma("unroll") for (int n = 0; n < 2; ++n) _Pragma("unroll") for (int k = 0; k < 2; ++k) dst[n][k] = *(const PG8_LAS bf16x8*)(lds + PG8_SB(b, h) + boff + n * 2048 + k * 1024); } while (0)
; #define PG8_WAIT_V(n) asm volatile("s_waitcnt vmcnt(" #n ")" ::: "memory")
; #define PG8_WAIT_L(n) asm volatile("s_waitcnt lgkmcnt(" #n ")" ::: "memory")
; #define PG8_BAR __builtin_amdgcn_s_barrier()
; #define PG8_SCHED __builtin_amdgcn_sched_barrier(0)
; template <class Epi, class Sched, bool ALIGN_EPI = false, bool SP2 = false, bool F8 = false>
; __device__ __forceinline__ void gemm_phase(PG8_LAS unsigned char* lds, const Gemm g, const Sched& S, const Epi& E) {
;     ...
;             const bool last = (t == nt - 2);
;             const char* a1 = cA + (size_t)(t + 1) * kstep;
;             const char* a2 = last ? nA : cA + (size_t)(t + 2) * kstep; const char* b2 = last ? nB : cB + (size_t)(t + 2) * kstep;
;             const char* a3 = a2 + kstep; const char* b3 = b2 + kstep;
;             if (last && has_next) S.a_ready(nxt);
;             if constexpr (SP2) {
;             PG8_LDB(B0, 0, 0); PG8_LDB(B1, 0, 1); PG8_SCHED; PG8_LDA(At, 0, 0); PG8_STAGE(PG8_SA(1, 1), a1 + hA, voffA);
;             PG8_WAIT_V(8); PG8_WAIT_L(0); PG8_BAR; PG8_MMA(0, 0, At, B0); PG8_MMA(0, 1, At, B1); PG8_BAR; PG8_SCHED;
;             PG8_LDA(At, 0, 1); PG8_STAGE(PG8_SB(0, 0), b2, voffB); PG8_STAGE(PG8_SB(0, 1), b2 + hB, voffB); PG8_STAGE(PG8_SA(0, 0), a2, voffA);
.LBB0_883:
	ds_read_b128 v[130:133], v247
	ds_read_b128 v[134:137], v247 offset:1024
	ds_read_b128 v[138:141], v247 offset:2048
	ds_read_b128 v[142:145], v247 offset:3072
	ds_read_b128 v[146:149], v248
	ds_read_b128 v[150:153], v248 offset:1024
	ds_read_b128 v[154:157], v248 offset:2048
	ds_read_b128 v[158:161], v248 offset:3072
	s_add_u32 s14, s10, 0xfff00080
	s_addc_u32 s15, s11, -1
	s_cmp_eq_u32 s88, 12
	s_cselect_b32 s17, s13, s15
	s_cselect_b32 s16, s77, s14
	s_cselect_b32 s15, s79, s87
	s_cselect_b32 s14, s85, s86
	v_lshl_add_u64 v[212:213], s[10:11], 0, v[194:195]
	s_add_i32 m0, s6, 0xc000
	ds_read_b128 v[162:165], v249
	ds_read_b128 v[166:169], v249 offset:1024
	ds_read_b128 v[170:173], v249 offset:2048
	ds_read_b128 v[174:177], v249 offset:3072
	ds_read_b128 v[178:181], v249 offset:4096
	ds_read_b128 v[200:203], v249 offset:5120
	ds_read_b128 v[204:207], v249 offset:6144
	ds_read_b128 v[208:211], v249 offset:7168
	global_load_lds_dwordx4 v[212:213], off
	v_lshl_add_u64 v[212:213], s[10:11], 0, v[192:193]
	s_add_i32 m0, s6, 0xe000
	s_nop 0
	global_load_lds_dwordx4 v[212:213], off
	s_setprio 1
	s_waitcnt vmcnt(8)
	s_waitcnt lgkmcnt(0)
	s_barrier
	v_mfma_f32_16x16x32_bf16 v[126:129], v[130:133], v[162:165], v[126:129]
	v_mfma_f32_16x16x32_bf16 v[122:125], v[138:141], v[162:165], v[122:125]
	v_mfma_f32_16x16x32_bf16 v[118:121], v[130:133], v[170:173], v[118:121]
	v_mfma_f32_16x16x32_bf16 v[114:117], v[138:141], v[170:173], v[114:117]
	v_mfma_f32_16x16x32_bf16 v[110:113], v[130:133], v[178:181], v[110:113]
	v_mfma_f32_16x16x32_bf16 v[106:109], v[138:141], v[178:181], v[106:109]
	v_mfma_f32_16x16x32_bf16 v[102:105], v[130:133], v[204:207], v[102:105]
	v_mfma_f32_16x16x32_bf16 v[98:101], v[138:141], v[204:207], v[98:101]
	v_mfma_f32_16x16x32_bf16 v[126:129], v[134:137], v[166:169], v[126:129]
	v_mfma_f32_16x16x32_bf16 v[122:125], v[142:145], v[166:169], v[122:125]
	v_mfma_f32_16x16x32_bf16 v[118:121], v[134:137], v[174:177], v[118:121]
	v_mfma_f32_16x16x32_bf16 v[114:117], v[142:145], v[174:177], v[114:117]
	v_mfma_f32_16x16x32_bf16 v[110:113], v[134:137], v[200:203], v[110:113]
	v_mfma_f32_16x16x32_bf16 v[106:109], v[142:145], v[200:203], v[106:109]
	v_mfma_f32_16x16x32_bf16 v[102:105], v[134:137], v[208:211], v[102:105]
	v_mfma_f32_16x16x32_bf16 v[98:101], v[142:145], v[208:211], v[98:101]
	v_mfma_f32_16x16x32_bf16 v[82:85], v[146:149], v[162:165], v[82:85]
	v_mfma_f32_16x16x32_bf16 v[74:77], v[154:157], v[162:165], v[74:77]
	v_mfma_f32_16x16x32_bf16 v[94:97], v[146:149], v[170:173], v[94:97]
	v_mfma_f32_16x16x32_bf16 v[90:93], v[154:157], v[170:173], v[90:93]
	v_mfma_f32_16x16x32_bf16 v[86:89], v[146:149], v[178:181], v[86:89]
	v_mfma_f32_16x16x32_bf16 v[78:81], v[154:157], v[178:181], v[78:81]
	v_mfma_f32_16x16x32_bf16 v[70:73], v[146:149], v[204:207], v[70:73]
	v_mfma_f32_16x16x32_bf16 v[62:65], v[154:157], v[204:207], v[62:65]
	v_mfma_f32_16x16x32_bf16 v[82:85], v[150:153], v[166:169], v[82:85]
	v_mfma_f32_16x16x32_bf16 v[74:77], v[158:161], v[166:169], v[74:77]
	v_mfma_f32_16x16x32_bf16 v[94:97], v[150:153], v[174:177], v[94:97]
	v_mfma_f32_16x16x32_bf16 v[90:93], v[158:161], v[174:177], v[90:93]
	v_mfma_f32_16x16x32_bf16 v[86:89], v[150:153], v[200:203], v[86:89]
	v_mfma_f32_16x16x32_bf16 v[78:81], v[158:161], v[200:203], v[78:81]
	v_mfma_f32_16x16x32_bf16 v[70:73], v[150:153], v[208:211], v[70:73]
	v_mfma_f32_16x16x32_bf16 v[62:65], v[158:161], v[208:211], v[62:65]
	s_barrier
	s_setprio 0
	s_add_i32 s89, s54, s96
	v_lshl_add_u64 v[212:213], s[14:15], 0, v[184:185]
	s_mov_b32 m0, s89
	ds_read_b128 v[162:165], v249 offset:16384
	ds_read_b128 v[166:169], v249 offset:17408
	ds_read_b128 v[170:173], v249 offset:18432
	ds_read_b128 v[174:177], v249 offset:19456
	ds_read_b128 v[178:181], v249 offset:20480
	ds_read_b128 v[200:203], v249 offset:21504
	ds_read_b128 v[204:207], v249 offset:22528
	ds_read_b128 v[208:211], v249 offset:23552
	global_load_lds_dwordx4 v[212:213], off
	s_add_i32 m0, s89, 0x2000
	s_add_u32 s90, s14, 0x100000
	v_lshl_add_u64 v[214:215], s[14:15], 0, v[188:189]
	s_addc_u32 s91, s15, 0
	s_add_i32 s89, s55, s96
	global_load_lds_dwordx4 v[214:215], off
	v_lshl_add_u64 v[216:217], s[90:91], 0, v[184:185]
	s_mov_b32 m0, s89
	v_lshl_add_u64 v[218:219], s[16:17], 0, v[186:187]
	global_load_lds_dwordx4 v[216:217], off
	v_lshl_add_u64 v[216:217], s[90:91], 0, v[188:189]
	s_add_i32 m0, s89, 0x2000
	s_nop 0
	global_load_lds_dwordx4 v[216:217], off
	v_lshl_add_u64 v[216:217], s[16:17], 0, v[182:183]
	s_mov_b32 m0, s6
	s_nop 0
	global_load_lds_dwordx4 v[216:217], off
	s_mov_b32 m0, s7
	s_nop 0
	global_load_lds_dwordx4 v[218:219], off
	s_setprio 1
	s_waitcnt vmcnt(8)
	s_waitcnt lgkmcnt(0)
	s_barrier
; #define PG8_STAGE(bufoff, gbase, voff) do { _Pragma("unroll") for (int _i = 0; _i < 2; ++_i) \
;         __builtin_amdgcn_global_load_lds((const unsigned*)((const char*)(gbase) + (voff)[_i]), (PG8_LAS unsigned*)(lds + (bufoff) + ldsw + _i * 8192), 16, 0, 0); } while (0)
; #define PG8_LDA(dst, b, h) do { _Pragma("unroll") for (int m = 0; m < 4; ++m) _Pragma("unroll") for (int k = 0; k < 2; ++k) dst[m][k] = *(const PG8_LAS bf16x8*)(lds + PG8_SA(b, h) + aoff + m * 2048 + k * 1024); } while (0)
; #define PG8_LDB(dst, b, h) do { _Pragma("unroll") for (int n = 0; n < 2; ++n) _Pragma("unroll") for (int k = 0; k < 2; ++k) dst[n][k] = *(const PG8_LAS bf16x8*)(lds + PG8_SB(b, h) + boff + n * 2048 + k * 1024); } while (0)
; #define PG8_WAIT_V(n) asm volatile("s_waitcnt vmcnt(" #n ")" ::: "memory")
; #define PG8_WAIT_L(n) asm volatile("s_waitcnt lgkmcnt(" #n ")" ::: "memory")
; #define PG8_BAR __builtin_amdgcn_s_barrier()
; #define PG8_SCHED __builtin_amdgcn_sched_barrier(0)
; template <class Epi, class Sched, bool ALIGN_EPI = false, bool SP2 = false, bool F8 = false>
; __device__ __forceinline__ void gemm_phase(PG8_LAS unsigned char* lds, const Gemm g, const Sched& S, const Epi& E) {
;     ...
;             PG8_WAIT_V(8); PG8_WAIT_L(0); PG8_BAR; PG8_MMA(1, 0, At, B0); PG8_MMA(1, 1, At, B1); PG8_BAR; PG8_SCHED;
;             PG8_LDB(B0, 1, 0); PG8_LDB(B1, 1, 1); PG8_SCHED; PG8_LDA(At, 1, 0); PG8_STAGE(PG8_SA(0, 1), a2 + hA, voffA);
;             PG8_WAIT_V(8); PG8_WAIT_L(0); PG8_BAR; PG8_MMA(0, 0, At, B0); PG8_MMA(0, 1, At, B1); PG8_BAR; PG8_SCHED;
	v_mfma_f32_16x16x32_bf16 v[66:69], v[130:133], v[162:165], v[66:69]
	v_mfma_f32_16x16x32_bf16 v[58:61], v[138:141], v[162:165], v[58:61]
	v_mfma_f32_16x16x32_bf16 v[54:57], v[130:133], v[170:173], v[54:57]
	v_mfma_f32_16x16x32_bf16 v[50:53], v[138:141], v[170:173], v[50:53]
	v_mfma_f32_16x16x32_bf16 v[46:49], v[130:133], v[178:181], v[46:49]
	v_mfma_f32_16x16x32_bf16 v[42:45], v[138:141], v[178:181], v[42:45]
	v_mfma_f32_16x16x32_bf16 v[38:41], v[130:133], v[204:207], v[38:41]
	v_mfma_f32_16x16x32_bf16 v[34:37], v[138:141], v[204:207], v[34:37]
	v_mfma_f32_16x16x32_bf16 v[66:69], v[134:137], v[166:169], v[66:69]
	v_mfma_f32_16x16x32_bf16 v[58:61], v[142:145], v[166:169], v[58:61]
	v_mfma_f32_16x16x32_bf16 v[54:57], v[134:137], v[174:177], v[54:57]
	v_mfma_f32_16x16x32_bf16 v[50:53], v[142:145], v[174:177], v[50:53]
	v_mfma_f32_16x16x32_bf16 v[46:49], v[134:137], v[200:203], v[46:49]
	v_mfma_f32_16x16x32_bf16 v[42:45], v[142:145], v[200:203], v[42:45]
	v_mfma_f32_16x16x32_bf16 v[38:41], v[134:137], v[208:211], v[38:41]
	v_mfma_f32_16x16x32_bf16 v[34:37], v[142:145], v[208:211], v[34:37]
	v_mfma_f32_16x16x32_bf16 v[30:33], v[146:149], v[162:165], v[30:33]
	v_mfma_f32_16x16x32_bf16 v[18:21], v[154:157], v[162:165], v[18:21]
	v_mfma_f32_16x16x32_bf16 v[26:29], v[146:149], v[170:173], v[26:29]
	v_mfma_f32_16x16x32_bf16 v[22:25], v[154:157], v[170:173], v[22:25]
	v_mfma_f32_16x16x32_bf16 v[14:17], v[146:149], v[178:181], v[14:17]
	v_mfma_f32_16x16x32_bf16 v[10:13], v[154:157], v[178:181], v[10:13]
	v_mfma_f32_16x16x32_bf16 v[6:9], v[146:149], v[204:207], v[6:9]
	v_mfma_f32_16x16x32_bf16 v[2:5], v[154:157], v[204:207], v[2:5]
	v_mfma_f32_16x16x32_bf16 v[30:33], v[150:153], v[166:169], v[30:33]
	v_mfma_f32_16x16x32_bf16 v[18:21], v[158:161], v[166:169], v[18:21]
	v_mfma_f32_16x16x32_bf16 v[26:29], v[150:153], v[174:177], v[26:29]
	v_mfma_f32_16x16x32_bf16 v[22:25], v[158:161], v[174:177], v[22:25]
	v_mfma_f32_16x16x32_bf16 v[14:17], v[150:153], v[200:203], v[14:17]
	v_mfma_f32_16x16x32_bf16 v[10:13], v[158:161], v[200:203], v[10:13]
	v_mfma_f32_16x16x32_bf16 v[6:9], v[150:153], v[208:211], v[6:9]
	v_mfma_f32_16x16x32_bf16 v[2:5], v[158:161], v[208:211], v[2:5]
	s_barrier
	s_setprio 0
	s_add_i32 s89, 0, 0x18000
	s_add_i32 s90, 0, 0x1c000
	v_add_u32_e32 v142, s89, v245
	v_add_u32_e32 v158, s90, v245
	ds_read_b128 v[130:133], v142
	ds_read_b128 v[134:137], v142 offset:1024
	ds_read_b128 v[138:141], v142 offset:2048
	ds_read_b128 v[142:145], v142 offset:3072
	ds_read_b128 v[146:149], v158
	ds_read_b128 v[150:153], v158 offset:1024
	ds_read_b128 v[154:157], v158 offset:2048
	ds_read_b128 v[158:161], v158 offset:3072
	s_add_u32 s16, s16, 0x100000
	s_addc_u32 s17, s17, 0
	s_mov_b32 m0, s5
	v_lshl_add_u64 v[220:221], s[16:17], 0, v[182:183]
	ds_read_b128 v[162:165], v249 offset:32768
	ds_read_b128 v[166:169], v249 offset:33792
	ds_read_b128 v[170:173], v249 offset:34816
	ds_read_b128 v[174:177], v249 offset:35840
	ds_read_b128 v[178:181], v249 offset:36864
	ds_read_b128 v[200:203], v249 offset:37888
	ds_read_b128 v[204:207], v249 offset:38912
	ds_read_b128 v[208:211], v249 offset:39936
	global_load_lds_dwordx4 v[220:221], off
	v_lshl_add_u64 v[220:221], s[16:17], 0, v[186:187]
	s_mov_b32 m0, s18
	s_nop 0
	global_load_lds_dwordx4 v[220:221], off
	s_setprio 1
	s_waitcnt vmcnt(8)
	s_waitcnt lgkmcnt(0)
	s_barrier
	v_mfma_f32_16x16x32_bf16 v[126:129], v[130:133], v[162:165], v[126:129]
	v_mfma_f32_16x16x32_bf16 v[122:125], v[138:141], v[162:165], v[122:125]
	v_mfma_f32_16x16x32_bf16 v[118:121], v[130:133], v[170:173], v[118:121]
	v_mfma_f32_16x16x32_bf16 v[114:117], v[138:141], v[170:173], v[114:117]
	v_mfma_f32_16x16x32_bf16 v[110:113], v[130:133], v[178:181], v[110:113]
	v_mfma_f32_16x16x32_bf16 v[106:109], v[138:141], v[178:181], v[106:109]
	v_mfma_f32_16x16x32_bf16 v[102:105], v[130:133], v[204:207], v[102:105]
	v_mfma_f32_16x16x32_bf16 v[98:101], v[138:141], v[204:207], v[98:101]
	v_mfma_f32_16x16x32_bf16 v[126:129], v[134:137], v[166:169], v[126:129]
	v_mfma_f32_16x16x32_bf16 v[122:125], v[142:145], v[166:169], v[122:125]
	v_mfma_f32_16x16x32_bf16 v[118:121], v[134:137], v[174:177], v[118:121]
	v_mfma_f32_16x16x32_bf16 v[114:117], v[142:145], v[174:177], v[114:117]
	v_mfma_f32_16x16x32_bf16 v[110:113], v[134:137], v[200:203], v[110:113]
	v_mfma_f32_16x16x32_bf16 v[106:109], v[142:145], v[200:203], v[106:109]
	v_mfma_f32_16x16x32_bf16 v[102:105], v[134:137], v[208:211], v[102:105]
	v_mfma_f32_16x16x32_bf16 v[98:101], v[142:145], v[208:211], v[98:101]
	v_mfma_f32_16x16x32_bf16 v[82:85], v[146:149], v[162:165], v[82:85]
	v_mfma_f32_16x16x32_bf16 v[74:77], v[154:157], v[162:165], v[74:77]
	v_mfma_f32_16x16x32_bf16 v[94:97], v[146:149], v[170:173], v[94:97]
	v_mfma_f32_16x16x32_bf16 v[90:93], v[154:157], v[170:173], v[90:93]
	v_mfma_f32_16x16x32_bf16 v[86:89], v[146:149], v[178:181], v[86:89]
	v_mfma_f32_16x16x32_bf16 v[78:81], v[154:157], v[178:181], v[78:81]
	v_mfma_f32_16x16x32_bf16 v[70:73], v[146:149], v[204:207], v[70:73]
	v_mfma_f32_16x16x32_bf16 v[62:65], v[154:157], v[204:207], v[62:65]
	v_mfma_f32_16x16x32_bf16 v[82:85], v[150:153], v[166:169], v[82:85]
	v_mfma_f32_16x16x32_bf16 v[74:77], v[158:161], v[166:169], v[74:77]
	v_mfma_f32_16x16x32_bf16 v[94:97], v[150:153], v[174:177], v[94:97]
	v_mfma_f32_16x16x32_bf16 v[90:93], v[158:161], v[174:177], v[90:93]
	v_mfma_f32_16x16x32_bf16 v[86:89], v[150:153], v[200:203], v[86:89]
	v_mfma_f32_16x16x32_bf16 v[78:81], v[158:161], v[200:203], v[78:81]
	v_mfma_f32_16x16x32_bf16 v[70:73], v[150:153], v[208:211], v[70:73]
	v_mfma_f32_16x16x32_bf16 v[62:65], v[158:161], v[208:211], v[62:65]
	s_barrier
; #define PG8_STAGE(bufoff, gbase, voff) do { _Pragma("unroll") for (int _i = 0; _i < 2; ++_i) \
;         __builtin_amdgcn_global_load_lds((const unsigned*)((const char*)(gbase) + (voff)[_i]), (PG8_LAS unsigned*)(lds + (bufoff) + ldsw + _i * 8192), 16, 0, 0); } while (0)
; #define PG8_LDA(dst, b, h) do { _Pragma("unroll") for (int m = 0; m < 4; ++m) _Pragma("unroll") for (int k = 0; k < 2; ++k) dst[m][k] = *(const PG8_LAS bf16x8*)(lds + PG8_SA(b, h) + aoff + m * 2048 + k * 1024); } while (0)
; #define PG8_WAIT_V(n) asm volatile("s_waitcnt vmcnt(" #n ")" ::: "memory")
; #define PG8_WAIT_L(n) asm volatile("s_waitcnt lgkmcnt(" #n ")" ::: "memory")
; #define PG8_BAR __builtin_amdgcn_s_barrier()
; #define PG8_SCHED __builtin_amdgcn_sched_barrier(0)
; template <class Epi, class Sched, bool ALIGN_EPI = false, bool SP2 = false, bool F8 = false>
; __device__ __forceinline__ void gemm_phase(PG8_LAS unsigned char* lds, const Gemm g, const Sched& S, const Epi& E) {
;     ...
;             PG8_LDA(At, 1, 1); PG8_STAGE(PG8_SB(1, 0), b3, voffB); PG8_STAGE(PG8_SB(1, 1), b3 + hB, voffB); PG8_STAGE(PG8_SA(1, 0), a3, voffA);
;             PG8_WAIT_V(8); PG8_WAIT_L(0); PG8_BAR; PG8_MMA(1, 0, At, B0); PG8_MMA(1, 1, At, B1); PG8_BAR; PG8_SCHED;
	s_setprio 0
	s_add_i32 s16, s89, s96
	v_lshl_add_u64 v[212:213], v[212:213], 0, s[34:35]
	s_mov_b32 m0, s16
	ds_read_b128 v[162:165], v249 offset:49152
	ds_read_b128 v[166:169], v249 offset:50176
	ds_read_b128 v[170:173], v249 offset:51200
	ds_read_b128 v[174:177], v249 offset:52224
	ds_read_b128 v[178:181], v249 offset:53248
	ds_read_b128 v[200:203], v249 offset:54272
	ds_read_b128 v[204:207], v249 offset:55296
	ds_read_b128 v[208:211], v249 offset:56320
	global_load_lds_dwordx4 v[212:213], off
	s_add_i32 m0, s16, 0x2000
	s_add_u32 s14, s14, 0x100080
	v_lshl_add_u64 v[212:213], v[214:215], 0, s[34:35]
	s_addc_u32 s15, s15, 0
	s_add_i32 s16, s90, s96
	global_load_lds_dwordx4 v[212:213], off
	v_lshl_add_u64 v[212:213], s[14:15], 0, v[184:185]
	s_mov_b32 m0, s16
	s_nop 0
	global_load_lds_dwordx4 v[212:213], off
	v_lshl_add_u64 v[212:213], s[14:15], 0, v[188:189]
	s_add_i32 m0, s16, 0x2000
	s_nop 0
	global_load_lds_dwordx4 v[212:213], off
	v_lshl_add_u64 v[212:213], v[216:217], 0, s[34:35]
	s_mov_b32 m0, s31
	s_nop 0
	global_load_lds_dwordx4 v[212:213], off
	v_lshl_add_u64 v[212:213], v[218:219], 0, s[34:35]
	s_mov_b32 m0, s50
	s_nop 0
	global_load_lds_dwordx4 v[212:213], off
	s_setprio 1
	s_waitcnt vmcnt(8)
	s_waitcnt lgkmcnt(0)
	s_barrier
	v_mfma_f32_16x16x32_bf16 v[66:69], v[130:133], v[162:165], v[66:69]
	v_mfma_f32_16x16x32_bf16 v[58:61], v[138:141], v[162:165], v[58:61]
	v_mfma_f32_16x16x32_bf16 v[54:57], v[130:133], v[170:173], v[54:57]
	v_mfma_f32_16x16x32_bf16 v[50:53], v[138:141], v[170:173], v[50:53]
	v_mfma_f32_16x16x32_bf16 v[46:49], v[130:133], v[178:181], v[46:49]
	v_mfma_f32_16x16x32_bf16 v[42:45], v[138:141], v[178:181], v[42:45]
	v_mfma_f32_16x16x32_bf16 v[38:41], v[130:133], v[204:207], v[38:41]
	v_mfma_f32_16x16x32_bf16 v[34:37], v[138:141], v[204:207], v[34:37]
	v_mfma_f32_16x16x32_bf16 v[66:69], v[134:137], v[166:169], v[66:69]
	v_mfma_f32_16x16x32_bf16 v[58:61], v[142:145], v[166:169], v[58:61]
	v_mfma_f32_16x16x32_bf16 v[54:57], v[134:137], v[174:177], v[54:57]
	v_mfma_f32_16x16x32_bf16 v[50:53], v[142:145], v[174:177], v[50:53]
	v_mfma_f32_16x16x32_bf16 v[46:49], v[134:137], v[200:203], v[46:49]
	v_mfma_f32_16x16x32_bf16 v[42:45], v[142:145], v[200:203], v[42:45]
	v_mfma_f32_16x16x32_bf16 v[38:41], v[134:137], v[208:211], v[38:41]
	v_mfma_f32_16x16x32_bf16 v[34:37], v[142:145], v[208:211], v[34:37]
	v_mfma_f32_16x16x32_bf16 v[30:33], v[146:149], v[162:165], v[30:33]
	v_mfma_f32_16x16x32_bf16 v[18:21], v[154:157], v[162:165], v[18:21]
	v_mfma_f32_16x16x32_bf16 v[26:29], v[146:149], v[170:173], v[26:29]
	v_mfma_f32_16x16x32_bf16 v[22:25], v[154:157], v[170:173], v[22:25]
	v_mfma_f32_16x16x32_bf16 v[14:17], v[146:149], v[178:181], v[14:17]
	v_mfma_f32_16x16x32_bf16 v[10:13], v[154:157], v[178:181], v[10:13]
	v_mfma_f32_16x16x32_bf16 v[6:9], v[146:149], v[204:207], v[6:9]
	v_mfma_f32_16x16x32_bf16 v[2:5], v[154:157], v[204:207], v[2:5]
	v_mfma_f32_16x16x32_bf16 v[30:33], v[150:153], v[166:169], v[30:33]
	v_mfma_f32_16x16x32_bf16 v[18:21], v[158:161], v[166:169], v[18:21]
	v_mfma_f32_16x16x32_bf16 v[26:29], v[150:153], v[174:177], v[26:29]
	v_mfma_f32_16x16x32_bf16 v[22:25], v[158:161], v[174:177], v[22:25]
	v_mfma_f32_16x16x32_bf16 v[14:17], v[150:153], v[200:203], v[14:17]
	v_mfma_f32_16x16x32_bf16 v[10:13], v[158:161], v[200:203], v[10:13]
	v_mfma_f32_16x16x32_bf16 v[6:9], v[150:153], v[208:211], v[6:9]
	v_mfma_f32_16x16x32_bf16 v[2:5], v[158:161], v[208:211], v[2:5]
	s_barrier
	s_setprio 0
	s_add_i32 s88, s88, 2
	s_add_u32 s86, s86, 0x100
	s_addc_u32 s87, s87, 0
	s_add_u32 s10, s10, 0x100
	s_addc_u32 s11, s11, 0
	s_cmp_gt_u32 s88, 13
	s_cbranch_scc0 .LBB0_883
	s_and_b64 vcc, exec, s[36:37]
	s_cbranch_vccz .LBB0_886
	s_barrier

; #define PG8_STAGE(bufoff, gbase, voff) do { _Pragma("unroll") for (int _i = 0; _i < 2; ++_i) \
;         __builtin_amdgcn_global_load_lds((const unsigned*)((const char*)(gbase) + (voff)[_i]), (PG8_LAS unsigned*)(lds + (bufoff) + ldsw + _i * 8192), 16, 0, 0); } while (0)
; #define PG8_LDA(dst, b, h) do { _Pragma("unroll") for (int m = 0; m < 4; ++m) _Pragma("unroll") for (int k = 0; k < 2; ++k) dst[m][k] = *(const PG8_LAS bf16x8*)(lds + PG8_SA(b, h) + aoff + m * 2048 + k * 1024); } while (0)
; #define PG8_LDB(dst, b, h) do { _Pragma("unroll") for (int n = 0; n < 2; ++n) _Pragma("unroll") for (int k = 0; k < 2; ++k) dst[n][k] = *(const PG8_LAS bf16x8*)(lds + PG8_SB(b, h) + boff + n * 2048 + k * 1024); } while (0)
; #define PG8_WAIT_V(n) asm volatile("s_waitcnt vmcnt(" #n ")" ::: "memory")
; #define PG8_WAIT_L(n) asm volatile("s_waitcnt lgkmcnt(" #n ")" ::: "memory")
; #define PG8_BAR __builtin_amdgcn_s_barrier()
; #define PG8_SCHED __builtin_amdgcn_sched_barrier(0)
; template <class Epi, class Sched, bool ALIGN_EPI = false, bool SP2 = false, bool F8 = false>
; __device__ __forceinline__ void gemm_phase(PG8_LAS unsigned char* lds, const Gemm g, const Sched& S, const Epi& E) {
;     ...
;             const bool last = (t == nt - 2);
;             const char* a1 = cA + (size_t)(t + 1) * kstep;
;             const char* a2 = last ? nA : cA + (size_t)(t + 2) * kstep; const char* b2 = last ? nB : cB + (size_t)(t + 2) * kstep;
;             const char* a3 = a2 + kstep; const char* b3 = b2 + kstep;
;             if (last && has_next) S.a_ready(nxt);
;             if constexpr (SP2) {
;             PG8_LDB(B0, 0, 0); PG8_LDB(B1, 0, 1); PG8_SCHED; PG8_LDA(At, 0, 0); PG8_STAGE(PG8_SA(1, 1), a1 + hA, voffA);
;             PG8_WAIT_V(8); PG8_WAIT_L(0); PG8_BAR; PG8_MMA(0, 0, At, B0); PG8_MMA(0, 1, At, B1); PG8_BAR; PG8_SCHED;
;             PG8_LDA(At, 0, 1); PG8_STAGE(PG8_SB(0, 0), b2, voffB); PG8_STAGE(PG8_SB(0, 1), b2 + hB, voffB); PG8_STAGE(PG8_SA(0, 0), a2, voffA);
.LBB0_1078:
	ds_read_b128 v[130:133], v197
	ds_read_b128 v[134:137], v197 offset:1024
	ds_read_b128 v[138:141], v197 offset:2048
	ds_read_b128 v[142:145], v197 offset:3072
	ds_read_b128 v[146:149], v198
	ds_read_b128 v[150:153], v198 offset:1024
	ds_read_b128 v[154:157], v198 offset:2048
	ds_read_b128 v[158:161], v198 offset:3072
	s_add_u32 s28, s26, 0x100
	s_addc_u32 s29, s27, 0
	s_cmpk_eq_i32 s55, 0xa8
	s_cselect_b32 s35, s7, s29
	s_cselect_b32 s34, s6, s28
	s_cselect_b32 s31, s9, s54
	s_cselect_b32 s30, s8, s53
	v_lshl_add_u64 v[216:217], s[26:27], 0, v[176:177]
	s_add_i32 m0, s39, 0xc000
	ds_read_b128 v[162:165], v199
	ds_read_b128 v[182:185], v199 offset:1024
	ds_read_b128 v[186:189], v199 offset:2048
	ds_read_b128 v[190:193], v199 offset:3072
	ds_read_b128 v[200:203], v199 offset:4096
	ds_read_b128 v[204:207], v199 offset:5120
	ds_read_b128 v[208:211], v199 offset:6144
	ds_read_b128 v[212:215], v199 offset:7168
	global_load_lds_dwordx4 v[216:217], off
	v_lshl_add_u64 v[216:217], s[26:27], 0, v[174:175]
	s_add_i32 m0, s39, 0xe000
	s_nop 0
	global_load_lds_dwordx4 v[216:217], off
	s_setprio 1
	s_waitcnt vmcnt(8)
	s_waitcnt lgkmcnt(0)
	s_barrier
	v_mfma_f32_16x16x32_bf16 v[126:129], v[130:133], v[162:165], v[126:129]
	v_mfma_f32_16x16x32_bf16 v[122:125], v[138:141], v[162:165], v[122:125]
	v_mfma_f32_16x16x32_bf16 v[118:121], v[130:133], v[186:189], v[118:121]
	v_mfma_f32_16x16x32_bf16 v[106:109], v[138:141], v[186:189], v[106:109]
	v_mfma_f32_16x16x32_bf16 v[98:101], v[130:133], v[200:203], v[98:101]
	v_mfma_f32_16x16x32_bf16 v[90:93], v[138:141], v[200:203], v[90:93]
	v_mfma_f32_16x16x32_bf16 v[82:85], v[130:133], v[208:211], v[82:85]
	v_mfma_f32_16x16x32_bf16 v[74:77], v[138:141], v[208:211], v[74:77]
	v_mfma_f32_16x16x32_bf16 v[126:129], v[134:137], v[182:185], v[126:129]
	v_mfma_f32_16x16x32_bf16 v[122:125], v[142:145], v[182:185], v[122:125]
	v_mfma_f32_16x16x32_bf16 v[118:121], v[134:137], v[190:193], v[118:121]
	v_mfma_f32_16x16x32_bf16 v[106:109], v[142:145], v[190:193], v[106:109]
	v_mfma_f32_16x16x32_bf16 v[98:101], v[134:137], v[204:207], v[98:101]
	v_mfma_f32_16x16x32_bf16 v[90:93], v[142:145], v[204:207], v[90:93]
	v_mfma_f32_16x16x32_bf16 v[82:85], v[134:137], v[212:215], v[82:85]
	v_mfma_f32_16x16x32_bf16 v[74:77], v[142:145], v[212:215], v[74:77]
	v_mfma_f32_16x16x32_bf16 v[114:117], v[146:149], v[162:165], v[114:117]
	v_mfma_f32_16x16x32_bf16 v[110:113], v[154:157], v[162:165], v[110:113]
	v_mfma_f32_16x16x32_bf16 v[102:105], v[146:149], v[186:189], v[102:105]
	v_mfma_f32_16x16x32_bf16 v[94:97], v[154:157], v[186:189], v[94:97]
	v_mfma_f32_16x16x32_bf16 v[86:89], v[146:149], v[200:203], v[86:89]
	v_mfma_f32_16x16x32_bf16 v[78:81], v[154:157], v[200:203], v[78:81]
	v_mfma_f32_16x16x32_bf16 v[70:73], v[146:149], v[208:211], v[70:73]
	v_mfma_f32_16x16x32_bf16 v[66:69], v[154:157], v[208:211], v[66:69]
	v_mfma_f32_16x16x32_bf16 v[114:117], v[150:153], v[182:185], v[114:117]
	v_mfma_f32_16x16x32_bf16 v[110:113], v[158:161], v[182:185], v[110:113]
	v_mfma_f32_16x16x32_bf16 v[102:105], v[150:153], v[190:193], v[102:105]
	v_mfma_f32_16x16x32_bf16 v[94:97], v[158:161], v[190:193], v[94:97]
	v_mfma_f32_16x16x32_bf16 v[86:89], v[150:153], v[204:207], v[86:89]
	v_mfma_f32_16x16x32_bf16 v[78:81], v[158:161], v[204:207], v[78:81]
	v_mfma_f32_16x16x32_bf16 v[70:73], v[150:153], v[212:215], v[70:73]
	v_mfma_f32_16x16x32_bf16 v[66:69], v[158:161], v[212:215], v[66:69]
	s_barrier
	s_setprio 0
	s_add_i32 s26, s47, s36
	v_lshl_add_u64 v[216:217], s[30:31], 0, v[170:171]
	s_mov_b32 m0, s26
	ds_read_b128 v[162:165], v199 offset:16384
	ds_read_b128 v[182:185], v199 offset:17408
	ds_read_b128 v[186:189], v199 offset:18432
	ds_read_b128 v[190:193], v199 offset:19456
	ds_read_b128 v[200:203], v199 offset:20480
	ds_read_b128 v[204:207], v199 offset:21504
	ds_read_b128 v[208:211], v199 offset:22528
	ds_read_b128 v[212:215], v199 offset:23552
	global_load_lds_dwordx4 v[216:217], off
	s_add_i32 m0, s26, 0x2000
	s_add_u32 s26, s30, 0x2b0000
	v_lshl_add_u64 v[218:219], s[30:31], 0, v[166:167]
	s_addc_u32 s27, s31, 0
	s_add_i32 s56, s48, s36
	global_load_lds_dwordx4 v[218:219], off
	v_lshl_add_u64 v[220:221], s[26:27], 0, v[170:171]
	s_mov_b32 m0, s56
	v_lshl_add_u64 v[222:223], s[34:35], 0, v[168:169]
	global_load_lds_dwordx4 v[220:221], off
	v_lshl_add_u64 v[220:221], s[26:27], 0, v[166:167]
	s_add_i32 m0, s56, 0x2000
	s_nop 0
	global_load_lds_dwordx4 v[220:221], off
	v_lshl_add_u64 v[220:221], s[34:35], 0, v[172:173]
	s_mov_b32 m0, s39
	s_nop 0
	global_load_lds_dwordx4 v[220:221], off
	s_mov_b32 m0, s40
	s_nop 0
	global_load_lds_dwordx4 v[222:223], off
	s_setprio 1
	s_waitcnt vmcnt(8)
	s_waitcnt lgkmcnt(0)
	s_barrier
; #define PG8_STAGE(bufoff, gbase, voff) do { _Pragma("unroll") for (int _i = 0; _i < 2; ++_i) \
;         __builtin_amdgcn_global_load_lds((const unsigned*)((const char*)(gbase) + (voff)[_i]), (PG8_LAS unsigned*)(lds + (bufoff) + ldsw + _i * 8192), 16, 0, 0); } while (0)
; #define PG8_LDA(dst, b, h) do { _Pragma("unroll") for (int m = 0; m < 4; ++m) _Pragma("unroll") for (int k = 0; k < 2; ++k) dst[m][k] = *(const PG8_LAS bf16x8*)(lds + PG8_SA(b, h) + aoff + m * 2048 + k * 1024); } while (0)
; #define PG8_LDB(dst, b, h) do { _Pragma("unroll") for (int n = 0; n < 2; ++n) _Pragma("unroll") for (int k = 0; k < 2; ++k) dst[n][k] = *(const PG8_LAS bf16x8*)(lds + PG8_SB(b, h) + boff + n * 2048 + k * 1024); } while (0)
; #define PG8_WAIT_V(n) asm volatile("s_waitcnt vmcnt(" #n ")" ::: "memory")
; #define PG8_WAIT_L(n) asm volatile("s_waitcnt lgkmcnt(" #n ")" ::: "memory")
; #define PG8_BAR __builtin_amdgcn_s_barrier()
; #define PG8_SCHED __builtin_amdgcn_sched_barrier(0)
; template <class Epi, class Sched, bool ALIGN_EPI = false, bool SP2 = false, bool F8 = false>
; __device__ __forceinline__ void gemm_phase(PG8_LAS unsigned char* lds, const Gemm g, const Sched& S, const Epi& E) {
;     ...
;             PG8_WAIT_V(8); PG8_WAIT_L(0); PG8_BAR; PG8_MMA(1, 0, At, B0); PG8_MMA(1, 1, At, B1); PG8_BAR; PG8_SCHED;
;             PG8_LDB(B0, 1, 0); PG8_LDB(B1, 1, 1); PG8_SCHED; PG8_LDA(At, 1, 0); PG8_STAGE(PG8_SA(0, 1), a2 + hA, voffA);
;             PG8_WAIT_V(8); PG8_WAIT_L(0); PG8_BAR; PG8_MMA(0, 0, At, B0); PG8_MMA(0, 1, At, B1); PG8_BAR; PG8_SCHED;
	v_mfma_f32_16x16x32_bf16 v[62:65], v[130:133], v[162:165], v[62:65]
	v_mfma_f32_16x16x32_bf16 v[58:61], v[138:141], v[162:165], v[58:61]
	v_mfma_f32_16x16x32_bf16 v[50:53], v[130:133], v[186:189], v[50:53]
	v_mfma_f32_16x16x32_bf16 v[42:45], v[138:141], v[186:189], v[42:45]
	v_mfma_f32_16x16x32_bf16 v[34:37], v[130:133], v[200:203], v[34:37]
	v_mfma_f32_16x16x32_bf16 v[26:29], v[138:141], v[200:203], v[26:29]
	v_mfma_f32_16x16x32_bf16 v[18:21], v[130:133], v[208:211], v[18:21]
	v_mfma_f32_16x16x32_bf16 v[10:13], v[138:141], v[208:211], v[10:13]
	v_mfma_f32_16x16x32_bf16 v[62:65], v[134:137], v[182:185], v[62:65]
	v_mfma_f32_16x16x32_bf16 v[58:61], v[142:145], v[182:185], v[58:61]
	v_mfma_f32_16x16x32_bf16 v[50:53], v[134:137], v[190:193], v[50:53]
	v_mfma_f32_16x16x32_bf16 v[42:45], v[142:145], v[190:193], v[42:45]
	v_mfma_f32_16x16x32_bf16 v[34:37], v[134:137], v[204:207], v[34:37]
	v_mfma_f32_16x16x32_bf16 v[26:29], v[142:145], v[204:207], v[26:29]
	v_mfma_f32_16x16x32_bf16 v[18:21], v[134:137], v[212:215], v[18:21]
	v_mfma_f32_16x16x32_bf16 v[10:13], v[142:145], v[212:215], v[10:13]
	v_mfma_f32_16x16x32_bf16 v[54:57], v[146:149], v[162:165], v[54:57]
	v_mfma_f32_16x16x32_bf16 v[46:49], v[154:157], v[162:165], v[46:49]
	v_mfma_f32_16x16x32_bf16 v[38:41], v[146:149], v[186:189], v[38:41]
	v_mfma_f32_16x16x32_bf16 v[30:33], v[154:157], v[186:189], v[30:33]
	v_mfma_f32_16x16x32_bf16 v[22:25], v[146:149], v[200:203], v[22:25]
	v_mfma_f32_16x16x32_bf16 v[14:17], v[154:157], v[200:203], v[14:17]
	v_mfma_f32_16x16x32_bf16 v[6:9], v[146:149], v[208:211], v[6:9]
	v_mfma_f32_16x16x32_bf16 v[2:5], v[154:157], v[208:211], v[2:5]
	v_mfma_f32_16x16x32_bf16 v[54:57], v[150:153], v[182:185], v[54:57]
	v_mfma_f32_16x16x32_bf16 v[46:49], v[158:161], v[182:185], v[46:49]
	v_mfma_f32_16x16x32_bf16 v[38:41], v[150:153], v[190:193], v[38:41]
	v_mfma_f32_16x16x32_bf16 v[30:33], v[158:161], v[190:193], v[30:33]
	v_mfma_f32_16x16x32_bf16 v[22:25], v[150:153], v[204:207], v[22:25]
	v_mfma_f32_16x16x32_bf16 v[14:17], v[158:161], v[204:207], v[14:17]
	v_mfma_f32_16x16x32_bf16 v[6:9], v[150:153], v[212:215], v[6:9]
	v_mfma_f32_16x16x32_bf16 v[2:5], v[158:161], v[212:215], v[2:5]
	s_barrier
	s_setprio 0
	s_add_i32 s56, 0, 0x18000
	s_add_i32 s57, 0, 0x1c000
	v_add_u32_e32 v142, s56, v195
	v_add_u32_e32 v158, s57, v195
	ds_read_b128 v[130:133], v142
	ds_read_b128 v[134:137], v142 offset:1024
	ds_read_b128 v[138:141], v142 offset:2048
	ds_read_b128 v[142:145], v142 offset:3072
	ds_read_b128 v[146:149], v158
	ds_read_b128 v[150:153], v158 offset:1024
	ds_read_b128 v[154:157], v158 offset:2048
	ds_read_b128 v[158:161], v158 offset:3072
	s_add_u32 s26, s34, 0x2b0000
	s_addc_u32 s27, s35, 0
	s_mov_b32 m0, s41
	v_lshl_add_u64 v[224:225], s[26:27], 0, v[172:173]
	ds_read_b128 v[162:165], v199 offset:32768
	ds_read_b128 v[182:185], v199 offset:33792
	ds_read_b128 v[186:189], v199 offset:34816
	ds_read_b128 v[190:193], v199 offset:35840
	ds_read_b128 v[200:203], v199 offset:36864
	ds_read_b128 v[204:207], v199 offset:37888
	ds_read_b128 v[208:211], v199 offset:38912
	ds_read_b128 v[212:215], v199 offset:39936
	global_load_lds_dwordx4 v[224:225], off
	v_lshl_add_u64 v[224:225], s[26:27], 0, v[168:169]
	s_mov_b32 m0, s42
	s_nop 0
	global_load_lds_dwordx4 v[224:225], off
	s_setprio 1
	s_waitcnt vmcnt(8)
	s_waitcnt lgkmcnt(0)
	s_barrier
	v_mfma_f32_16x16x32_bf16 v[126:129], v[130:133], v[162:165], v[126:129]
	v_mfma_f32_16x16x32_bf16 v[122:125], v[138:141], v[162:165], v[122:125]
	v_mfma_f32_16x16x32_bf16 v[118:121], v[130:133], v[186:189], v[118:121]
	v_mfma_f32_16x16x32_bf16 v[106:109], v[138:141], v[186:189], v[106:109]
	v_mfma_f32_16x16x32_bf16 v[98:101], v[130:133], v[200:203], v[98:101]
	v_mfma_f32_16x16x32_bf16 v[90:93], v[138:141], v[200:203], v[90:93]
	v_mfma_f32_16x16x32_bf16 v[82:85], v[130:133], v[208:211], v[82:85]
	v_mfma_f32_16x16x32_bf16 v[74:77], v[138:141], v[208:211], v[74:77]
	v_mfma_f32_16x16x32_bf16 v[126:129], v[134:137], v[182:185], v[126:129]
	v_mfma_f32_16x16x32_bf16 v[122:125], v[142:145], v[182:185], v[122:125]
	v_mfma_f32_16x16x32_bf16 v[118:121], v[134:137], v[190:193], v[118:121]
	v_mfma_f32_16x16x32_bf16 v[106:109], v[142:145], v[190:193], v[106:109]
	v_mfma_f32_16x16x32_bf16 v[98:101], v[134:137], v[204:207], v[98:101]
	v_mfma_f32_16x16x32_bf16 v[90:93], v[142:145], v[204:207], v[90:93]
	v_mfma_f32_16x16x32_bf16 v[82:85], v[134:137], v[212:215], v[82:85]
	v_mfma_f32_16x16x32_bf16 v[74:77], v[142:145], v[212:215], v[74:77]
	v_mfma_f32_16x16x32_bf16 v[114:117], v[146:149], v[162:165], v[114:117]
	v_mfma_f32_16x16x32_bf16 v[110:113], v[154:157], v[162:165], v[110:113]
	v_mfma_f32_16x16x32_bf16 v[102:105], v[146:149], v[186:189], v[102:105]
	v_mfma_f32_16x16x32_bf16 v[94:97], v[154:157], v[186:189], v[94:97]
	v_mfma_f32_16x16x32_bf16 v[86:89], v[146:149], v[200:203], v[86:89]
	v_mfma_f32_16x16x32_bf16 v[78:81], v[154:157], v[200:203], v[78:81]
	v_mfma_f32_16x16x32_bf16 v[70:73], v[146:149], v[208:211], v[70:73]
	v_mfma_f32_16x16x32_bf16 v[66:69], v[154:157], v[208:211], v[66:69]
	v_mfma_f32_16x16x32_bf16 v[114:117], v[150:153], v[182:185], v[114:117]
	v_mfma_f32_16x16x32_bf16 v[110:113], v[158:161], v[182:185], v[110:113]
	v_mfma_f32_16x16x32_bf16 v[102:105], v[150:153], v[190:193], v[102:105]
	v_mfma_f32_16x16x32_bf16 v[94:97], v[158:161], v[190:193], v[94:97]
	v_mfma_f32_16x16x32_bf16 v[86:89], v[150:153], v[204:207], v[86:89]
	v_mfma_f32_16x16x32_bf16 v[78:81], v[158:161], v[204:207], v[78:81]
	v_mfma_f32_16x16x32_bf16 v[70:73], v[150:153], v[212:215], v[70:73]
	v_mfma_f32_16x16x32_bf16 v[66:69], v[158:161], v[212:215], v[66:69]
	s_barrier
; #define PG8_GAS __attribute__((address_space(1)))
; #define PG8_STAGE(bufoff, gbase, voff) do { _Pragma("unroll") for (int _i = 0; _i < 2; ++_i) \
;         __builtin_amdgcn_global_load_lds((const unsigned*)((const char*)(gbase) + (voff)[_i]), (PG8_LAS unsigned*)(lds + (bufoff) + ldsw + _i * 8192), 16, 0, 0); } while (0)
; #define PG8_LDA(dst, b, h) do { _Pragma("unroll") for (int m = 0; m < 4; ++m) _Pragma("unroll") for (int k = 0; k < 2; ++k) dst[m][k] = *(const PG8_LAS bf16x8*)(lds + PG8_SA(b, h) + aoff + m * 2048 + k * 1024); } while (0)
; #define PG8_WAIT_V(n) asm volatile("s_waitcnt vmcnt(" #n ")" ::: "memory")
; #define PG8_WAIT_L(n) asm volatile("s_waitcnt lgkmcnt(" #n ")" ::: "memory")
; #define PG8_BAR __builtin_amdgcn_s_barrier()
; #define PG8_SCHED __builtin_amdgcn_sched_barrier(0)
;     __device__ __forceinline__ void operator()(const f32x4 (&acc)[2][2][4][2], const Unit& un, int wr, int wc, int fr, int fq) const {
;     ...
;         u32x4 rr[2][4][2];
; #pragma unroll
;         for (int ai = 0; ai < 2; ++ai)
; #pragma unroll
;             for (int m = 0; m < 4; ++m)
; #pragma unroll
;                 for (int bj = 0; bj < 2; ++bj) rr[ai][m][bj] = *(const PG8_GAS u32x4*)((PG8_GAS bf16_t*)h + (size_t)(row0 + ai * HALF + m * 16) * 4096 + col0 + bj * HALF);
; template <class Epi, class Sched, bool ALIGN_EPI = false, bool SP2 = false, bool F8 = false>
; __device__ __forceinline__ void gemm_phase(PG8_LAS unsigned char* lds, const Gemm g, const Sched& S, const Epi& E) {
;     ...
;             PG8_LDA(At, 1, 1); PG8_STAGE(PG8_SB(1, 0), b3, voffB); PG8_STAGE(PG8_SB(1, 1), b3 + hB, voffB); PG8_STAGE(PG8_SA(1, 0), a3, voffA);
;             PG8_WAIT_V(8); PG8_WAIT_L(0); PG8_BAR; PG8_MMA(1, 0, At, B0); PG8_MMA(1, 1, At, B1); PG8_BAR; PG8_SCHED;
	s_setprio 0
	s_add_i32 s26, s56, s36
	v_lshl_add_u64 v[216:217], v[216:217], 0, s[14:15]
	s_mov_b32 m0, s26
	ds_read_b128 v[162:165], v199 offset:49152
	ds_read_b128 v[182:185], v199 offset:50176
	ds_read_b128 v[186:189], v199 offset:51200
	ds_read_b128 v[190:193], v199 offset:52224
	ds_read_b128 v[200:203], v199 offset:53248
	ds_read_b128 v[204:207], v199 offset:54272
	ds_read_b128 v[208:211], v199 offset:55296
	ds_read_b128 v[212:215], v199 offset:56320
	global_load_lds_dwordx4 v[216:217], off
	s_add_i32 m0, s26, 0x2000
	s_add_u32 s26, s30, 0x2b0080
	v_lshl_add_u64 v[216:217], v[218:219], 0, s[14:15]
	s_addc_u32 s27, s31, 0
	s_add_i32 s30, s57, s36
	global_load_lds_dwordx4 v[216:217], off
	v_lshl_add_u64 v[216:217], s[26:27], 0, v[170:171]
	s_mov_b32 m0, s30
	s_nop 0
	global_load_lds_dwordx4 v[216:217], off
	v_lshl_add_u64 v[216:217], s[26:27], 0, v[166:167]
	s_add_i32 m0, s30, 0x2000
	s_nop 0
	global_load_lds_dwordx4 v[216:217], off
	v_lshl_add_u64 v[216:217], v[220:221], 0, s[14:15]
	s_mov_b32 m0, s44
	s_nop 0
	global_load_lds_dwordx4 v[216:217], off
	v_lshl_add_u64 v[216:217], v[222:223], 0, s[14:15]
	s_mov_b32 m0, s45
	s_nop 0
	global_load_lds_dwordx4 v[216:217], off
	s_setprio 1
	s_waitcnt vmcnt(8)
	s_waitcnt lgkmcnt(0)
	s_barrier
	v_mfma_f32_16x16x32_bf16 v[62:65], v[130:133], v[162:165], v[62:65]
	v_mfma_f32_16x16x32_bf16 v[58:61], v[138:141], v[162:165], v[58:61]
	v_mfma_f32_16x16x32_bf16 v[50:53], v[130:133], v[186:189], v[50:53]
	v_mfma_f32_16x16x32_bf16 v[42:45], v[138:141], v[186:189], v[42:45]
	v_mfma_f32_16x16x32_bf16 v[34:37], v[130:133], v[200:203], v[34:37]
	v_mfma_f32_16x16x32_bf16 v[26:29], v[138:141], v[200:203], v[26:29]
	v_mfma_f32_16x16x32_bf16 v[18:21], v[130:133], v[208:211], v[18:21]
	v_mfma_f32_16x16x32_bf16 v[10:13], v[138:141], v[208:211], v[10:13]
	v_mfma_f32_16x16x32_bf16 v[62:65], v[134:137], v[182:185], v[62:65]
	v_mfma_f32_16x16x32_bf16 v[58:61], v[142:145], v[182:185], v[58:61]
	v_mfma_f32_16x16x32_bf16 v[50:53], v[134:137], v[190:193], v[50:53]
	v_mfma_f32_16x16x32_bf16 v[42:45], v[142:145], v[190:193], v[42:45]
	v_mfma_f32_16x16x32_bf16 v[34:37], v[134:137], v[204:207], v[34:37]
	v_mfma_f32_16x16x32_bf16 v[26:29], v[142:145], v[204:207], v[26:29]
	v_mfma_f32_16x16x32_bf16 v[18:21], v[134:137], v[212:215], v[18:21]
	v_mfma_f32_16x16x32_bf16 v[10:13], v[142:145], v[212:215], v[10:13]
	v_mfma_f32_16x16x32_bf16 v[54:57], v[146:149], v[162:165], v[54:57]
	v_mfma_f32_16x16x32_bf16 v[46:49], v[154:157], v[162:165], v[46:49]
	v_mfma_f32_16x16x32_bf16 v[38:41], v[146:149], v[186:189], v[38:41]
	v_mfma_f32_16x16x32_bf16 v[30:33], v[154:157], v[186:189], v[30:33]
	v_mfma_f32_16x16x32_bf16 v[22:25], v[146:149], v[200:203], v[22:25]
	v_mfma_f32_16x16x32_bf16 v[14:17], v[154:157], v[200:203], v[14:17]
	v_mfma_f32_16x16x32_bf16 v[6:9], v[146:149], v[208:211], v[6:9]
	v_mfma_f32_16x16x32_bf16 v[2:5], v[154:157], v[208:211], v[2:5]
	v_mfma_f32_16x16x32_bf16 v[54:57], v[150:153], v[182:185], v[54:57]
	v_mfma_f32_16x16x32_bf16 v[46:49], v[158:161], v[182:185], v[46:49]
	v_mfma_f32_16x16x32_bf16 v[38:41], v[150:153], v[190:193], v[38:41]
	v_mfma_f32_16x16x32_bf16 v[30:33], v[158:161], v[190:193], v[30:33]
	v_mfma_f32_16x16x32_bf16 v[22:25], v[150:153], v[204:207], v[22:25]
	v_mfma_f32_16x16x32_bf16 v[14:17], v[158:161], v[204:207], v[14:17]
	v_mfma_f32_16x16x32_bf16 v[6:9], v[150:153], v[212:215], v[6:9]
	v_mfma_f32_16x16x32_bf16 v[2:5], v[158:161], v[212:215], v[2:5]
	s_barrier
	s_setprio 0
	s_add_i32 s55, s55, 2
	s_add_u32 s53, s53, 0x100
	s_addc_u32 s54, s54, 0
	s_cmpk_gt_u32 s55, 0xa9
	s_mov_b64 s[26:27], s[28:29]
	s_cbranch_scc0 .LBB0_1078
	v_lshl_or_b32 v132, s52, 8, v196
	v_lshl_add_u32 v130, s51, 8, v194
	v_ashrrev_i32_e32 v133, 31, v132
	v_lshlrev_b64 v[182:183], 1, v[132:133]
	v_ashrrev_i32_e32 v131, 31, v130
	v_lshl_add_u64 v[132:133], s[12:13], 0, v[182:183]
	v_lshlrev_b64 v[134:135], 13, v[130:131]
	v_lshl_add_u64 v[136:137], v[132:133], 0, v[134:135]
	global_load_dwordx4 v[200:203], v[136:137], off
	global_load_dwordx4 v[204:207], v[136:137], off offset:256
	v_or_b32_e32 v136, 16, v130
	v_ashrrev_i32_e32 v137, 31, v136
	v_lshlrev_b64 v[228:229], 13, v[136:137]
	v_lshl_add_u64 v[136:137], v[132:133], 0, v[228:229]
	global_load_dwordx4 v[208:211], v[136:137], off
	global_load_dwordx4 v[212:215], v[136:137], off offset:256
	v_or_b32_e32 v138, 32, v130
	v_or_b32_e32 v130, 48, v130
	v_ashrrev_i32_e32 v139, 31, v138
	v_ashrrev_i32_e32 v131, 31, v130
	v_lshlrev_b64 v[230:231], 13, v[138:139]
	v_lshlrev_b64 v[192:193], 13, v[130:131]
	v_lshl_add_u64 v[190:191], v[134:135], 0, s[16:17]
	v_lshl_add_u64 v[188:189], v[134:135], 0, s[20:21]
	v_lshl_add_u64 v[186:187], v[134:135], 0, s[22:23]
	v_lshl_add_u64 v[184:185], v[134:135], 0, s[24:25]
	v_lshl_add_u64 v[130:131], s[12:13], 0, v[134:135]
	v_lshl_add_u64 v[134:135], v[132:133], 0, v[230:231]
	v_lshl_add_u64 v[136:137], v[132:133], 0, v[192:193]
	v_lshl_add_u64 v[138:139], v[132:133], 0, v[190:191]
	v_lshl_add_u64 v[140:141], v[132:133], 0, v[188:189]
	v_lshl_add_u64 v[232:233], v[132:133], 0, v[186:187]
	v_lshl_add_u64 v[132:133], v[132:133], 0, v[184:185]
	v_lshl_add_u64 v[234:235], v[130:131], 0, v[182:183]
	global_load_dwordx4 v[216:219], v[134:135], off
	global_load_dwordx4 v[220:223], v[134:135], off offset:256
	global_load_dwordx4 v[224:227], v[136:137], off
	global_load_dwordx4 v[162:165], v[136:137], off offset:256
	global_load_dwordx4 v[158:161], v[138:139], off
	global_load_dwordx4 v[154:157], v[138:139], off offset:256
	global_load_dwordx4 v[150:153], v[140:141], off
	global_load_dwordx4 v[146:149], v[140:141], off offset:256
	global_load_dwordx4 v[142:145], v[232:233], off
	s_nop 0
	global_load_dwordx4 v[138:141], v[232:233], off offset:256
	global_load_dwordx4 v[134:137], v[132:133], off
	s_nop 0
	global_load_dwordx4 v[130:133], v[132:133], off offset:256
	s_and_b64 vcc, exec, s[4:5]
	s_mov_b32 s52, s49
	s_mov_b32 s51, s50
	s_mov_b64 s[28:29], s[8:9]
	s_mov_b64 s[26:27], s[6:7]
	s_waitcnt vmcnt(0)
; #define PG8_GAS __attribute__((address_space(1)))
; __device__ __forceinline__ unsigned cvt_pk_bf16(float lo, float hi) { const f32x2c v = {lo, hi}; return __builtin_bit_cast(unsigned, __builtin_convertvector(v, bf16x2c)); }
; __device__ __forceinline__ float bf_lo(unsigned w) { return __uint_as_float(w << 16); }
; __device__ __forceinline__ float bf_hi(unsigned w) { return __uint_as_float(w & 0xffff0000u); }
;     __device__ __forceinline__ void operator()(const f32x4 (&acc)[2][2][4][2], const Unit& un, int wr, int wc, int fr, int fq) const {
;     ...
; #pragma unroll
;         for (int ai = 0; ai < 2; ++ai)
; #pragma unroll
;             for (int m = 0; m < 4; ++m)
; #pragma unroll
;                 for (int bj = 0; bj < 2; ++bj) { const u32x4 r = rr[ai][m][bj]; const f32x4 v0 = acc[ai][bj][m][0], v1 = acc[ai][bj][m][1];
;                     u32x4 w; w.x = cvt_pk_bf16(v0[0] + bf_lo(r.x), v0[1] + bf_hi(r.x)); w.y = cvt_pk_bf16(v0[2] + bf_lo(r.y), v0[3] + bf_hi(r.y));
;                     w.z = cvt_pk_bf16(v1[0] + bf_lo(r.z), v1[1] + bf_hi(r.z)); w.w = cvt_pk_bf16(v1[2] + bf_lo(r.w), v1[3] + bf_hi(r.w));
;                     *(PG8_GAS u32x4*)((PG8_GAS bf16_t*)h + (size_t)(row0 + ai * HALF + m * 16) * 4096 + col0 + bj * HALF) = w; }
	v_lshlrev_b32_e32 v232, 16, v200
	v_and_b32_e32 v233, 0xffff0000, v200
	v_lshlrev_b32_e32 v200, 16, v201
	v_and_b32_e32 v201, 0xffff0000, v201
	v_lshlrev_b32_e32 v236, 16, v202
	v_and_b32_e32 v237, 0xffff0000, v202
	v_lshlrev_b32_e32 v202, 16, v203
	v_and_b32_e32 v203, 0xffff0000, v203
	v_lshlrev_b32_e32 v238, 16, v204
	v_and_b32_e32 v239, 0xffff0000, v204
	v_lshlrev_b32_e32 v204, 16, v205
	v_and_b32_e32 v205, 0xffff0000, v205
	v_lshlrev_b32_e32 v240, 16, v206
	v_and_b32_e32 v241, 0xffff0000, v206
	v_lshlrev_b32_e32 v206, 16, v207
	v_and_b32_e32 v207, 0xffff0000, v207
	v_pk_add_f32 v[126:127], v[126:127], v[232:233]
	v_pk_add_f32 v[128:129], v[128:129], v[200:201]
	v_pk_add_f32 v[122:123], v[122:123], v[236:237]
	v_pk_add_f32 v[124:125], v[124:125], v[202:203]
	v_pk_add_f32 v[114:115], v[114:115], v[238:239]
	v_pk_add_f32 v[116:117], v[116:117], v[204:205]
	v_pk_add_f32 v[200:201], v[110:111], v[240:241]
	v_pk_add_f32 v[202:203], v[112:113], v[206:207]
	v_cvt_pk_bf16_f32 v110, v126, v127
	v_cvt_pk_bf16_f32 v111, v128, v129
	v_cvt_pk_bf16_f32 v112, v122, v123
	v_cvt_pk_bf16_f32 v113, v124, v125
	v_lshlrev_b32_e32 v242, 16, v208
	v_and_b32_e32 v243, 0xffff0000, v208
	v_lshlrev_b32_e32 v208, 16, v209
	v_and_b32_e32 v209, 0xffff0000, v209
	v_cvt_pk_bf16_f32 v114, v114, v115
	v_cvt_pk_bf16_f32 v115, v116, v117
	v_cvt_pk_bf16_f32 v116, v200, v201
	v_cvt_pk_bf16_f32 v117, v202, v203
	global_store_dwordx4 v[234:235], v[110:113], off
	global_store_dwordx4 v[234:235], v[114:117], off offset:256
	v_pk_add_f32 v[118:119], v[118:119], v[242:243]
	v_lshlrev_b32_e32 v110, 16, v210
	v_and_b32_e32 v111, 0xffff0000, v210
	v_pk_add_f32 v[120:121], v[120:121], v[208:209]
	v_pk_add_f32 v[106:107], v[106:107], v[110:111]
	v_cvt_pk_bf16_f32 v118, v118, v119
	v_cvt_pk_bf16_f32 v119, v120, v121
	v_cvt_pk_bf16_f32 v120, v106, v107
	v_lshlrev_b32_e32 v106, 16, v211
	v_and_b32_e32 v107, 0xffff0000, v211
	v_pk_add_f32 v[106:107], v[108:109], v[106:107]
	v_lshlrev_b32_e32 v108, 16, v212
	v_and_b32_e32 v109, 0xffff0000, v212
	v_pk_add_f32 v[102:103], v[102:103], v[108:109]
	v_lshlrev_b32_e32 v108, 16, v213
	v_and_b32_e32 v109, 0xffff0000, v213
	v_pk_add_f32 v[104:105], v[104:105], v[108:109]
	v_cvt_pk_bf16_f32 v102, v102, v103
	v_cvt_pk_bf16_f32 v103, v104, v105
	v_lshlrev_b32_e32 v104, 16, v214
	v_and_b32_e32 v105, 0xffff0000, v214
	v_pk_add_f32 v[94:95], v[94:95], v[104:105]
	v_cvt_pk_bf16_f32 v121, v106, v107
	v_cvt_pk_bf16_f32 v104, v94, v95
	v_lshlrev_b32_e32 v94, 16, v215
	v_and_b32_e32 v95, 0xffff0000, v215
	v_pk_add_f32 v[94:95], v[96:97], v[94:95]
	v_lshlrev_b32_e32 v96, 16, v217
	v_cvt_pk_bf16_f32 v105, v94, v95
	v_lshlrev_b32_e32 v94, 16, v216
	v_and_b32_e32 v95, 0xffff0000, v216
	v_and_b32_e32 v97, 0xffff0000, v217
	v_pk_add_f32 v[94:95], v[98:99], v[94:95]
	v_pk_add_f32 v[96:97], v[100:101], v[96:97]
	v_cvt_pk_bf16_f32 v94, v94, v95
	v_cvt_pk_bf16_f32 v95, v96, v97
	v_lshlrev_b32_e32 v96, 16, v218
	v_and_b32_e32 v97, 0xffff0000, v218
	v_pk_add_f32 v[90:91], v[90:91], v[96:97]
	v_lshl_add_u64 v[106:107], s[12:13], 0, v[228:229]
	v_cvt_pk_bf16_f32 v96, v90, v91
	v_lshlrev_b32_e32 v90, 16, v219
	v_and_b32_e32 v91, 0xffff0000, v219
	v_pk_add_f32 v[90:91], v[92:93], v[90:91]
	v_lshlrev_b32_e32 v92, 16, v220
	v_and_b32_e32 v93, 0xffff0000, v220
	v_pk_add_f32 v[86:87], v[86:87], v[92:93]
	v_lshlrev_b32_e32 v92, 16, v221
	v_and_b32_e32 v93, 0xffff0000, v221
	v_pk_add_f32 v[88:89], v[88:89], v[92:93]
	v_cvt_pk_bf16_f32 v86, v86, v87
	v_cvt_pk_bf16_f32 v87, v88, v89
	v_lshlrev_b32_e32 v88, 16, v222
	v_and_b32_e32 v89, 0xffff0000, v222
	v_pk_add_f32 v[78:79], v[78:79], v[88:89]
	v_cvt_pk_bf16_f32 v97, v90, v91
	v_cvt_pk_bf16_f32 v88, v78, v79
	v_lshlrev_b32_e32 v78, 16, v223
	v_and_b32_e32 v79, 0xffff0000, v223
	v_pk_add_f32 v[78:79], v[80:81], v[78:79]
	v_lshlrev_b32_e32 v80, 16, v225
	v_cvt_pk_bf16_f32 v89, v78, v79
	v_lshlrev_b32_e32 v78, 16, v224
	v_and_b32_e32 v79, 0xffff0000, v224
	v_and_b32_e32 v81, 0xffff0000, v225
	v_pk_add_f32 v[78:79], v[82:83], v[78:79]
	v_pk_add_f32 v[80:81], v[84:85], v[80:81]
	v_cvt_pk_bf16_f32 v78, v78, v79
	v_cvt_pk_bf16_f32 v79, v80, v81
	v_lshlrev_b32_e32 v80, 16, v226
	v_and_b32_e32 v81, 0xffff0000, v226
	v_pk_add_f32 v[74:75], v[74:75], v[80:81]
	v_lshl_add_u64 v[90:91], s[12:13], 0, v[230:231]
	v_cvt_pk_bf16_f32 v80, v74, v75
	v_lshlrev_b32_e32 v74, 16, v227
	v_and_b32_e32 v75, 0xffff0000, v227
	v_pk_add_f32 v[74:75], v[76:77], v[74:75]
	v_lshlrev_b32_e32 v76, 16, v162
	v_and_b32_e32 v77, 0xffff0000, v162
	v_pk_add_f32 v[70:71], v[70:71], v[76:77]
	v_lshlrev_b32_e32 v76, 16, v163
	v_and_b32_e32 v77, 0xffff0000, v163
	v_pk_add_f32 v[72:73], v[72:73], v[76:77]
	v_cvt_pk_bf16_f32 v70, v70, v71
	v_cvt_pk_bf16_f32 v71, v72, v73
	v_lshlrev_b32_e32 v72, 16, v164
	v_and_b32_e32 v73, 0xffff0000, v164
	v_pk_add_f32 v[66:67], v[66:67], v[72:73]
	v_cvt_pk_bf16_f32 v81, v74, v75
	v_cvt_pk_bf16_f32 v72, v66, v67
	v_lshlrev_b32_e32 v66, 16, v165
	v_and_b32_e32 v67, 0xffff0000, v165
	v_pk_add_f32 v[66:67], v[68:69], v[66:67]
	v_lshl_add_u64 v[74:75], s[12:13], 0, v[192:193]
	v_cvt_pk_bf16_f32 v73, v66, v67
	v_lshlrev_b32_e32 v66, 16, v158
	v_and_b32_e32 v67, 0xffff0000, v158
	v_pk_add_f32 v[62:63], v[62:63], v[66:67]
	v_lshlrev_b32_e32 v66, 16, v159
	v_and_b32_e32 v67, 0xffff0000, v159
	v_pk_add_f32 v[64:65], v[64:65], v[66:67]
	v_cvt_pk_bf16_f32 v62, v62, v63
	v_cvt_pk_bf16_f32 v63, v64, v65
	v_lshlrev_b32_e32 v64, 16, v160
	v_and_b32_e32 v65, 0xffff0000, v160
	v_pk_add_f32 v[58:59], v[58:59], v[64:65]
	v_lshl_add_u64 v[106:107], v[106:107], 0, v[182:183]
; #define PG8_GAS __attribute__((address_space(1)))
; __device__ __forceinline__ unsigned cvt_pk_bf16(float lo, float hi) { const f32x2c v = {lo, hi}; return __builtin_bit_cast(unsigned, __builtin_convertvector(v, bf16x2c)); }
; __device__ __forceinline__ float bf_lo(unsigned w) { return __uint_as_float(w << 16); }
; __device__ __forceinline__ float bf_hi(unsigned w) { return __uint_as_float(w & 0xffff0000u); }
;     __device__ __forceinline__ void operator()(const f32x4 (&acc)[2][2][4][2], const Unit& un, int wr, int wc, int fr, int fq) const {
;     ...
; #pragma unroll
;         for (int ai = 0; ai < 2; ++ai)
; #pragma unroll
;             for (int m = 0; m < 4; ++m)
; #pragma unroll
;                 for (int bj = 0; bj < 2; ++bj) { const u32x4 r = rr[ai][m][bj]; const f32x4 v0 = acc[ai][bj][m][0], v1 = acc[ai][bj][m][1];
;                     u32x4 w; w.x = cvt_pk_bf16(v0[0] + bf_lo(r.x), v0[1] + bf_hi(r.x)); w.y = cvt_pk_bf16(v0[2] + bf_lo(r.y), v0[3] + bf_hi(r.y));
;                     w.z = cvt_pk_bf16(v1[0] + bf_lo(r.z), v1[1] + bf_hi(r.z)); w.w = cvt_pk_bf16(v1[2] + bf_lo(r.w), v1[3] + bf_hi(r.w));
;                     *(PG8_GAS u32x4*)((PG8_GAS bf16_t*)h + (size_t)(row0 + ai * HALF + m * 16) * 4096 + col0 + bj * HALF) = w; }
	v_cvt_pk_bf16_f32 v64, v58, v59
	v_lshlrev_b32_e32 v58, 16, v161
	v_and_b32_e32 v59, 0xffff0000, v161
	v_pk_add_f32 v[58:59], v[60:61], v[58:59]
	v_lshlrev_b32_e32 v60, 16, v154
	v_and_b32_e32 v61, 0xffff0000, v154
	v_pk_add_f32 v[54:55], v[54:55], v[60:61]
	v_lshlrev_b32_e32 v60, 16, v155
	v_and_b32_e32 v61, 0xffff0000, v155
	v_pk_add_f32 v[56:57], v[56:57], v[60:61]
	v_cvt_pk_bf16_f32 v54, v54, v55
	v_cvt_pk_bf16_f32 v55, v56, v57
	v_lshlrev_b32_e32 v56, 16, v156
	v_and_b32_e32 v57, 0xffff0000, v156
	v_pk_add_f32 v[46:47], v[46:47], v[56:57]
	v_cvt_pk_bf16_f32 v65, v58, v59
	v_cvt_pk_bf16_f32 v56, v46, v47
	v_lshlrev_b32_e32 v46, 16, v157
	v_and_b32_e32 v47, 0xffff0000, v157
	v_pk_add_f32 v[46:47], v[48:49], v[46:47]
	v_lshlrev_b32_e32 v48, 16, v151
	v_cvt_pk_bf16_f32 v57, v46, v47
	v_lshlrev_b32_e32 v46, 16, v150
	v_and_b32_e32 v47, 0xffff0000, v150
	v_and_b32_e32 v49, 0xffff0000, v151
	v_pk_add_f32 v[46:47], v[50:51], v[46:47]
	v_pk_add_f32 v[48:49], v[52:53], v[48:49]
	v_cvt_pk_bf16_f32 v46, v46, v47
	v_cvt_pk_bf16_f32 v47, v48, v49
	v_lshlrev_b32_e32 v48, 16, v152
	v_and_b32_e32 v49, 0xffff0000, v152
	v_pk_add_f32 v[42:43], v[42:43], v[48:49]
	v_lshl_add_u64 v[58:59], s[12:13], 0, v[190:191]
	v_cvt_pk_bf16_f32 v48, v42, v43
	v_lshlrev_b32_e32 v42, 16, v153
	v_and_b32_e32 v43, 0xffff0000, v153
	v_pk_add_f32 v[42:43], v[44:45], v[42:43]
	v_lshlrev_b32_e32 v44, 16, v146
	v_and_b32_e32 v45, 0xffff0000, v146
	v_pk_add_f32 v[38:39], v[38:39], v[44:45]
	v_lshlrev_b32_e32 v44, 16, v147
	v_and_b32_e32 v45, 0xffff0000, v147
	v_pk_add_f32 v[40:41], v[40:41], v[44:45]
	v_cvt_pk_bf16_f32 v38, v38, v39
	v_cvt_pk_bf16_f32 v39, v40, v41
	v_lshlrev_b32_e32 v40, 16, v148
	v_and_b32_e32 v41, 0xffff0000, v148
	v_pk_add_f32 v[30:31], v[30:31], v[40:41]
	v_cvt_pk_bf16_f32 v49, v42, v43
	v_cvt_pk_bf16_f32 v40, v30, v31
	v_lshlrev_b32_e32 v30, 16, v149
	v_and_b32_e32 v31, 0xffff0000, v149
	v_pk_add_f32 v[30:31], v[32:33], v[30:31]
	v_lshlrev_b32_e32 v32, 16, v143
	v_cvt_pk_bf16_f32 v41, v30, v31
	v_lshlrev_b32_e32 v30, 16, v142
	v_and_b32_e32 v31, 0xffff0000, v142
	v_and_b32_e32 v33, 0xffff0000, v143
	v_pk_add_f32 v[30:31], v[34:35], v[30:31]
	v_pk_add_f32 v[32:33], v[36:37], v[32:33]
	v_cvt_pk_bf16_f32 v30, v30, v31
	v_cvt_pk_bf16_f32 v31, v32, v33
	v_lshlrev_b32_e32 v32, 16, v144
	v_and_b32_e32 v33, 0xffff0000, v144
	v_pk_add_f32 v[26:27], v[26:27], v[32:33]
	v_lshl_add_u64 v[42:43], s[12:13], 0, v[188:189]
	v_cvt_pk_bf16_f32 v32, v26, v27
	v_lshlrev_b32_e32 v26, 16, v145
	v_and_b32_e32 v27, 0xffff0000, v145
	v_pk_add_f32 v[26:27], v[28:29], v[26:27]
	v_lshlrev_b32_e32 v28, 16, v138
	v_and_b32_e32 v29, 0xffff0000, v138
	v_pk_add_f32 v[22:23], v[22:23], v[28:29]
	v_lshlrev_b32_e32 v28, 16, v139
	v_and_b32_e32 v29, 0xffff0000, v139
	v_pk_add_f32 v[24:25], v[24:25], v[28:29]
	v_cvt_pk_bf16_f32 v22, v22, v23
	v_cvt_pk_bf16_f32 v23, v24, v25
	v_lshlrev_b32_e32 v24, 16, v140
	v_and_b32_e32 v25, 0xffff0000, v140
	v_pk_add_f32 v[14:15], v[14:15], v[24:25]
	v_cvt_pk_bf16_f32 v33, v26, v27
	v_cvt_pk_bf16_f32 v24, v14, v15
	v_lshlrev_b32_e32 v14, 16, v141
	v_and_b32_e32 v15, 0xffff0000, v141
	v_pk_add_f32 v[14:15], v[16:17], v[14:15]
	v_lshlrev_b32_e32 v16, 16, v135
	v_cvt_pk_bf16_f32 v25, v14, v15
	v_lshlrev_b32_e32 v14, 16, v134
	v_and_b32_e32 v15, 0xffff0000, v134
	v_and_b32_e32 v17, 0xffff0000, v135
	v_pk_add_f32 v[14:15], v[18:19], v[14:15]
	v_pk_add_f32 v[16:17], v[20:21], v[16:17]
	v_cvt_pk_bf16_f32 v14, v14, v15
	v_cvt_pk_bf16_f32 v15, v16, v17
	v_lshlrev_b32_e32 v16, 16, v136
	v_and_b32_e32 v17, 0xffff0000, v136
	v_pk_add_f32 v[10:11], v[10:11], v[16:17]
	v_lshl_add_u64 v[26:27], s[12:13], 0, v[186:187]
	v_cvt_pk_bf16_f32 v16, v10, v11
	v_lshlrev_b32_e32 v10, 16, v137
	v_and_b32_e32 v11, 0xffff0000, v137
	v_pk_add_f32 v[10:11], v[12:13], v[10:11]
	v_lshlrev_b32_e32 v12, 16, v130
	v_and_b32_e32 v13, 0xffff0000, v130
	v_pk_add_f32 v[6:7], v[6:7], v[12:13]
	v_lshlrev_b32_e32 v12, 16, v131
	v_and_b32_e32 v13, 0xffff0000, v131
	v_pk_add_f32 v[8:9], v[8:9], v[12:13]
	v_cvt_pk_bf16_f32 v6, v6, v7
	v_cvt_pk_bf16_f32 v7, v8, v9
	v_lshlrev_b32_e32 v8, 16, v132
	v_and_b32_e32 v9, 0xffff0000, v132
	v_pk_add_f32 v[2:3], v[2:3], v[8:9]
	v_cvt_pk_bf16_f32 v17, v10, v11
	v_cvt_pk_bf16_f32 v8, v2, v3
	v_lshlrev_b32_e32 v2, 16, v133
	v_and_b32_e32 v3, 0xffff0000, v133
	v_lshl_add_u64 v[10:11], s[12:13], 0, v[184:185]
	v_pk_add_f32 v[2:3], v[4:5], v[2:3]
	v_lshl_add_u64 v[90:91], v[90:91], 0, v[182:183]
	v_lshl_add_u64 v[74:75], v[74:75], 0, v[182:183]
	v_lshl_add_u64 v[58:59], v[58:59], 0, v[182:183]
	v_lshl_add_u64 v[42:43], v[42:43], 0, v[182:183]
	v_lshl_add_u64 v[26:27], v[26:27], 0, v[182:183]
	v_lshl_add_u64 v[10:11], v[10:11], 0, v[182:183]
	v_cvt_pk_bf16_f32 v9, v2, v3
	global_store_dwordx4 v[106:107], v[118:121], off
	global_store_dwordx4 v[106:107], v[102:105], off offset:256
	global_store_dwordx4 v[90:91], v[94:97], off
	global_store_dwordx4 v[90:91], v[86:89], off offset:256
	global_store_dwordx4 v[74:75], v[78:81], off
	global_store_dwordx4 v[74:75], v[70:73], off offset:256
	global_store_dwordx4 v[58:59], v[62:65], off
	global_store_dwordx4 v[58:59], v[54:57], off offset:256
	global_store_dwordx4 v[42:43], v[46:49], off
	global_store_dwordx4 v[42:43], v[38:41], off offset:256
	global_store_dwordx4 v[26:27], v[30:33], off
	global_store_dwordx4 v[26:27], v[22:25], off offset:256
	global_store_dwordx4 v[10:11], v[14:17], off
	global_store_dwordx4 v[10:11], v[6:9], off offset:256
	s_cbranch_vccz .LBB0_1071
	s_waitcnt vmcnt(0)
	s_cmpk_gt_u32 s18, 0xff
	s_cbranch_scc1 .LBB0_1082
	s_barrier
